# MT4 k-loop: memory ops spread <=2 per MFMA gap (simulated lgkmcnt) + attention P-pack via v_cvt_pk_bf16_f32
# speedup vs baseline: 1.0523x; 1.0130x over previous
.LBB0_302:
	ds_read_b128 v[216:219], v176 offset:36864
	ds_read_b128 v[200:203], v188
	ds_read_b128 v[220:223], v176 offset:41472
	ds_read_b128 v[204:207], v188 offset:4608
	ds_read_b128 v[208:211], v188 offset:9216
	ds_read_b128 v[212:215], v187
	s_waitcnt lgkmcnt(4)
	v_mfma_f32_32x32x16_bf16 v[112:127], v[200:203], v[216:219], v[112:127]
	ds_read_b128 v[240:243], v176 offset:36896
	global_load_dwordx4 v[140:143], v190, s[42:43]
	s_waitcnt lgkmcnt(4)
	v_mfma_f32_32x32x16_bf16 v[96:111], v[200:203], v[220:223], v[96:111]
	ds_read_b128 v[224:227], v188 offset:32
	global_load_dwordx4 v[164:167], v190, s[40:41]
	s_waitcnt lgkmcnt(4)
	v_mfma_f32_32x32x16_bf16 v[80:95], v[204:207], v[216:219], v[80:95]
	ds_read_b128 v[244:247], v176 offset:41504
	global_load_dwordx4 v[128:131], v191, s[40:41]
	s_waitcnt lgkmcnt(5)
	v_mfma_f32_32x32x16_bf16 v[64:79], v[204:207], v[220:223], v[64:79]
	ds_read_b128 v[228:231], v188 offset:4640
	global_load_dwordx4 v[132:135], v192, s[40:41]
	s_waitcnt lgkmcnt(5)
	v_mfma_f32_32x32x16_bf16 v[48:63], v[208:211], v[216:219], v[48:63]
	ds_read_b128 v[232:235], v188 offset:9248
	global_load_dwordx4 v[136:139], v193, s[40:41]
	s_waitcnt lgkmcnt(6)
	v_mfma_f32_32x32x16_bf16 v[32:47], v[208:211], v[220:223], v[32:47]
	ds_read_b128 v[236:239], v187 offset:32
	global_load_dwordx4 v[144:147], v194, s[40:41]
	s_waitcnt lgkmcnt(6)
	v_mfma_f32_32x32x16_bf16 v[16:31], v[212:215], v[216:219], v[16:31]
	global_load_dwordx4 v[148:151], v195, s[40:41]
	global_load_dwordx4 v[152:155], v196, s[40:41]
	s_waitcnt lgkmcnt(6)
	v_mfma_f32_32x32x16_bf16 v[0:15], v[212:215], v[220:223], v[0:15]
	global_load_dwordx4 v[156:159], v197, s[40:41]
	global_load_dwordx4 v[160:163], v191, s[42:43]
	s_waitcnt lgkmcnt(4)
	v_mfma_f32_32x32x16_bf16 v[112:127], v[224:227], v[240:243], v[112:127]
	ds_read_b128 v[200:203], v188 offset:64
	global_load_dwordx4 v[168:171], v192, s[42:43]
	s_waitcnt lgkmcnt(4)
	v_mfma_f32_32x32x16_bf16 v[96:111], v[224:227], v[244:247], v[96:111]
	ds_read_b128 v[204:207], v188 offset:4672
	global_load_dwordx4 v[172:175], v193, s[42:43]
	s_add_u32 s40, s40, 0x80
	s_addc_u32 s41, s41, 0
	s_add_u32 s42, s42, 0x80
	s_addc_u32 s43, s43, 0
	s_add_u32 s16, s16, 0x80
	s_waitcnt lgkmcnt(4)
	v_mfma_f32_32x32x16_bf16 v[80:95], v[228:231], v[240:243], v[80:95]
	ds_read_b128 v[208:211], v188 offset:9280
	s_waitcnt lgkmcnt(5)
	v_mfma_f32_32x32x16_bf16 v[64:79], v[228:231], v[244:247], v[64:79]
	ds_read_b128 v[212:215], v187 offset:64
	s_waitcnt lgkmcnt(5)
	v_mfma_f32_32x32x16_bf16 v[48:63], v[232:235], v[240:243], v[48:63]
	ds_read_b128 v[216:219], v176 offset:36928
	s_waitcnt lgkmcnt(6)
	v_mfma_f32_32x32x16_bf16 v[32:47], v[232:235], v[244:247], v[32:47]
	ds_read_b128 v[220:223], v176 offset:41536
	s_waitcnt lgkmcnt(6)
	v_mfma_f32_32x32x16_bf16 v[16:31], v[236:239], v[240:243], v[16:31]
	s_waitcnt lgkmcnt(6)
	v_mfma_f32_32x32x16_bf16 v[0:15], v[236:239], v[244:247], v[0:15]
	s_waitcnt lgkmcnt(1)
	v_mfma_f32_32x32x16_bf16 v[112:127], v[200:203], v[216:219], v[112:127]
	ds_read_b128 v[224:227], v188 offset:96
	s_waitcnt lgkmcnt(1)
	v_mfma_f32_32x32x16_bf16 v[96:111], v[200:203], v[220:223], v[96:111]
	ds_read_b128 v[228:231], v188 offset:4704
	s_waitcnt lgkmcnt(3)
	v_mfma_f32_32x32x16_bf16 v[80:95], v[204:207], v[216:219], v[80:95]
	ds_read_b128 v[232:235], v188 offset:9312
	s_waitcnt lgkmcnt(3)
	v_mfma_f32_32x32x16_bf16 v[64:79], v[204:207], v[220:223], v[64:79]
	ds_read_b128 v[236:239], v187 offset:96
	s_waitcnt lgkmcnt(5)
	v_mfma_f32_32x32x16_bf16 v[48:63], v[208:211], v[216:219], v[48:63]
	ds_read_b128 v[240:243], v176 offset:36960
	s_waitcnt lgkmcnt(5)
	v_mfma_f32_32x32x16_bf16 v[32:47], v[208:211], v[220:223], v[32:47]
	ds_read_b128 v[244:247], v176 offset:41568
	s_waitcnt lgkmcnt(7)
	v_mfma_f32_32x32x16_bf16 v[16:31], v[212:215], v[216:219], v[16:31]
	s_waitcnt lgkmcnt(6)
	v_mfma_f32_32x32x16_bf16 v[0:15], v[212:215], v[220:223], v[0:15]
	s_waitcnt lgkmcnt(0)
	s_barrier
	s_waitcnt vmcnt(0)
	s_waitcnt lgkmcnt(1)
	v_mfma_f32_32x32x16_bf16 v[112:127], v[224:227], v[240:243], v[112:127]
	ds_write_b128 v189, v[164:167]
	ds_write_b128 v189, v[128:131] offset:4608
	s_waitcnt lgkmcnt(2)
	v_mfma_f32_32x32x16_bf16 v[96:111], v[224:227], v[244:247], v[96:111]
	ds_write_b128 v189, v[132:135] offset:9216
	s_waitcnt lgkmcnt(4)
	v_mfma_f32_32x32x16_bf16 v[80:95], v[228:231], v[240:243], v[80:95]
	ds_write_b128 v189, v[136:139] offset:13824
	ds_write_b128 v189, v[144:147] offset:18432
	s_waitcnt lgkmcnt(5)
	v_mfma_f32_32x32x16_bf16 v[64:79], v[228:231], v[244:247], v[64:79]
	ds_write_b128 v189, v[148:151] offset:23040
	s_waitcnt lgkmcnt(7)
	v_mfma_f32_32x32x16_bf16 v[48:63], v[232:235], v[240:243], v[48:63]
	ds_write_b128 v189, v[152:155] offset:27648
	ds_write_b128 v189, v[156:159] offset:32256
	s_waitcnt lgkmcnt(8)
	v_mfma_f32_32x32x16_bf16 v[32:47], v[232:235], v[244:247], v[32:47]
	ds_write_b128 v189, v[140:143] offset:36864
	s_waitcnt lgkmcnt(10)
	v_mfma_f32_32x32x16_bf16 v[16:31], v[236:239], v[240:243], v[16:31]
	ds_write_b128 v189, v[160:163] offset:41472
	ds_write_b128 v189, v[168:171] offset:46080
	s_waitcnt lgkmcnt(11)
	v_mfma_f32_32x32x16_bf16 v[0:15], v[236:239], v[244:247], v[0:15]
	ds_write_b128 v189, v[172:175] offset:50688
	s_waitcnt lgkmcnt(0)
	s_barrier
	s_cmpk_lg_i32 s16, 0x780
	s_cbranch_scc1 .LBB0_302
	ds_read_b128 v[128:131], v188 offset:4608
	ds_read_b128 v[132:135], v188 offset:9216
	ds_read_b128 v[136:139], v176 offset:41472
	ds_read_b128 v[140:143], v188
	ds_read_b128 v[144:147], v188 offset:32
	ds_read_b128 v[148:151], v176 offset:36864
	ds_read_b128 v[152:155], v176 offset:36896
	s_waitcnt lgkmcnt(1)
	v_mfma_f32_32x32x16_bf16 v[80:95], v[128:131], v[148:151], v[80:95]
	v_cmp_gt_u32_e32 vcc, s48, v182
	v_mfma_f32_32x32x16_bf16 v[64:79], v[128:131], v[136:139], v[64:79]
	v_mfma_f32_32x32x16_bf16 v[48:63], v[132:135], v[148:151], v[48:63]
	v_mfma_f32_32x32x16_bf16 v[32:47], v[132:135], v[136:139], v[32:47]
	ds_read_b128 v[128:131], v187
	ds_read_b128 v[132:135], v187 offset:32
	v_mfma_f32_32x32x16_bf16 v[112:127], v[140:143], v[148:151], v[112:127]
	v_mfma_f32_32x32x16_bf16 v[96:111], v[140:143], v[136:139], v[96:111]
	s_waitcnt lgkmcnt(1)
	v_mfma_f32_32x32x16_bf16 v[16:31], v[128:131], v[148:151], v[16:31]
	v_mfma_f32_32x32x16_bf16 v[0:15], v[128:131], v[136:139], v[0:15]
	ds_read_b128 v[128:131], v188 offset:4640
	ds_read_b128 v[136:139], v188 offset:9248
	ds_read_b128 v[140:143], v176 offset:41504
	v_mfma_f32_32x32x16_bf16 v[112:127], v[144:147], v[152:155], v[112:127]
	s_waitcnt lgkmcnt(0)
	v_mfma_f32_32x32x16_bf16 v[96:111], v[144:147], v[140:143], v[96:111]
	v_mfma_f32_32x32x16_bf16 v[80:95], v[128:131], v[152:155], v[80:95]
	v_mfma_f32_32x32x16_bf16 v[64:79], v[128:131], v[140:143], v[64:79]
	v_mfma_f32_32x32x16_bf16 v[48:63], v[136:139], v[152:155], v[48:63]
	v_mfma_f32_32x32x16_bf16 v[32:47], v[136:139], v[140:143], v[32:47]
	v_mfma_f32_32x32x16_bf16 v[16:31], v[132:135], v[152:155], v[16:31]
	v_mfma_f32_32x32x16_bf16 v[0:15], v[132:135], v[140:143], v[0:15]
	ds_read_b128 v[128:131], v188 offset:64
	ds_read_b128 v[132:135], v188 offset:4672
	ds_read_b128 v[136:139], v188 offset:9280
	ds_read_b128 v[140:143], v187 offset:64
	ds_read_b128 v[144:147], v176 offset:36928
	ds_read_b128 v[148:151], v176 offset:41536
	s_waitcnt lgkmcnt(1)
	v_mfma_f32_32x32x16_bf16 v[112:127], v[128:131], v[144:147], v[112:127]
	s_waitcnt lgkmcnt(0)
	v_mfma_f32_32x32x16_bf16 v[96:111], v[128:131], v[148:151], v[96:111]
	v_mfma_f32_32x32x16_bf16 v[80:95], v[132:135], v[144:147], v[80:95]
	v_mfma_f32_32x32x16_bf16 v[64:79], v[132:135], v[148:151], v[64:79]
	v_mfma_f32_32x32x16_bf16 v[48:63], v[136:139], v[144:147], v[48:63]
	v_mfma_f32_32x32x16_bf16 v[32:47], v[136:139], v[148:151], v[32:47]
	v_mfma_f32_32x32x16_bf16 v[16:31], v[140:143], v[144:147], v[16:31]
	v_mfma_f32_32x32x16_bf16 v[0:15], v[140:143], v[148:151], v[0:15]
	ds_read_b128 v[128:131], v188 offset:96
	ds_read_b128 v[132:135], v188 offset:4704
	ds_read_b128 v[136:139], v188 offset:9312
	ds_read_b128 v[140:143], v187 offset:96
	ds_read_b128 v[144:147], v176 offset:36960
	ds_read_b128 v[148:151], v176 offset:41568
	s_waitcnt lgkmcnt(0)
	s_barrier
	v_mfma_f32_32x32x16_bf16 v[112:127], v[128:131], v[144:147], v[112:127]
	v_mfma_f32_32x32x16_bf16 v[96:111], v[128:131], v[148:151], v[96:111]
	v_lshlrev_b32_e32 v128, 7, v185
	v_lshl_or_b32 v128, v184, 1, v128
	v_mad_u32_u24 v130, v186, s49, v128
	s_nop 7
	v_bfe_u32 v131, v117, 16, 1
	v_bfe_u32 v251, v118, 16, 1
	v_bfe_u32 v183, v121, 16, 1
	v_bfe_u32 v250, v122, 16, 1
	v_mfma_f32_32x32x16_bf16 v[80:95], v[132:135], v[144:147], v[80:95]
	v_bfe_u32 v249, v123, 16, 1
	v_bfe_u32 v246, v124, 16, 1
	v_bfe_u32 v244, v125, 16, 1
	v_bfe_u32 v247, v126, 16, 1
	v_bfe_u32 v248, v127, 16, 1
	v_bfe_u32 v245, v96, 16, 1
	v_bfe_u32 v243, v97, 16, 1
	v_mfma_f32_32x32x16_bf16 v[64:79], v[132:135], v[148:151], v[64:79]
	v_bfe_u32 v135, v115, 16, 1
	v_bfe_u32 v134, v116, 16, 1
	v_bfe_u32 v132, v119, 16, 1
	v_bfe_u32 v133, v120, 16, 1
	v_bfe_u32 v242, v98, 16, 1
	v_bfe_u32 v239, v99, 16, 1
	v_bfe_u32 v237, v100, 16, 1
	v_mfma_f32_32x32x16_bf16 v[48:63], v[136:139], v[144:147], v[48:63]
	v_bfe_u32 v240, v101, 16, 1
	v_bfe_u32 v241, v102, 16, 1
	v_bfe_u32 v238, v103, 16, 1
	v_bfe_u32 v236, v104, 16, 1
	v_bfe_u32 v235, v105, 16, 1
	v_bfe_u32 v232, v106, 16, 1
	v_bfe_u32 v230, v107, 16, 1
	v_mfma_f32_32x32x16_bf16 v[32:47], v[136:139], v[148:151], v[32:47]
	v_bfe_u32 v137, v112, 16, 1
	v_bfe_u32 v138, v113, 16, 1
	v_bfe_u32 v136, v114, 16, 1
	v_bfe_u32 v233, v108, 16, 1
	v_bfe_u32 v234, v109, 16, 1
	v_bfe_u32 v231, v110, 16, 1
	v_bfe_u32 v229, v111, 16, 1
	v_mfma_f32_32x32x16_bf16 v[16:31], v[140:143], v[144:147], v[16:31]
	v_bfe_u32 v228, v80, 16, 1
	v_bfe_u32 v252, v81, 16, 1
	v_bfe_u32 v253, v69, 16, 1
	v_bfe_u32 v225, v70, 16, 1
	v_bfe_u32 v223, v71, 16, 1
	v_bfe_u32 v226, v72, 16, 1
	v_bfe_u32 v227, v73, 16, 1
	v_mfma_f32_32x32x16_bf16 v[0:15], v[140:143], v[148:151], v[0:15]
	v_bfe_u32 v224, v74, 16, 1
	v_bfe_u32 v222, v75, 16, 1
	v_bfe_u32 v221, v76, 16, 1
	v_bfe_u32 v218, v77, 16, 1
	v_bfe_u32 v216, v78, 16, 1
	v_bfe_u32 v219, v79, 16, 1
	v_bfe_u32 v220, v48, 16, 1
	v_bfe_u32 v217, v49, 16, 1
	v_bfe_u32 v215, v50, 16, 1
	v_bfe_u32 v214, v51, 16, 1
	v_bfe_u32 v211, v52, 16, 1
	v_bfe_u32 v209, v53, 16, 1
	v_bfe_u32 v212, v54, 16, 1
	v_bfe_u32 v213, v55, 16, 1
	v_bfe_u32 v210, v56, 16, 1
	v_bfe_u32 v208, v57, 16, 1
	v_bfe_u32 v207, v58, 16, 1
	v_bfe_u32 v204, v59, 16, 1
	v_bfe_u32 v202, v60, 16, 1
	v_bfe_u32 v205, v61, 16, 1
	v_bfe_u32 v206, v62, 16, 1
	v_bfe_u32 v203, v63, 16, 1
	v_bfe_u32 v201, v32, 16, 1
	v_bfe_u32 v200, v33, 16, 1
	v_bfe_u32 v197, v34, 16, 1
	v_bfe_u32 v195, v35, 16, 1
	v_bfe_u32 v198, v36, 16, 1
	v_bfe_u32 v199, v37, 16, 1
	v_bfe_u32 v196, v38, 16, 1
	v_bfe_u32 v194, v39, 16, 1
	v_bfe_u32 v193, v40, 16, 1
	v_bfe_u32 v190, v41, 16, 1
	v_bfe_u32 v188, v42, 16, 1
	v_bfe_u32 v191, v43, 16, 1
	v_bfe_u32 v192, v44, 16, 1
	v_bfe_u32 v189, v45, 16, 1
	v_bfe_u32 v187, v46, 16, 1
	v_bfe_u32 v186, v47, 16, 1
	v_bfe_u32 v181, v16, 16, 1
	v_bfe_u32 v179, v17, 16, 1
	v_bfe_u32 v184, v18, 16, 1
	v_bfe_u32 v185, v19, 16, 1
	v_bfe_u32 v180, v20, 16, 1
	v_bfe_u32 v178, v21, 16, 1
	v_bfe_u32 v175, v22, 16, 1
	v_bfe_u32 v173, v23, 16, 1
	v_bfe_u32 v170, v24, 16, 1
	v_bfe_u32 v174, v25, 16, 1
	v_bfe_u32 v171, v26, 16, 1
	v_bfe_u32 v172, v27, 16, 1
	v_bfe_u32 v169, v28, 16, 1
	v_bfe_u32 v168, v29, 16, 1
	v_bfe_u32 v166, v30, 16, 1
	v_bfe_u32 v164, v31, 16, 1
	v_bfe_u32 v167, v0, 16, 1
	v_bfe_u32 v165, v1, 16, 1
	v_bfe_u32 v163, v2, 16, 1
	v_bfe_u32 v162, v3, 16, 1
	v_bfe_u32 v161, v4, 16, 1
	v_bfe_u32 v160, v5, 16, 1
	v_bfe_u32 v159, v6, 16, 1
	v_bfe_u32 v158, v7, 16, 1
	v_bfe_u32 v157, v8, 16, 1
	v_bfe_u32 v156, v9, 16, 1
	v_bfe_u32 v155, v10, 16, 1
	v_bfe_u32 v154, v11, 16, 1
	v_bfe_u32 v153, v12, 16, 1
	v_bfe_u32 v152, v13, 16, 1
	v_bfe_u32 v147, v14, 16, 1
	v_bfe_u32 v151, v15, 16, 1
	s_and_saveexec_b64 s[16:17], vcc
	s_cbranch_execz .LBB0_305
	v_add3_u32 v128, v112, v137, s50
	ds_write_b16_d16_hi v130, v128
	v_add3_u32 v128, v113, v138, s50
	ds_write_b16_d16_hi v130, v128 offset:272
	v_add3_u32 v128, v114, v136, s50
	ds_write_b16_d16_hi v130, v128 offset:544
	v_add3_u32 v128, v115, v135, s50
	ds_write_b16_d16_hi v130, v128 offset:816
	v_add3_u32 v128, v116, v134, s50
	ds_write_b16_d16_hi v130, v128 offset:2176
	v_add3_u32 v128, v117, v131, s50
	ds_write_b16_d16_hi v130, v128 offset:2448
	v_add3_u32 v128, v118, v251, s50
	ds_write_b16_d16_hi v130, v128 offset:2720
	v_add3_u32 v128, v119, v132, s50
	ds_write_b16_d16_hi v130, v128 offset:2992
	v_add3_u32 v128, v120, v133, s50
	ds_write_b16_d16_hi v130, v128 offset:4352
	v_add3_u32 v128, v121, v183, s50
	ds_write_b16_d16_hi v130, v128 offset:4624
	v_add3_u32 v128, v122, v250, s50
	ds_write_b16_d16_hi v130, v128 offset:4896
	v_add3_u32 v128, v123, v249, s50
	ds_write_b16_d16_hi v130, v128 offset:5168
	v_add3_u32 v128, v124, v246, s50
	ds_write_b16_d16_hi v130, v128 offset:6528
	v_add3_u32 v128, v125, v244, s50
	ds_write_b16_d16_hi v130, v128 offset:6800
	v_add3_u32 v128, v126, v247, s50
	ds_write_b16_d16_hi v130, v128 offset:7072
	v_add3_u32 v128, v127, v248, s50
	ds_write_b16_d16_hi v130, v128 offset:7344
	v_add3_u32 v128, v96, v245, s50
	ds_write_b16_d16_hi v130, v128 offset:64
	v_add3_u32 v128, v97, v243, s50
	ds_write_b16_d16_hi v130, v128 offset:336
	v_add3_u32 v128, v98, v242, s50
	ds_write_b16_d16_hi v130, v128 offset:608
	v_add3_u32 v128, v99, v239, s50
	ds_write_b16_d16_hi v130, v128 offset:880
	v_add3_u32 v128, v100, v237, s50
	ds_write_b16_d16_hi v130, v128 offset:2240
	v_add3_u32 v128, v101, v240, s50
	ds_write_b16_d16_hi v130, v128 offset:2512
	v_add3_u32 v128, v102, v241, s50
	ds_write_b16_d16_hi v130, v128 offset:2784
	v_add3_u32 v128, v103, v238, s50
	ds_write_b16_d16_hi v130, v128 offset:3056
	v_add3_u32 v128, v104, v236, s50
	ds_write_b16_d16_hi v130, v128 offset:4416
	v_add3_u32 v128, v105, v235, s50
	ds_write_b16_d16_hi v130, v128 offset:4688
	v_add3_u32 v128, v106, v232, s50
	ds_write_b16_d16_hi v130, v128 offset:4960
	v_add3_u32 v128, v107, v230, s50
	ds_write_b16_d16_hi v130, v128 offset:5232
	v_add3_u32 v128, v108, v233, s50
	ds_write_b16_d16_hi v130, v128 offset:6592
	v_add3_u32 v128, v109, v234, s50
	ds_write_b16_d16_hi v130, v128 offset:6864
	v_add3_u32 v128, v110, v231, s50
	ds_write_b16_d16_hi v130, v128 offset:7136
	v_add3_u32 v128, v111, v229, s50
	ds_write_b16_d16_hi v130, v128 offset:7408
	v_add3_u32 v128, v80, v228, s50
	ds_write_b16_d16_hi v130, v128 offset:8704
	v_add3_u32 v128, v81, v252, s50
	ds_write_b16_d16_hi v130, v128 offset:8976
	v_bfe_u32 v128, v82, 16, 1
	v_add3_u32 v128, v82, v128, s50
	ds_write_b16_d16_hi v130, v128 offset:9248
	v_bfe_u32 v128, v83, 16, 1
	v_add3_u32 v128, v83, v128, s50
	ds_write_b16_d16_hi v130, v128 offset:9520
	v_bfe_u32 v128, v84, 16, 1
	v_add3_u32 v128, v84, v128, s50
	ds_write_b16_d16_hi v130, v128 offset:10880
	v_bfe_u32 v128, v85, 16, 1
	v_add3_u32 v128, v85, v128, s50
	ds_write_b16_d16_hi v130, v128 offset:11152
	v_bfe_u32 v128, v86, 16, 1
	v_add3_u32 v128, v86, v128, s50
	ds_write_b16_d16_hi v130, v128 offset:11424
	v_bfe_u32 v128, v87, 16, 1
	v_add3_u32 v128, v87, v128, s50
	ds_write_b16_d16_hi v130, v128 offset:11696
	v_bfe_u32 v128, v88, 16, 1
	v_add3_u32 v128, v88, v128, s50
	ds_write_b16_d16_hi v130, v128 offset:13056
	v_bfe_u32 v128, v89, 16, 1
	v_add3_u32 v128, v89, v128, s50
	ds_write_b16_d16_hi v130, v128 offset:13328
	v_bfe_u32 v128, v90, 16, 1
	v_add3_u32 v128, v90, v128, s50
	ds_write_b16_d16_hi v130, v128 offset:13600
	v_bfe_u32 v128, v91, 16, 1
	v_add3_u32 v128, v91, v128, s50
	ds_write_b16_d16_hi v130, v128 offset:13872
	v_bfe_u32 v128, v92, 16, 1
	v_add3_u32 v128, v92, v128, s50
	ds_write_b16_d16_hi v130, v128 offset:15232
	v_bfe_u32 v128, v93, 16, 1
	v_add3_u32 v128, v93, v128, s50
	ds_write_b16_d16_hi v130, v128 offset:15504
	v_bfe_u32 v128, v94, 16, 1
	v_add3_u32 v128, v94, v128, s50
	ds_write_b16_d16_hi v130, v128 offset:15776
	v_bfe_u32 v128, v95, 16, 1
	v_add3_u32 v128, v95, v128, s50
	ds_write_b16_d16_hi v130, v128 offset:16048
	v_bfe_u32 v128, v64, 16, 1
	v_add3_u32 v128, v64, v128, s50
	ds_write_b16_d16_hi v130, v128 offset:8768
	v_bfe_u32 v128, v65, 16, 1
	v_add3_u32 v128, v65, v128, s50
	ds_write_b16_d16_hi v130, v128 offset:9040
	v_bfe_u32 v128, v66, 16, 1
	v_add3_u32 v128, v66, v128, s50
	ds_write_b16_d16_hi v130, v128 offset:9312
	v_bfe_u32 v128, v67, 16, 1
	v_add3_u32 v128, v67, v128, s50
	ds_write_b16_d16_hi v130, v128 offset:9584
	v_bfe_u32 v128, v68, 16, 1
	v_add3_u32 v128, v68, v128, s50
	ds_write_b16_d16_hi v130, v128 offset:10944
	v_add3_u32 v128, v69, v253, s50
	ds_write_b16_d16_hi v130, v128 offset:11216
	v_add3_u32 v128, v70, v225, s50
	ds_write_b16_d16_hi v130, v128 offset:11488
	v_add3_u32 v128, v71, v223, s50
	ds_write_b16_d16_hi v130, v128 offset:11760
	v_add3_u32 v128, v72, v226, s50
	ds_write_b16_d16_hi v130, v128 offset:13120
	v_add3_u32 v128, v73, v227, s50
	ds_write_b16_d16_hi v130, v128 offset:13392
	v_add3_u32 v128, v74, v224, s50
	ds_write_b16_d16_hi v130, v128 offset:13664
	v_add3_u32 v128, v75, v222, s50
	ds_write_b16_d16_hi v130, v128 offset:13936
	v_add3_u32 v128, v76, v221, s50
	ds_write_b16_d16_hi v130, v128 offset:15296
	v_add3_u32 v128, v77, v218, s50
	ds_write_b16_d16_hi v130, v128 offset:15568
	v_add3_u32 v128, v78, v216, s50
	ds_write_b16_d16_hi v130, v128 offset:15840
	v_add3_u32 v128, v79, v219, s50
	ds_write_b16_d16_hi v130, v128 offset:16112
	v_add3_u32 v128, v48, v220, s50
	ds_write_b16_d16_hi v130, v128 offset:17408
	v_add3_u32 v128, v49, v217, s50
	ds_write_b16_d16_hi v130, v128 offset:17680
	v_add3_u32 v128, v50, v215, s50
	ds_write_b16_d16_hi v130, v128 offset:17952
	v_add3_u32 v128, v51, v214, s50
	ds_write_b16_d16_hi v130, v128 offset:18224
	v_add3_u32 v128, v52, v211, s50
	ds_write_b16_d16_hi v130, v128 offset:19584
	v_add3_u32 v128, v53, v209, s50
	ds_write_b16_d16_hi v130, v128 offset:19856
	v_add3_u32 v128, v54, v212, s50
	ds_write_b16_d16_hi v130, v128 offset:20128
	v_add3_u32 v128, v55, v213, s50
	ds_write_b16_d16_hi v130, v128 offset:20400
	v_add3_u32 v128, v56, v210, s50
	ds_write_b16_d16_hi v130, v128 offset:21760
	v_add3_u32 v128, v57, v208, s50
	ds_write_b16_d16_hi v130, v128 offset:22032
	v_add3_u32 v128, v58, v207, s50
	ds_write_b16_d16_hi v130, v128 offset:22304
	v_add3_u32 v128, v59, v204, s50
	ds_write_b16_d16_hi v130, v128 offset:22576
	v_add3_u32 v128, v60, v202, s50
	ds_write_b16_d16_hi v130, v128 offset:23936
	v_add3_u32 v128, v61, v205, s50
	ds_write_b16_d16_hi v130, v128 offset:24208
	v_add3_u32 v128, v62, v206, s50
	ds_write_b16_d16_hi v130, v128 offset:24480
	v_add3_u32 v128, v63, v203, s50
	ds_write_b16_d16_hi v130, v128 offset:24752
	v_add3_u32 v128, v32, v201, s50
	ds_write_b16_d16_hi v130, v128 offset:17472
	v_add3_u32 v128, v33, v200, s50
	ds_write_b16_d16_hi v130, v128 offset:17744
	v_add3_u32 v128, v34, v197, s50
	ds_write_b16_d16_hi v130, v128 offset:18016
	v_add3_u32 v128, v35, v195, s50
	ds_write_b16_d16_hi v130, v128 offset:18288
	v_add3_u32 v128, v36, v198, s50
	ds_write_b16_d16_hi v130, v128 offset:19648
	v_add3_u32 v128, v37, v199, s50
	ds_write_b16_d16_hi v130, v128 offset:19920
	v_add3_u32 v128, v38, v196, s50
	ds_write_b16_d16_hi v130, v128 offset:20192
	v_add3_u32 v128, v39, v194, s50
	ds_write_b16_d16_hi v130, v128 offset:20464
	v_add3_u32 v128, v40, v193, s50
	ds_write_b16_d16_hi v130, v128 offset:21824
	v_add3_u32 v128, v41, v190, s50
	ds_write_b16_d16_hi v130, v128 offset:22096
	v_add3_u32 v128, v42, v188, s50
	ds_write_b16_d16_hi v130, v128 offset:22368
	v_add3_u32 v128, v43, v191, s50
	ds_write_b16_d16_hi v130, v128 offset:22640
	v_add3_u32 v128, v44, v192, s50
	ds_write_b16_d16_hi v130, v128 offset:24000
	v_add3_u32 v128, v45, v189, s50
	ds_write_b16_d16_hi v130, v128 offset:24272
	v_add3_u32 v128, v46, v187, s50
	ds_write_b16_d16_hi v130, v128 offset:24544
	v_add3_u32 v128, v47, v186, s50
	ds_write_b16_d16_hi v130, v128 offset:24816
	v_add3_u32 v128, v16, v181, s50
	ds_write_b16_d16_hi v130, v128 offset:26112
	v_add3_u32 v128, v17, v179, s50
	ds_write_b16_d16_hi v130, v128 offset:26384
	v_add3_u32 v128, v18, v184, s50
	ds_write_b16_d16_hi v130, v128 offset:26656
	v_add3_u32 v128, v19, v185, s50
	ds_write_b16_d16_hi v130, v128 offset:26928
	v_add3_u32 v128, v20, v180, s50
	ds_write_b16_d16_hi v130, v128 offset:28288
	v_add3_u32 v128, v21, v178, s50
	ds_write_b16_d16_hi v130, v128 offset:28560
	v_add3_u32 v128, v22, v175, s50
	ds_write_b16_d16_hi v130, v128 offset:28832
	v_add3_u32 v128, v23, v173, s50
	ds_write_b16_d16_hi v130, v128 offset:29104
	v_add3_u32 v128, v24, v170, s50
	ds_write_b16_d16_hi v130, v128 offset:30464
	v_add3_u32 v128, v25, v174, s50
	ds_write_b16_d16_hi v130, v128 offset:30736
	v_add3_u32 v128, v26, v171, s50
	ds_write_b16_d16_hi v130, v128 offset:31008
	v_add3_u32 v128, v27, v172, s50
	ds_write_b16_d16_hi v130, v128 offset:31280
	v_add3_u32 v128, v28, v169, s50
	ds_write_b16_d16_hi v130, v128 offset:32640
	v_add3_u32 v128, v29, v168, s50
	ds_write_b16_d16_hi v130, v128 offset:32912
	v_add3_u32 v128, v30, v166, s50
	ds_write_b16_d16_hi v130, v128 offset:33184
	v_add3_u32 v128, v31, v164, s50
	ds_write_b16_d16_hi v130, v128 offset:33456
	v_add3_u32 v128, v0, v167, s50
	ds_write_b16_d16_hi v130, v128 offset:26176
	v_add3_u32 v128, v1, v165, s50
	ds_write_b16_d16_hi v130, v128 offset:26448
	v_add3_u32 v128, v2, v163, s50
	ds_write_b16_d16_hi v130, v128 offset:26720
	v_add3_u32 v128, v3, v162, s50
	ds_write_b16_d16_hi v130, v128 offset:26992
	v_add3_u32 v128, v4, v161, s50
	ds_write_b16_d16_hi v130, v128 offset:28352
	v_add3_u32 v128, v5, v160, s50
	ds_write_b16_d16_hi v130, v128 offset:28624
	v_add3_u32 v128, v6, v159, s50
	ds_write_b16_d16_hi v130, v128 offset:28896
	v_add3_u32 v128, v7, v158, s50
	ds_write_b16_d16_hi v130, v128 offset:29168
	v_add3_u32 v128, v8, v157, s50
	ds_write_b16_d16_hi v130, v128 offset:30528
	v_add3_u32 v128, v9, v156, s50
	ds_write_b16_d16_hi v130, v128 offset:30800
	v_add3_u32 v128, v10, v155, s50
	ds_write_b16_d16_hi v130, v128 offset:31072
	v_add3_u32 v128, v11, v154, s50
	ds_write_b16_d16_hi v130, v128 offset:31344
	v_add3_u32 v128, v12, v153, s50
	ds_write_b16_d16_hi v130, v128 offset:32704
	v_add3_u32 v128, v13, v152, s50
	ds_write_b16_d16_hi v130, v128 offset:32976
	v_add3_u32 v128, v14, v147, s50
	ds_write_b16_d16_hi v130, v128 offset:33248
	v_add3_u32 v128, v15, v151, s50
	ds_write_b16_d16_hi v130, v128 offset:33520

.LBB0_704:
	s_waitcnt lgkmcnt(0)
	s_barrier
	s_waitcnt vmcnt(0)
	ds_write_b128 v165, v[88:91]
	ds_write_b128 v166, v[92:95]
	ds_write_b128 v167, v[112:115]
	ds_write_b128 v168, v[100:103] offset:13312
	ds_write_b128 v169, v[96:99] offset:13312
	s_waitcnt lgkmcnt(0)
	s_barrier
	ds_read_b128 v[32:35], v164
	ds_read_b128 v[88:91], v164 offset:32
	s_waitcnt lgkmcnt(1)
	v_mfma_f32_32x32x16_bf16 v[32:47], v[32:35], v[84:87], 0
	ds_read_b128 v[48:51], v164 offset:6656
	ds_read_b128 v[92:95], v164 offset:6688
	v_mov_b32_e32 v171, v105
	v_mov_b32_e32 v170, v104
	v_lshl_add_u64 v[112:113], s[8:9], 0, v[138:139]
	v_lshl_add_u64 v[148:149], s[8:9], 0, v[136:137]
	v_lshl_add_u64 v[114:115], s[8:9], 0, v[134:135]
	v_lshl_add_u64 v[142:143], s[8:9], 0, v[132:133]
	s_waitcnt lgkmcnt(1)
	v_mfma_f32_32x32x16_bf16 v[48:63], v[48:51], v[84:87], 0
	v_lshl_add_u64 v[140:141], s[8:9], 0, v[130:131]
	v_lshl_add_u64 v[144:145], s[8:9], 0, v[128:129]
	v_lshl_add_u64 v[146:147], s[8:9], 0, v[126:127]
	v_cndmask_b32_e32 v113, v149, v113, vcc
	v_cndmask_b32_e32 v112, v148, v112, vcc
	v_cndmask_b32_e64 v115, v143, v115, s[4:5]
	v_cndmask_b32_e64 v114, v142, v114, s[4:5]
	v_mfma_f32_32x32x16_bf16 v[32:47], v[88:91], v[80:83], v[32:47]
	ds_read_b128 v[88:91], v164 offset:64
	v_lshl_add_u64 v[150:151], s[8:9], 0, v[124:125]
	v_cndmask_b32_e64 v145, v145, v141, s[6:7]
	v_cndmask_b32_e64 v144, v144, v140, s[6:7]
	v_add_u32_e32 v172, v122, v163
	v_add_u32_e32 v143, 0x3000, v172
	v_add_u32_e32 v173, v122, v116
	s_waitcnt lgkmcnt(1)
	v_mfma_f32_32x32x16_bf16 v[48:63], v[92:95], v[80:83], v[48:63]
	ds_read_b128 v[100:103], v164 offset:96
	ds_read_b128 v[92:95], v164 offset:6720
	ds_read_b128 v[96:99], v164 offset:6752
	v_add_u32_e32 v174, v162, v163
	v_add_u32_e32 v175, v162, v116
	v_add_u32_e32 v142, 0x3000, v173
	v_add_u32_e32 v141, 0x3000, v174
	v_add_u32_e32 v140, 0x3000, v175
	s_waitcnt lgkmcnt(3)
	v_mfma_f32_32x32x16_bf16 v[32:47], v[88:91], v[76:79], v[32:47]
	s_add_i32 s0, s0, -1
	v_lshl_add_u64 v[124:125], v[124:125], 0, s[42:43]
	v_lshl_add_u64 v[126:127], v[126:127], 0, s[42:43]
	v_lshl_add_u64 v[128:129], v[128:129], 0, s[44:45]
	v_lshl_add_u64 v[130:131], v[130:131], 0, s[46:47]
	v_lshl_add_u64 v[132:133], v[132:133], 0, s[44:45]
	v_lshl_add_u64 v[134:135], v[134:135], 0, s[46:47]
	s_waitcnt lgkmcnt(1)
	v_mfma_f32_32x32x16_bf16 v[48:63], v[92:95], v[76:79], v[48:63]
	ds_read_b128 v[88:91], v164 offset:128
	ds_read_b128 v[104:107], v164 offset:160
	ds_read_b128 v[92:95], v164 offset:6784
	ds_read_b128 v[108:111], v164 offset:6816
	v_lshl_add_u64 v[136:137], v[136:137], 0, s[44:45]
	v_lshl_add_u64 v[138:139], v[138:139], 0, s[46:47]
	s_cmp_lg_u32 s0, 0
	v_mfma_f32_32x32x16_bf16 v[32:47], v[100:103], v[72:75], v[32:47]
	s_waitcnt lgkmcnt(4)
	v_mfma_f32_32x32x16_bf16 v[48:63], v[96:99], v[72:75], v[48:63]
	global_load_dwordx4 v[100:103], v[146:147], off
	global_load_dwordx4 v[96:99], v[150:151], off
	s_waitcnt lgkmcnt(0)
	v_mfma_f32_32x32x16_bf16 v[32:47], v[88:91], v[68:71], v[32:47]
	v_mfma_f32_32x32x16_bf16 v[48:63], v[92:95], v[68:71], v[48:63]
	global_load_dwordx4 v[88:91], v[112:113], off
	global_load_dwordx4 v[92:95], v[114:115], off
	s_nop 0
	global_load_dwordx4 v[112:115], v[144:145], off
	ds_read2_b64 v[144:147], v143 offset0:128 offset1:130
	ds_read2_b64 v[148:151], v143 offset0:132 offset1:134
	ds_read2_b64 v[172:175], v142 offset0:128 offset1:130
	ds_read2_b64 v[176:179], v142 offset0:132 offset1:134
	ds_read2_b64 v[180:183], v143 offset0:136 offset1:138
	ds_read2_b64 v[184:187], v142 offset0:136 offset1:138
	ds_read2_b64 v[188:191], v141 offset0:140 offset1:142
	ds_read2_b64 v[192:195], v140 offset0:140 offset1:142
	v_mfma_f32_32x32x16_bf16 v[32:47], v[104:107], v[64:67], v[32:47]
	v_mfma_f32_32x32x16_bf16 v[48:63], v[108:111], v[64:67], v[48:63]
	s_nop 10
	v_max_f32_e32 v104, v33, v33
	v_max_f32_e32 v105, v32, v32
	v_max_f32_e32 v104, v105, v104
	v_max3_f32 v104, v104, v34, v35
	v_max3_f32 v104, v104, v36, v37
	v_max3_f32 v104, v104, v38, v39
	v_max3_f32 v104, v104, v40, v41
	v_max3_f32 v104, v104, v42, v43
	v_max3_f32 v104, v104, v44, v45
	v_max3_f32 v104, v104, v46, v47
	v_max3_f32 v104, v104, v48, v49
	v_max3_f32 v104, v104, v50, v51
	v_max3_f32 v104, v104, v52, v53
	v_max3_f32 v104, v104, v54, v55
	v_max3_f32 v104, v104, v56, v57
	v_max3_f32 v104, v104, v58, v59
	v_max3_f32 v104, v104, v60, v61
	v_max3_f32 v104, v104, v62, v63
	ds_bpermute_b32 v105, v123, v104
	s_waitcnt lgkmcnt(0)
	v_max3_f32 v105, v171, v104, v105
	v_sub_f32_e32 v104, v171, v105
	v_sub_f32_e32 v32, v32, v105
	v_sub_f32_e32 v33, v33, v105
	v_sub_f32_e32 v34, v34, v105
	v_sub_f32_e32 v35, v35, v105
	v_sub_f32_e32 v36, v36, v105
	v_sub_f32_e32 v37, v37, v105
	v_sub_f32_e32 v38, v38, v105
	v_sub_f32_e32 v39, v39, v105
	v_sub_f32_e32 v106, v42, v105
	v_exp_f32_e32 v42, v104
	v_exp_f32_e32 v32, v32
	v_exp_f32_e32 v33, v33
	s_nop 0
	v_cvt_pk_bf16_f32 v223, v32, v33
	v_exp_f32_e32 v104, v34
	v_exp_f32_e32 v107, v35
	v_exp_f32_e32 v108, v36
	v_exp_f32_e32 v109, v37
	v_exp_f32_e32 v110, v38
	v_exp_f32_e32 v111, v39
	v_sub_f32_e32 v43, v43, v105
	v_sub_f32_e32 v40, v40, v105
	v_sub_f32_e32 v41, v41, v105
	v_exp_f32_e32 v43, v43
	v_exp_f32_e32 v171, v40
	v_exp_f32_e32 v196, v41
	v_add_f32_e32 v34, 0, v32
	v_bfe_u32 v39, v32, 16, 1
	v_add_f32_e32 v222, v33, v34
	v_add3_u32 v32, v32, v39, s59
	v_lshrrev_b32_e32 v32, 16, v32
	v_sub_f32_e32 v44, v44, v105
	v_sub_f32_e32 v45, v45, v105
	v_sub_f32_e32 v46, v46, v105
	v_pk_mul_f32 v[30:31], v[30:31], v[42:43] op_sel_hi:[1,0]
	v_pk_mul_f32 v[28:29], v[28:29], v[42:43] op_sel_hi:[1,0]
	v_pk_mul_f32 v[26:27], v[26:27], v[42:43] op_sel_hi:[1,0]
	v_pk_mul_f32 v[24:25], v[24:25], v[42:43] op_sel_hi:[1,0]
	v_pk_mul_f32 v[22:23], v[22:23], v[42:43] op_sel_hi:[1,0]
	v_pk_mul_f32 v[20:21], v[20:21], v[42:43] op_sel_hi:[1,0]
	v_pk_mul_f32 v[18:19], v[18:19], v[42:43] op_sel_hi:[1,0]
	v_pk_mul_f32 v[16:17], v[16:17], v[42:43] op_sel_hi:[1,0]
	v_pk_mul_f32 v[14:15], v[14:15], v[42:43] op_sel_hi:[1,0]
	v_pk_mul_f32 v[12:13], v[12:13], v[42:43] op_sel_hi:[1,0]
	v_pk_mul_f32 v[10:11], v[10:11], v[42:43] op_sel_hi:[1,0]
	v_pk_mul_f32 v[8:9], v[8:9], v[42:43] op_sel_hi:[1,0]
	v_pk_mul_f32 v[6:7], v[6:7], v[42:43] op_sel_hi:[1,0]
	v_pk_mul_f32 v[4:5], v[4:5], v[42:43] op_sel_hi:[1,0]
	v_pk_mul_f32 v[2:3], v[2:3], v[42:43] op_sel_hi:[1,0]
	v_pk_mul_f32 v[0:1], v[0:1], v[42:43] op_sel_hi:[1,0]
	v_cvt_pk_bf16_f32 v35, v110, v111
	v_cvt_pk_bf16_f32 v34, v108, v109
	v_cvt_pk_bf16_f32 v33, v104, v107
	v_mov_b32_e32 v32, v223
	v_sub_f32_e32 v47, v47, v105
	v_exp_f32_e32 v106, v106
	v_exp_f32_e32 v44, v44
	v_exp_f32_e32 v45, v45
	v_exp_f32_e32 v46, v46
	v_mfma_f32_32x32x16_bf16 v[16:31], v[144:147], v[32:35], v[16:31]
	v_exp_f32_e32 v47, v47
	v_bfe_u32 v199, v45, 16, 1
	v_bfe_u32 v202, v171, 16, 1
	v_bfe_u32 v203, v106, 16, 1
	v_bfe_u32 v204, v44, 16, 1
	v_mfma_f32_32x32x16_bf16 v[0:15], v[172:175], v[32:35], v[0:15]
	v_bfe_u32 v205, v46, 16, 1
	v_bfe_u32 v198, v47, 16, 1
	v_add3_u32 v197, v45, v199, s59
	v_add3_u32 v199, v46, v205, s59
	v_add3_u32 v200, v44, v204, s59
	v_add3_u32 v201, v106, v203, s59
	v_add3_u32 v202, v171, v202, s59
	v_add3_u32 v198, v47, v198, s59
	v_add_f32_e32 v37, v104, v222
	v_lshrrev_b32_e32 v144, 16, v199
	v_cvt_pk_bf16_f32 v35, v46, v47
	v_cvt_pk_bf16_f32 v34, v44, v45
	v_cvt_pk_bf16_f32 v33, v106, v43
	v_cvt_pk_bf16_f32 v32, v171, v196
	v_add_f32_e32 v104, v107, v37
	v_sub_f32_e32 v48, v48, v105
	v_mfma_f32_32x32x16_bf16 v[16:31], v[148:151], v[32:35], v[16:31]
	v_sub_f32_e32 v49, v49, v105
	v_sub_f32_e32 v50, v50, v105
	v_sub_f32_e32 v51, v51, v105
	v_sub_f32_e32 v52, v52, v105
	v_sub_f32_e32 v53, v53, v105
	v_sub_f32_e32 v54, v54, v105
	v_sub_f32_e32 v55, v55, v105
	v_mfma_f32_32x32x16_bf16 v[0:15], v[176:179], v[32:35], v[0:15]
	v_add_f32_e32 v32, v108, v104
	v_add_f32_e32 v32, v109, v32
	v_add_f32_e32 v32, v110, v32
	v_add_f32_e32 v32, v111, v32
	v_add_f32_e32 v32, v171, v32
	v_sub_f32_e32 v56, v56, v105
	v_exp_f32_e32 v48, v48
	v_exp_f32_e32 v49, v49
	v_exp_f32_e32 v50, v50
	v_exp_f32_e32 v51, v51
	v_exp_f32_e32 v52, v52
	v_exp_f32_e32 v53, v53
	v_exp_f32_e32 v54, v54
	v_add_f32_e32 v32, v196, v32
	v_exp_f32_e32 v55, v55
	v_exp_f32_e32 v56, v56
	v_add_f32_e32 v32, v106, v32
	v_add_f32_e32 v32, v43, v32
	v_add_f32_e32 v32, v44, v32
	v_bfe_u32 v207, v53, 16, 1
	v_bfe_u32 v208, v51, 16, 1
	v_bfe_u32 v209, v49, 16, 1
	v_bfe_u32 v210, v48, 16, 1
	v_bfe_u32 v211, v50, 16, 1
	v_bfe_u32 v212, v52, 16, 1
	v_bfe_u32 v213, v54, 16, 1
	v_add_f32_e32 v32, v45, v32
	v_bfe_u32 v206, v55, 16, 1
	v_bfe_u32 v218, v56, 16, 1
	v_add3_u32 v203, v49, v209, s59
	v_add3_u32 v204, v51, v208, s59
	v_add3_u32 v205, v53, v207, s59
	v_add3_u32 v207, v54, v213, s59
	v_add3_u32 v208, v52, v212, s59
	v_add3_u32 v209, v50, v211, s59
	v_add3_u32 v210, v48, v210, s59
	v_add_f32_e32 v32, v46, v32
	v_add3_u32 v206, v55, v206, s59
	v_lshrrev_b32_e32 v145, 16, v210
	v_lshrrev_b32_e32 v146, 16, v209
	v_lshrrev_b32_e32 v147, 16, v208
	v_lshrrev_b32_e32 v172, 16, v207
	v_add_f32_e32 v32, v47, v32
	v_sub_f32_e32 v57, v57, v105
	v_sub_f32_e32 v58, v58, v105
	v_sub_f32_e32 v59, v59, v105
	v_sub_f32_e32 v60, v60, v105
	v_sub_f32_e32 v61, v61, v105
	v_sub_f32_e32 v62, v62, v105
	v_cvt_pk_bf16_f32 v37, v54, v55
	v_cvt_pk_bf16_f32 v36, v52, v53
	v_cvt_pk_bf16_f32 v35, v50, v51
	v_cvt_pk_bf16_f32 v34, v48, v49
	v_add_f32_e32 v32, v48, v32
	v_sub_f32_e32 v63, v63, v105
	v_exp_f32_e32 v57, v57
	v_exp_f32_e32 v58, v58
	v_exp_f32_e32 v59, v59
	v_exp_f32_e32 v60, v60
	v_exp_f32_e32 v61, v61
	v_exp_f32_e32 v62, v62
	v_mfma_f32_32x32x16_bf16 v[16:31], v[180:183], v[34:37], v[16:31]
	v_add_f32_e32 v32, v49, v32
	v_exp_f32_e32 v63, v63
	v_add_f32_e32 v32, v50, v32
	v_add_f32_e32 v32, v51, v32
	v_add_f32_e32 v32, v52, v32
	v_bfe_u32 v215, v61, 16, 1
	v_bfe_u32 v216, v59, 16, 1
	v_mfma_f32_32x32x16_bf16 v[0:15], v[184:187], v[34:37], v[0:15]
	v_bfe_u32 v217, v57, 16, 1
	v_bfe_u32 v219, v58, 16, 1
	v_bfe_u32 v220, v60, 16, 1
	v_bfe_u32 v221, v62, 16, 1
	v_add_f32_e32 v32, v53, v32
	v_bfe_u32 v214, v63, 16, 1
	v_add3_u32 v211, v57, v217, s59
	v_add3_u32 v212, v59, v216, s59
	v_add3_u32 v213, v61, v215, s59
	v_add3_u32 v215, v62, v221, s59
	v_add3_u32 v216, v60, v220, s59
	v_add3_u32 v217, v58, v219, s59
	v_add_f32_e32 v32, v54, v32
	v_add3_u32 v214, v63, v214, s59
	v_add_f32_e32 v32, v55, v32
	v_cvt_pk_bf16_f32 v41, v62, v63
	v_cvt_pk_bf16_f32 v40, v60, v61
	v_cvt_pk_bf16_f32 v39, v58, v59
	v_cvt_pk_bf16_f32 v38, v56, v57
	v_add_f32_e32 v32, v56, v32
	v_add_f32_e32 v32, v57, v32
	v_mfma_f32_32x32x16_bf16 v[16:31], v[188:191], v[38:41], v[16:31]
	v_add_f32_e32 v32, v58, v32
	v_add_f32_e32 v32, v59, v32
	v_add_f32_e32 v32, v60, v32
	v_add_f32_e32 v32, v61, v32
	v_add_f32_e32 v32, v62, v32
	v_add_f32_e32 v104, v63, v32
	v_fmac_f32_e32 v104, v170, v42
	v_mfma_f32_32x32x16_bf16 v[0:15], v[192:195], v[38:41], v[0:15]
	s_cbranch_scc1 .LBB0_704
	s_barrier
	s_waitcnt vmcnt(0)
	ds_write_b128 v165, v[88:91]
	ds_write_b128 v166, v[92:95]
	ds_write_b128 v167, v[112:115]
	ds_write_b128 v168, v[100:103] offset:13312
	ds_write_b128 v169, v[96:99] offset:13312
	s_waitcnt lgkmcnt(0)
	s_barrier
	ds_read_b128 v[32:35], v164
	ds_read_b128 v[36:39], v164 offset:32
	s_waitcnt lgkmcnt(1)
	v_mfma_f32_32x32x16_bf16 v[48:63], v[32:35], v[84:87], 0
	s_waitcnt lgkmcnt(0)
	v_mfma_f32_32x32x16_bf16 v[48:63], v[36:39], v[80:83], v[48:63]
	ds_read_b128 v[32:35], v164 offset:64
	ds_read_b128 v[36:39], v164 offset:96
	s_waitcnt lgkmcnt(1)
	v_mfma_f32_32x32x16_bf16 v[48:63], v[32:35], v[76:79], v[48:63]
	s_waitcnt lgkmcnt(0)
	v_mfma_f32_32x32x16_bf16 v[48:63], v[36:39], v[72:75], v[48:63]
	ds_read_b128 v[32:35], v164 offset:128
	ds_read_b128 v[36:39], v164 offset:160
	s_waitcnt lgkmcnt(1)
	v_mfma_f32_32x32x16_bf16 v[48:63], v[32:35], v[68:71], v[48:63]
	ds_read_b128 v[32:35], v164 offset:6656
	ds_read_b128 v[88:91], v164 offset:6688
	s_waitcnt lgkmcnt(2)
	v_mfma_f32_32x32x16_bf16 v[48:63], v[36:39], v[64:67], v[48:63]
	s_waitcnt lgkmcnt(1)
	v_mfma_f32_32x32x16_bf16 v[32:47], v[32:35], v[84:87], 0
	s_waitcnt lgkmcnt(0)
	v_mfma_f32_32x32x16_bf16 v[32:47], v[88:91], v[80:83], v[32:47]
	ds_read_b128 v[80:83], v164 offset:6720
	ds_read_b128 v[84:87], v164 offset:6752
	s_waitcnt lgkmcnt(1)
	v_mfma_f32_32x32x16_bf16 v[32:47], v[80:83], v[76:79], v[32:47]
	s_nop 3
	v_max_f32_e32 v80, v49, v49
	v_max_f32_e32 v81, v48, v48
	v_max_f32_e32 v80, v81, v80
	s_waitcnt lgkmcnt(0)
	v_mfma_f32_32x32x16_bf16 v[32:47], v[84:87], v[72:75], v[32:47]
	ds_read_b128 v[72:75], v164 offset:6784
	ds_read_b128 v[76:79], v164 offset:6816
	s_waitcnt lgkmcnt(1)
	v_mfma_f32_32x32x16_bf16 v[32:47], v[72:75], v[68:71], v[32:47]
	v_max3_f32 v68, v80, v50, v51
	v_max3_f32 v68, v68, v52, v53
	v_max3_f32 v68, v68, v54, v55
	v_max3_f32 v68, v68, v56, v57
	v_max3_f32 v68, v68, v58, v59
	v_max3_f32 v68, v68, v60, v61
	v_max3_f32 v68, v68, v62, v63
	s_waitcnt lgkmcnt(0)
	v_mfma_f32_32x32x16_bf16 v[32:47], v[76:79], v[64:67], v[32:47]
	s_nop 11
	v_max3_f32 v64, v68, v32, v33
	v_max3_f32 v64, v64, v34, v35
	v_max3_f32 v64, v64, v36, v37
	v_max3_f32 v64, v64, v38, v39
	v_max3_f32 v64, v64, v40, v41
	v_max3_f32 v64, v64, v42, v43
	v_max3_f32 v64, v64, v44, v45
	v_max3_f32 v64, v64, v46, v47
	ds_bpermute_b32 v65, v123, v64
	s_waitcnt lgkmcnt(0)
	v_max3_f32 v65, v105, v64, v65
	v_sub_f32_e32 v32, v32, v65
	v_exp_f32_e32 v66, v32
	v_sub_f32_e32 v32, v33, v65
	v_exp_f32_e32 v67, v32
	v_sub_f32_e32 v32, v34, v65
	v_exp_f32_e32 v68, v32
	v_sub_f32_e32 v32, v35, v65
	v_exp_f32_e32 v69, v32
	v_sub_f32_e32 v32, v36, v65
	v_exp_f32_e32 v70, v32
	v_sub_f32_e32 v32, v37, v65
	v_exp_f32_e32 v71, v32
	v_sub_f32_e32 v32, v38, v65
	v_exp_f32_e32 v72, v32
	v_sub_f32_e32 v32, v39, v65
	v_exp_f32_e32 v73, v32
	v_sub_f32_e32 v32, v40, v65
	v_exp_f32_e32 v74, v32
	v_sub_f32_e32 v32, v41, v65
	v_exp_f32_e32 v75, v32
	v_sub_f32_e32 v32, v42, v65
	v_sub_f32_e32 v48, v48, v65
	v_exp_f32_e32 v76, v32
	v_sub_f32_e32 v32, v43, v65
	v_exp_f32_e32 v48, v48
	v_sub_f32_e32 v49, v49, v65
	v_exp_f32_e32 v77, v32
	v_sub_f32_e32 v32, v44, v65
	v_exp_f32_e32 v49, v49
	v_sub_f32_e32 v50, v50, v65
	v_sub_f32_e32 v55, v55, v65
	v_exp_f32_e32 v78, v32
	v_sub_f32_e32 v32, v45, v65
	v_exp_f32_e32 v50, v50
	v_sub_f32_e32 v51, v51, v65
	v_sub_f32_e32 v53, v53, v65
	v_exp_f32_e32 v55, v55
	v_exp_f32_e32 v79, v32
	v_sub_f32_e32 v32, v46, v65
	v_exp_f32_e32 v51, v51
	v_sub_f32_e32 v52, v52, v65
	v_exp_f32_e32 v53, v53
	v_sub_f32_e32 v54, v54, v65
	v_exp_f32_e32 v80, v32
	v_sub_f32_e32 v32, v47, v65
	v_sub_f32_e32 v64, v105, v65
	v_exp_f32_e32 v52, v52
	v_exp_f32_e32 v54, v54
	v_sub_f32_e32 v56, v56, v65
	v_sub_f32_e32 v57, v57, v65
	v_sub_f32_e32 v58, v58, v65
	v_sub_f32_e32 v59, v59, v65
	v_sub_f32_e32 v60, v60, v65
	v_sub_f32_e32 v61, v61, v65
	v_sub_f32_e32 v62, v62, v65
	v_sub_f32_e32 v63, v63, v65
	v_exp_f32_e32 v65, v32
	v_add_f32_e32 v32, 0, v48
	v_add_f32_e32 v32, v49, v32
	v_add_f32_e32 v44, v50, v32
	ds_read2_b64 v[32:35], v143 offset0:128 offset1:130
	v_exp_f32_e32 v64, v64
	v_cvt_pk_bf16_f32 v39, v54, v55
	v_cvt_pk_bf16_f32 v38, v52, v53
	v_cvt_pk_bf16_f32 v37, v50, v51
	v_cvt_pk_bf16_f32 v36, v48, v49
	ds_read2_b64 v[40:43], v142 offset0:128 offset1:130
	v_pk_mul_f32 v[30:31], v[30:31], v[64:65] op_sel_hi:[1,0]
	v_pk_mul_f32 v[28:29], v[28:29], v[64:65] op_sel_hi:[1,0]
	v_pk_mul_f32 v[26:27], v[26:27], v[64:65] op_sel_hi:[1,0]
	v_pk_mul_f32 v[24:25], v[24:25], v[64:65] op_sel_hi:[1,0]
	v_pk_mul_f32 v[22:23], v[22:23], v[64:65] op_sel_hi:[1,0]
	v_pk_mul_f32 v[20:21], v[20:21], v[64:65] op_sel_hi:[1,0]
	v_pk_mul_f32 v[18:19], v[18:19], v[64:65] op_sel_hi:[1,0]
	v_pk_mul_f32 v[16:17], v[16:17], v[64:65] op_sel_hi:[1,0]
	v_exp_f32_e32 v57, v57
	v_exp_f32_e32 v59, v59
	s_waitcnt lgkmcnt(1)
	v_mfma_f32_32x32x16_bf16 v[16:31], v[32:35], v[36:39], v[16:31]
	v_add_f32_e32 v32, v51, v44
	v_exp_f32_e32 v56, v56
	v_exp_f32_e32 v58, v58
	v_exp_f32_e32 v60, v60
	v_exp_f32_e32 v62, v62
	v_add_f32_e32 v32, v52, v32
	v_exp_f32_e32 v61, v61
	v_exp_f32_e32 v63, v63
	v_add_f32_e32 v32, v53, v32
	v_pk_mul_f32 v[14:15], v[14:15], v[64:65] op_sel_hi:[1,0]
	v_pk_mul_f32 v[12:13], v[12:13], v[64:65] op_sel_hi:[1,0]
	v_pk_mul_f32 v[10:11], v[10:11], v[64:65] op_sel_hi:[1,0]
	v_pk_mul_f32 v[8:9], v[8:9], v[64:65] op_sel_hi:[1,0]
	v_pk_mul_f32 v[6:7], v[6:7], v[64:65] op_sel_hi:[1,0]
	v_pk_mul_f32 v[4:5], v[4:5], v[64:65] op_sel_hi:[1,0]
	v_pk_mul_f32 v[2:3], v[2:3], v[64:65] op_sel_hi:[1,0]
	v_pk_mul_f32 v[0:1], v[0:1], v[64:65] op_sel_hi:[1,0]
	v_add_f32_e32 v32, v54, v32
	v_add_f32_e32 v48, v55, v32
	s_waitcnt lgkmcnt(0)
	v_mfma_f32_32x32x16_bf16 v[0:15], v[40:43], v[36:39], v[0:15]
	ds_read2_b64 v[32:35], v143 offset0:132 offset1:134
	ds_read2_b64 v[44:47], v142 offset0:132 offset1:134
	v_add_f32_e32 v40, v56, v48
	v_bfe_u32 v38, v56, 16, 1
	v_bfe_u32 v39, v58, 16, 1
	v_bfe_u32 v48, v62, 16, 1
	v_add3_u32 v48, v62, v48, s59
	v_add3_u32 v39, v58, v39, s59
	v_add3_u32 v38, v56, v38, s59
	v_lshrrev_b32_e32 v49, 16, v38
	v_lshrrev_b32_e32 v50, 16, v39
	v_cvt_pk_bf16_f32 v39, v62, v63
	v_cvt_pk_bf16_f32 v38, v60, v61
	v_cvt_pk_bf16_f32 v37, v58, v59
	v_cvt_pk_bf16_f32 v36, v56, v57
	s_waitcnt lgkmcnt(1)
	s_nop 0
	v_mfma_f32_32x32x16_bf16 v[16:31], v[32:35], v[36:39], v[16:31]
	v_add_f32_e32 v32, v57, v40
	v_add_f32_e32 v32, v58, v32
	v_add_f32_e32 v32, v59, v32
	v_add_f32_e32 v32, v60, v32
	v_add_f32_e32 v32, v61, v32
	v_add_f32_e32 v32, v62, v32
	v_add_f32_e32 v32, v63, v32
	s_waitcnt lgkmcnt(0)
	v_mfma_f32_32x32x16_bf16 v[0:15], v[44:47], v[36:39], v[0:15]
	v_add_f32_e32 v44, v66, v32
	ds_read2_b64 v[32:35], v143 offset0:136 offset1:138
	v_cvt_pk_bf16_f32 v39, v72, v73
	v_cvt_pk_bf16_f32 v38, v70, v71
	v_cvt_pk_bf16_f32 v37, v68, v69
	v_cvt_pk_bf16_f32 v36, v66, v67
	ds_read2_b64 v[40:43], v142 offset0:136 offset1:138
	s_waitcnt lgkmcnt(1)
	v_mfma_f32_32x32x16_bf16 v[16:31], v[32:35], v[36:39], v[16:31]
	v_add_f32_e32 v32, v67, v44
	v_add_f32_e32 v32, v68, v32
	v_add_f32_e32 v32, v69, v32
	v_add_f32_e32 v32, v70, v32
	v_add_f32_e32 v32, v71, v32
	v_add_f32_e32 v32, v72, v32
	v_add_f32_e32 v32, v73, v32
	v_add_f32_e32 v32, v74, v32
	v_add_f32_e32 v32, v75, v32
	v_add_f32_e32 v32, v76, v32
	v_add_f32_e32 v32, v77, v32
	v_add_f32_e32 v32, v78, v32
	v_add_f32_e32 v32, v79, v32
	v_add_f32_e32 v32, v80, v32
	s_waitcnt lgkmcnt(0)
	v_mfma_f32_32x32x16_bf16 v[0:15], v[40:43], v[36:39], v[0:15]
	v_add_f32_e32 v40, v65, v32
	v_bfe_u32 v32, v74, 16, 1
	v_bfe_u32 v33, v76, 16, 1
	v_add3_u32 v33, v76, v33, s59
	v_add3_u32 v32, v74, v32, s59
	v_lshrrev_b32_e32 v43, 16, v32
	v_lshrrev_b32_e32 v44, 16, v33
	ds_read2_b64 v[32:35], v141 offset0:140 offset1:142
	v_fmac_f32_e32 v40, v104, v64
	v_cvt_pk_bf16_f32 v39, v80, v65
	ds_bpermute_b32 v41, v123, v40
	v_cvt_pk_bf16_f32 v38, v78, v79
	v_cvt_pk_bf16_f32 v37, v76, v77
	v_cvt_pk_bf16_f32 v36, v74, v75
	v_mov_b32_e32 v123, v117
	s_waitcnt lgkmcnt(0)
	v_add_f32_e32 v40, v40, v41
	v_mfma_f32_32x32x16_bf16 v[16:31], v[32:35], v[36:39], v[16:31]
	ds_read2_b64 v[32:35], v140 offset0:140 offset1:142
	v_div_scale_f32 v41, s[0:1], v40, v40, 1.0
	v_rcp_f32_e32 v42, v41
	s_waitcnt lgkmcnt(0)
	v_mfma_f32_32x32x16_bf16 v[0:15], v[32:35], v[36:39], v[0:15]
	v_fma_f32 v32, -v41, v42, 1.0
	v_fmac_f32_e32 v42, v32, v42
	v_div_scale_f32 v32, vcc, 1.0, v40, 1.0
	v_mul_f32_e32 v33, v32, v42
	v_fma_f32 v34, -v41, v33, v32
	v_fmac_f32_e32 v33, v34, v42
	v_fma_f32 v32, -v41, v33, v32
	v_div_fmas_f32 v32, v32, v42, v33
	v_div_fixup_f32 v32, v32, v40, 1.0
	v_mov_b32_e32 v38, v16
	v_mov_b32_e32 v39, v18
	v_mov_b32_e32 v18, v17
	v_lshlrev_b64 v[34:35], 11, v[118:119]
	v_pk_mul_f32 v[38:39], v[38:39], v[32:33] op_sel_hi:[1,0]
	v_pk_mul_f32 v[16:17], v[18:19], v[32:33] op_sel_hi:[1,0]
	v_lshl_add_u64 v[34:35], s[8:9], 0, v[34:35]
	v_and_b32_sdwa v19, v38, v159 dst_sel:DWORD dst_unused:UNUSED_PAD src0_sel:WORD_1 src1_sel:DWORD
	v_and_b32_sdwa v33, v17, v159 dst_sel:DWORD dst_unused:UNUSED_PAD src0_sel:WORD_1 src1_sel:DWORD
	v_lshl_add_u64 v[34:35], v[120:121], 1, v[34:35]
	v_and_b32_sdwa v18, v39, v159 dst_sel:DWORD dst_unused:UNUSED_PAD src0_sel:WORD_1 src1_sel:DWORD
	v_add3_u32 v19, v38, v19, s59
	v_and_b32_sdwa v38, v16, v159 dst_sel:DWORD dst_unused:UNUSED_PAD src0_sel:WORD_1 src1_sel:DWORD
	v_add3_u32 v17, v17, v33, s59
	v_lshl_add_u64 v[34:35], v[34:35], 0, v[122:123]
	v_add3_u32 v18, v39, v18, s59
	v_add3_u32 v16, v16, v38, s59
	v_and_b32_e32 v17, 0xffff0000, v17
	v_and_b32_e32 v16, 0xffff0000, v16
	v_or_b32_sdwa v17, v17, v18 dst_sel:DWORD dst_unused:UNUSED_PAD src0_sel:DWORD src1_sel:WORD_1
	v_add_co_u32_e32 v18, vcc, s61, v34
	v_or_b32_sdwa v16, v16, v19 dst_sel:DWORD dst_unused:UNUSED_PAD src0_sel:DWORD src1_sel:WORD_1
	s_nop 0
	v_addc_co_u32_e32 v19, vcc, 0, v35, vcc
	global_store_dwordx2 v[18:19], v[16:17], off offset:3840
	v_mov_b32_e32 v16, v20
	v_mov_b32_e32 v17, v22
	v_pk_mul_f32 v[16:17], v[16:17], v[32:33] op_sel_hi:[1,0]
	v_mov_b32_e32 v22, v21
	v_pk_mul_f32 v[18:19], v[22:23], v[32:33] op_sel_hi:[1,0]
	v_and_b32_sdwa v20, v17, v159 dst_sel:DWORD dst_unused:UNUSED_PAD src0_sel:WORD_1 src1_sel:DWORD
	v_and_b32_sdwa v21, v16, v159 dst_sel:DWORD dst_unused:UNUSED_PAD src0_sel:WORD_1 src1_sel:DWORD
	v_add3_u32 v16, v16, v21, s59
	v_add3_u32 v17, v17, v20, s59
	v_and_b32_sdwa v20, v19, v159 dst_sel:DWORD dst_unused:UNUSED_PAD src0_sel:WORD_1 src1_sel:DWORD
	v_and_b32_sdwa v21, v18, v159 dst_sel:DWORD dst_unused:UNUSED_PAD src0_sel:WORD_1 src1_sel:DWORD
	v_add3_u32 v19, v19, v20, s59
	v_add3_u32 v18, v18, v21, s59
	v_and_b32_e32 v19, 0xffff0000, v19
	v_and_b32_e32 v18, 0xffff0000, v18
	v_lshl_add_u64 v[36:37], v[34:35], 0, s[48:49]
	v_or_b32_sdwa v17, v19, v17 dst_sel:DWORD dst_unused:UNUSED_PAD src0_sel:DWORD src1_sel:WORD_1
	v_or_b32_sdwa v16, v18, v16 dst_sel:DWORD dst_unused:UNUSED_PAD src0_sel:DWORD src1_sel:WORD_1
	global_store_dwordx2 v[36:37], v[16:17], off offset:16
	v_mov_b32_e32 v16, v24
	v_mov_b32_e32 v17, v26
	v_pk_mul_f32 v[16:17], v[16:17], v[32:33] op_sel_hi:[1,0]
	v_mov_b32_e32 v26, v25
	v_pk_mul_f32 v[18:19], v[26:27], v[32:33] op_sel_hi:[1,0]
	v_and_b32_sdwa v20, v17, v159 dst_sel:DWORD dst_unused:UNUSED_PAD src0_sel:WORD_1 src1_sel:DWORD
	v_and_b32_sdwa v21, v16, v159 dst_sel:DWORD dst_unused:UNUSED_PAD src0_sel:WORD_1 src1_sel:DWORD
	v_add3_u32 v16, v16, v21, s59
	v_add3_u32 v17, v17, v20, s59
	v_and_b32_sdwa v20, v19, v159 dst_sel:DWORD dst_unused:UNUSED_PAD src0_sel:WORD_1 src1_sel:DWORD
	v_and_b32_sdwa v21, v18, v159 dst_sel:DWORD dst_unused:UNUSED_PAD src0_sel:WORD_1 src1_sel:DWORD
	v_add3_u32 v19, v19, v20, s59
	v_add3_u32 v18, v18, v21, s59
	v_and_b32_e32 v19, 0xffff0000, v19
	v_and_b32_e32 v18, 0xffff0000, v18
	v_or_b32_sdwa v17, v19, v17 dst_sel:DWORD dst_unused:UNUSED_PAD src0_sel:DWORD src1_sel:WORD_1
	v_or_b32_sdwa v16, v18, v16 dst_sel:DWORD dst_unused:UNUSED_PAD src0_sel:DWORD src1_sel:WORD_1
	global_store_dwordx2 v[36:37], v[16:17], off offset:32
	v_mov_b32_e32 v16, v28
	v_mov_b32_e32 v17, v30
	v_pk_mul_f32 v[16:17], v[16:17], v[32:33] op_sel_hi:[1,0]
	v_mov_b32_e32 v30, v29
	v_pk_mul_f32 v[18:19], v[30:31], v[32:33] op_sel_hi:[1,0]
	v_and_b32_sdwa v20, v17, v159 dst_sel:DWORD dst_unused:UNUSED_PAD src0_sel:WORD_1 src1_sel:DWORD
	v_and_b32_sdwa v21, v16, v159 dst_sel:DWORD dst_unused:UNUSED_PAD src0_sel:WORD_1 src1_sel:DWORD
	v_add3_u32 v16, v16, v21, s59
	v_add3_u32 v17, v17, v20, s59
	v_and_b32_sdwa v20, v19, v159 dst_sel:DWORD dst_unused:UNUSED_PAD src0_sel:WORD_1 src1_sel:DWORD
	v_and_b32_sdwa v21, v18, v159 dst_sel:DWORD dst_unused:UNUSED_PAD src0_sel:WORD_1 src1_sel:DWORD
	v_add3_u32 v19, v19, v20, s59
	v_add3_u32 v18, v18, v21, s59
	v_and_b32_e32 v19, 0xffff0000, v19
	v_and_b32_e32 v18, 0xffff0000, v18
	v_or_b32_sdwa v17, v19, v17 dst_sel:DWORD dst_unused:UNUSED_PAD src0_sel:DWORD src1_sel:WORD_1
	v_or_b32_sdwa v16, v18, v16 dst_sel:DWORD dst_unused:UNUSED_PAD src0_sel:DWORD src1_sel:WORD_1
	global_store_dwordx2 v[36:37], v[16:17], off offset:48
	v_mov_b32_e32 v16, v0
	v_mov_b32_e32 v17, v2
	v_pk_mul_f32 v[16:17], v[16:17], v[32:33] op_sel_hi:[1,0]
	v_mov_b32_e32 v2, v1
	v_pk_mul_f32 v[0:1], v[2:3], v[32:33] op_sel_hi:[1,0]
	v_and_b32_sdwa v2, v17, v159 dst_sel:DWORD dst_unused:UNUSED_PAD src0_sel:WORD_1 src1_sel:DWORD
	v_and_b32_sdwa v3, v16, v159 dst_sel:DWORD dst_unused:UNUSED_PAD src0_sel:WORD_1 src1_sel:DWORD
	v_add3_u32 v3, v16, v3, s59
	v_add3_u32 v2, v17, v2, s59
	v_and_b32_sdwa v16, v1, v159 dst_sel:DWORD dst_unused:UNUSED_PAD src0_sel:WORD_1 src1_sel:DWORD
	v_and_b32_sdwa v17, v0, v159 dst_sel:DWORD dst_unused:UNUSED_PAD src0_sel:WORD_1 src1_sel:DWORD
	v_add3_u32 v1, v1, v16, s59
	v_add3_u32 v0, v0, v17, s59
	v_and_b32_e32 v1, 0xffff0000, v1
	v_and_b32_e32 v0, 0xffff0000, v0
	v_or_b32_sdwa v1, v1, v2 dst_sel:DWORD dst_unused:UNUSED_PAD src0_sel:DWORD src1_sel:WORD_1
	v_or_b32_sdwa v0, v0, v3 dst_sel:DWORD dst_unused:UNUSED_PAD src0_sel:DWORD src1_sel:WORD_1
	global_store_dwordx2 v[36:37], v[0:1], off offset:64
	v_mov_b32_e32 v0, v4
	v_mov_b32_e32 v1, v6
	v_pk_mul_f32 v[0:1], v[0:1], v[32:33] op_sel_hi:[1,0]
	v_mov_b32_e32 v6, v5
	v_pk_mul_f32 v[2:3], v[6:7], v[32:33] op_sel_hi:[1,0]
	v_and_b32_sdwa v4, v1, v159 dst_sel:DWORD dst_unused:UNUSED_PAD src0_sel:WORD_1 src1_sel:DWORD
	v_and_b32_sdwa v5, v0, v159 dst_sel:DWORD dst_unused:UNUSED_PAD src0_sel:WORD_1 src1_sel:DWORD
	v_add3_u32 v0, v0, v5, s59
	v_add3_u32 v1, v1, v4, s59
	v_and_b32_sdwa v4, v3, v159 dst_sel:DWORD dst_unused:UNUSED_PAD src0_sel:WORD_1 src1_sel:DWORD
	v_and_b32_sdwa v5, v2, v159 dst_sel:DWORD dst_unused:UNUSED_PAD src0_sel:WORD_1 src1_sel:DWORD
	v_add3_u32 v3, v3, v4, s59
	v_add3_u32 v2, v2, v5, s59
	v_and_b32_e32 v3, 0xffff0000, v3
	v_and_b32_e32 v2, 0xffff0000, v2
	v_or_b32_sdwa v1, v3, v1 dst_sel:DWORD dst_unused:UNUSED_PAD src0_sel:DWORD src1_sel:WORD_1
	v_or_b32_sdwa v0, v2, v0 dst_sel:DWORD dst_unused:UNUSED_PAD src0_sel:DWORD src1_sel:WORD_1
	global_store_dwordx2 v[36:37], v[0:1], off offset:80
	v_mov_b32_e32 v0, v8
	v_mov_b32_e32 v1, v10
	v_pk_mul_f32 v[0:1], v[0:1], v[32:33] op_sel_hi:[1,0]
	v_mov_b32_e32 v10, v9
	v_pk_mul_f32 v[2:3], v[10:11], v[32:33] op_sel_hi:[1,0]
	v_and_b32_sdwa v4, v1, v159 dst_sel:DWORD dst_unused:UNUSED_PAD src0_sel:WORD_1 src1_sel:DWORD
	v_and_b32_sdwa v5, v0, v159 dst_sel:DWORD dst_unused:UNUSED_PAD src0_sel:WORD_1 src1_sel:DWORD
	v_add3_u32 v0, v0, v5, s59
	v_add3_u32 v1, v1, v4, s59
	v_and_b32_sdwa v4, v3, v159 dst_sel:DWORD dst_unused:UNUSED_PAD src0_sel:WORD_1 src1_sel:DWORD
	v_and_b32_sdwa v5, v2, v159 dst_sel:DWORD dst_unused:UNUSED_PAD src0_sel:WORD_1 src1_sel:DWORD
	v_add3_u32 v3, v3, v4, s59
	v_add3_u32 v2, v2, v5, s59
	v_and_b32_e32 v3, 0xffff0000, v3
	v_and_b32_e32 v2, 0xffff0000, v2
	v_or_b32_sdwa v1, v3, v1 dst_sel:DWORD dst_unused:UNUSED_PAD src0_sel:DWORD src1_sel:WORD_1
	v_or_b32_sdwa v0, v2, v0 dst_sel:DWORD dst_unused:UNUSED_PAD src0_sel:DWORD src1_sel:WORD_1
	global_store_dwordx2 v[36:37], v[0:1], off offset:96
	v_mov_b32_e32 v0, v12
	v_mov_b32_e32 v1, v14
	v_pk_mul_f32 v[0:1], v[0:1], v[32:33] op_sel_hi:[1,0]
	v_mov_b32_e32 v14, v13
	v_pk_mul_f32 v[2:3], v[14:15], v[32:33] op_sel_hi:[1,0]
	v_and_b32_sdwa v4, v1, v159 dst_sel:DWORD dst_unused:UNUSED_PAD src0_sel:WORD_1 src1_sel:DWORD
	v_and_b32_sdwa v5, v0, v159 dst_sel:DWORD dst_unused:UNUSED_PAD src0_sel:WORD_1 src1_sel:DWORD
	v_add3_u32 v0, v0, v5, s59
	v_add3_u32 v1, v1, v4, s59
	v_and_b32_sdwa v4, v3, v159 dst_sel:DWORD dst_unused:UNUSED_PAD src0_sel:WORD_1 src1_sel:DWORD
	v_and_b32_sdwa v5, v2, v159 dst_sel:DWORD dst_unused:UNUSED_PAD src0_sel:WORD_1 src1_sel:DWORD
	v_add3_u32 v3, v3, v4, s59
	v_add3_u32 v2, v2, v5, s59
	v_and_b32_e32 v3, 0xffff0000, v3
	v_and_b32_e32 v2, 0xffff0000, v2
	v_or_b32_sdwa v1, v3, v1 dst_sel:DWORD dst_unused:UNUSED_PAD src0_sel:DWORD src1_sel:WORD_1
	v_or_b32_sdwa v0, v2, v0 dst_sel:DWORD dst_unused:UNUSED_PAD src0_sel:DWORD src1_sel:WORD_1
	global_store_dwordx2 v[36:37], v[0:1], off offset:112
	s_branch .LBB0_579

.LBB0_997:
	ds_read_b128 v[216:219], v188 offset:36864
	ds_read_b128 v[200:203], v187
	ds_read_b128 v[220:223], v188 offset:41472
	ds_read_b128 v[204:207], v187 offset:4608
	ds_read_b128 v[208:211], v187 offset:9216
	ds_read_b128 v[212:215], v176
	s_waitcnt lgkmcnt(4)
	v_mfma_f32_32x32x16_bf16 v[112:127], v[200:203], v[216:219], v[112:127]
	ds_read_b128 v[240:243], v188 offset:36896
	global_load_dwordx4 v[160:163], v190, s[38:39]
	s_waitcnt lgkmcnt(4)
	v_mfma_f32_32x32x16_bf16 v[96:111], v[200:203], v[220:223], v[96:111]
	ds_read_b128 v[224:227], v187 offset:32
	global_load_dwordx4 v[128:131], v191, s[38:39]
	s_waitcnt lgkmcnt(4)
	v_mfma_f32_32x32x16_bf16 v[80:95], v[204:207], v[216:219], v[80:95]
	ds_read_b128 v[244:247], v188 offset:41504
	global_load_dwordx4 v[132:135], v192, s[38:39]
	s_waitcnt lgkmcnt(5)
	v_mfma_f32_32x32x16_bf16 v[64:79], v[204:207], v[220:223], v[64:79]
	ds_read_b128 v[228:231], v187 offset:4640
	global_load_dwordx4 v[136:139], v193, s[38:39]
	s_waitcnt lgkmcnt(5)
	v_mfma_f32_32x32x16_bf16 v[48:63], v[208:211], v[216:219], v[48:63]
	ds_read_b128 v[232:235], v187 offset:9248
	global_load_dwordx4 v[140:143], v194, s[38:39]
	s_waitcnt lgkmcnt(6)
	v_mfma_f32_32x32x16_bf16 v[32:47], v[208:211], v[220:223], v[32:47]
	ds_read_b128 v[236:239], v176 offset:32
	global_load_dwordx4 v[144:147], v195, s[38:39]
	s_waitcnt lgkmcnt(6)
	v_mfma_f32_32x32x16_bf16 v[16:31], v[212:215], v[216:219], v[16:31]
	global_load_dwordx4 v[148:151], v196, s[38:39]
	global_load_dwordx4 v[156:159], v197, s[38:39]
	s_waitcnt lgkmcnt(6)
	v_mfma_f32_32x32x16_bf16 v[0:15], v[212:215], v[220:223], v[0:15]
	global_load_dwordx4 v[152:155], v190, s[40:41]
	global_load_dwordx4 v[164:167], v191, s[40:41]
	s_waitcnt lgkmcnt(4)
	v_mfma_f32_32x32x16_bf16 v[112:127], v[224:227], v[240:243], v[112:127]
	ds_read_b128 v[200:203], v187 offset:64
	global_load_dwordx4 v[168:171], v192, s[40:41]
	s_waitcnt lgkmcnt(4)
	v_mfma_f32_32x32x16_bf16 v[96:111], v[224:227], v[244:247], v[96:111]
	ds_read_b128 v[204:207], v187 offset:4672
	global_load_dwordx4 v[172:175], v193, s[40:41]
	s_add_u32 s38, s38, 0x80
	s_addc_u32 s39, s39, 0
	s_add_u32 s40, s40, 0x80
	s_addc_u32 s41, s41, 0
	s_add_u32 s12, s12, 0x80
	s_waitcnt lgkmcnt(4)
	v_mfma_f32_32x32x16_bf16 v[80:95], v[228:231], v[240:243], v[80:95]
	ds_read_b128 v[208:211], v187 offset:9280
	s_waitcnt lgkmcnt(5)
	v_mfma_f32_32x32x16_bf16 v[64:79], v[228:231], v[244:247], v[64:79]
	ds_read_b128 v[212:215], v176 offset:64
	s_waitcnt lgkmcnt(5)
	v_mfma_f32_32x32x16_bf16 v[48:63], v[232:235], v[240:243], v[48:63]
	ds_read_b128 v[216:219], v188 offset:36928
	s_waitcnt lgkmcnt(6)
	v_mfma_f32_32x32x16_bf16 v[32:47], v[232:235], v[244:247], v[32:47]
	ds_read_b128 v[220:223], v188 offset:41536
	s_waitcnt lgkmcnt(6)
	v_mfma_f32_32x32x16_bf16 v[16:31], v[236:239], v[240:243], v[16:31]
	s_waitcnt lgkmcnt(6)
	v_mfma_f32_32x32x16_bf16 v[0:15], v[236:239], v[244:247], v[0:15]
	s_waitcnt lgkmcnt(1)
	v_mfma_f32_32x32x16_bf16 v[112:127], v[200:203], v[216:219], v[112:127]
	ds_read_b128 v[224:227], v187 offset:96
	s_waitcnt lgkmcnt(1)
	v_mfma_f32_32x32x16_bf16 v[96:111], v[200:203], v[220:223], v[96:111]
	ds_read_b128 v[228:231], v187 offset:4704
	s_waitcnt lgkmcnt(3)
	v_mfma_f32_32x32x16_bf16 v[80:95], v[204:207], v[216:219], v[80:95]
	ds_read_b128 v[232:235], v187 offset:9312
	s_waitcnt lgkmcnt(3)
	v_mfma_f32_32x32x16_bf16 v[64:79], v[204:207], v[220:223], v[64:79]
	ds_read_b128 v[236:239], v176 offset:96
	s_waitcnt lgkmcnt(5)
	v_mfma_f32_32x32x16_bf16 v[48:63], v[208:211], v[216:219], v[48:63]
	ds_read_b128 v[240:243], v188 offset:36960
	s_waitcnt lgkmcnt(5)
	v_mfma_f32_32x32x16_bf16 v[32:47], v[208:211], v[220:223], v[32:47]
	ds_read_b128 v[244:247], v188 offset:41568
	s_waitcnt lgkmcnt(7)
	v_mfma_f32_32x32x16_bf16 v[16:31], v[212:215], v[216:219], v[16:31]
	s_waitcnt lgkmcnt(6)
	v_mfma_f32_32x32x16_bf16 v[0:15], v[212:215], v[220:223], v[0:15]
	s_waitcnt lgkmcnt(0)
	s_barrier
	s_waitcnt vmcnt(0)
	s_waitcnt lgkmcnt(1)
	v_mfma_f32_32x32x16_bf16 v[112:127], v[224:227], v[240:243], v[112:127]
	ds_write_b128 v189, v[160:163]
	ds_write_b128 v189, v[128:131] offset:4608
	s_waitcnt lgkmcnt(2)
	v_mfma_f32_32x32x16_bf16 v[96:111], v[224:227], v[244:247], v[96:111]
	ds_write_b128 v189, v[132:135] offset:9216
	s_waitcnt lgkmcnt(4)
	v_mfma_f32_32x32x16_bf16 v[80:95], v[228:231], v[240:243], v[80:95]
	ds_write_b128 v189, v[136:139] offset:13824
	ds_write_b128 v189, v[140:143] offset:18432
	s_waitcnt lgkmcnt(5)
	v_mfma_f32_32x32x16_bf16 v[64:79], v[228:231], v[244:247], v[64:79]
	ds_write_b128 v189, v[144:147] offset:23040
	s_waitcnt lgkmcnt(7)
	v_mfma_f32_32x32x16_bf16 v[48:63], v[232:235], v[240:243], v[48:63]
	ds_write_b128 v189, v[148:151] offset:27648
	ds_write_b128 v189, v[156:159] offset:32256
	s_waitcnt lgkmcnt(8)
	v_mfma_f32_32x32x16_bf16 v[32:47], v[232:235], v[244:247], v[32:47]
	ds_write_b128 v189, v[152:155] offset:36864
	s_waitcnt lgkmcnt(10)
	v_mfma_f32_32x32x16_bf16 v[16:31], v[236:239], v[240:243], v[16:31]
	ds_write_b128 v189, v[164:167] offset:41472
	ds_write_b128 v189, v[168:171] offset:46080
	s_waitcnt lgkmcnt(11)
	v_mfma_f32_32x32x16_bf16 v[0:15], v[236:239], v[244:247], v[0:15]
	ds_write_b128 v189, v[172:175] offset:50688
	s_waitcnt lgkmcnt(0)
	s_barrier
	s_cmpk_lg_i32 s12, 0x780
	s_cbranch_scc1 .LBB0_997
	ds_read_b128 v[128:131], v187
	ds_read_b128 v[132:135], v188 offset:36864
	ds_read_b128 v[136:139], v187 offset:32
	ds_read_b128 v[140:143], v188 offset:36896
	ds_read_b128 v[144:147], v188 offset:41472
	ds_read_b128 v[148:151], v188 offset:41504
	s_waitcnt lgkmcnt(4)
	v_mfma_f32_32x32x16_bf16 v[112:127], v[128:131], v[132:135], v[112:127]
	v_cmp_gt_u32_e32 vcc, s50, v182
	s_waitcnt lgkmcnt(1)
	v_mfma_f32_32x32x16_bf16 v[96:111], v[128:131], v[144:147], v[96:111]
	ds_read_b128 v[128:131], v187 offset:4608
	ds_read_b128 v[152:155], v187 offset:4640
	s_waitcnt lgkmcnt(1)
	v_mfma_f32_32x32x16_bf16 v[80:95], v[128:131], v[132:135], v[80:95]
	v_mfma_f32_32x32x16_bf16 v[64:79], v[128:131], v[144:147], v[64:79]
	ds_read_b128 v[128:131], v187 offset:9216
	ds_read_b128 v[156:159], v187 offset:9248
	s_waitcnt lgkmcnt(1)
	v_mfma_f32_32x32x16_bf16 v[48:63], v[128:131], v[132:135], v[48:63]
	v_mfma_f32_32x32x16_bf16 v[32:47], v[128:131], v[144:147], v[32:47]
	ds_read_b128 v[128:131], v176
	ds_read_b128 v[160:163], v176 offset:32
	s_waitcnt lgkmcnt(1)
	v_mfma_f32_32x32x16_bf16 v[16:31], v[128:131], v[132:135], v[16:31]
	v_mfma_f32_32x32x16_bf16 v[0:15], v[128:131], v[144:147], v[0:15]
	v_mfma_f32_32x32x16_bf16 v[112:127], v[136:139], v[140:143], v[112:127]
	v_mfma_f32_32x32x16_bf16 v[96:111], v[136:139], v[148:151], v[96:111]
	v_mfma_f32_32x32x16_bf16 v[80:95], v[152:155], v[140:143], v[80:95]
	v_mfma_f32_32x32x16_bf16 v[64:79], v[152:155], v[148:151], v[64:79]
	v_mfma_f32_32x32x16_bf16 v[48:63], v[156:159], v[140:143], v[48:63]
	v_mfma_f32_32x32x16_bf16 v[32:47], v[156:159], v[148:151], v[32:47]
	s_waitcnt lgkmcnt(0)
	v_mfma_f32_32x32x16_bf16 v[16:31], v[160:163], v[140:143], v[16:31]
	v_mfma_f32_32x32x16_bf16 v[0:15], v[160:163], v[148:151], v[0:15]
	ds_read_b128 v[128:131], v187 offset:64
	ds_read_b128 v[144:147], v188 offset:36928
	ds_read_b128 v[148:151], v187 offset:96
	ds_read_b128 v[152:155], v188 offset:36960
	ds_read_b128 v[156:159], v188 offset:41536
	ds_read_b128 v[160:163], v188 offset:41568
	s_waitcnt lgkmcnt(4)
	v_mfma_f32_32x32x16_bf16 v[112:127], v[128:131], v[144:147], v[112:127]
	s_waitcnt lgkmcnt(1)
	v_mfma_f32_32x32x16_bf16 v[96:111], v[128:131], v[156:159], v[96:111]
	ds_read_b128 v[130:133], v187 offset:4672
	ds_read_b128 v[164:167], v187 offset:4704
	ds_read_b128 v[168:171], v187 offset:9280
	ds_read_b128 v[172:175], v187 offset:9312
	ds_read_b128 v[178:181], v176 offset:64
	ds_read_b128 v[188:191], v176 offset:96
	v_lshlrev_b32_e32 v128, 7, v184
	v_lshl_or_b32 v128, v185, 1, v128
	v_mad_u32_u24 v128, v186, s51, v128
	s_waitcnt lgkmcnt(0)
	s_barrier
	v_mfma_f32_32x32x16_bf16 v[80:95], v[130:133], v[144:147], v[80:95]
	v_mfma_f32_32x32x16_bf16 v[64:79], v[130:133], v[156:159], v[64:79]
	v_mfma_f32_32x32x16_bf16 v[48:63], v[168:171], v[144:147], v[48:63]
	v_mfma_f32_32x32x16_bf16 v[32:47], v[168:171], v[156:159], v[32:47]
	v_mfma_f32_32x32x16_bf16 v[16:31], v[178:181], v[144:147], v[16:31]
	v_mfma_f32_32x32x16_bf16 v[0:15], v[178:181], v[156:159], v[0:15]
	v_mfma_f32_32x32x16_bf16 v[112:127], v[148:151], v[152:155], v[112:127]
	v_mfma_f32_32x32x16_bf16 v[96:111], v[148:151], v[160:163], v[96:111]
	s_nop 10
	v_max_f32_e32 v143, v112, v112
	v_max_f32_e32 v142, v113, v113
	v_max_f32_e32 v141, v114, v114
	v_max_f32_e32 v140, v115, v115
	v_max_f32_e32 v139, v116, v116
	v_max_f32_e32 v138, v117, v117
	v_max_f32_e32 v137, v118, v118
	v_mfma_f32_32x32x16_bf16 v[80:95], v[164:167], v[152:155], v[80:95]
	v_max_f32_e32 v136, v119, v119
	v_max_f32_e32 v135, v120, v120
	v_max_f32_e32 v134, v121, v121
	v_max_f32_e32 v133, v122, v122
	v_max_f32_e32 v132, v123, v123
	v_max_f32_e32 v131, v124, v124
	v_max_f32_e32 v130, v125, v125
	v_mfma_f32_32x32x16_bf16 v[64:79], v[164:167], v[160:163], v[64:79]
	v_max_f32_e32 v129, v126, v126
	v_max_f32_e32 v127, v127, v127
	v_max_f32_e32 v126, v96, v96
	v_max_f32_e32 v125, v97, v97
	v_max_f32_e32 v124, v98, v98
	v_max_f32_e32 v123, v99, v99
	v_max_f32_e32 v122, v100, v100
	v_mfma_f32_32x32x16_bf16 v[48:63], v[172:175], v[152:155], v[48:63]
	v_max_f32_e32 v121, v101, v101
	v_max_f32_e32 v120, v102, v102
	v_max_f32_e32 v119, v103, v103
	v_max_f32_e32 v118, v104, v104
	v_max_f32_e32 v117, v105, v105
	v_max_f32_e32 v116, v106, v106
	v_max_f32_e32 v115, v107, v107
	v_mfma_f32_32x32x16_bf16 v[32:47], v[172:175], v[160:163], v[32:47]
	v_max_f32_e32 v114, v108, v108
	v_max_f32_e32 v113, v109, v109
	v_max_f32_e32 v112, v110, v110
	v_max_f32_e32 v110, v111, v111
	v_max_f32_e32 v109, v80, v80
	v_max_f32_e32 v108, v81, v81
	v_max_f32_e32 v107, v82, v82
	v_mfma_f32_32x32x16_bf16 v[16:31], v[188:191], v[152:155], v[16:31]
	v_max_f32_e32 v106, v83, v83
	v_max_f32_e32 v105, v84, v84
	v_max_f32_e32 v104, v85, v85
	v_max_f32_e32 v103, v86, v86
	v_max_f32_e32 v102, v87, v87
	v_max_f32_e32 v101, v88, v88
	v_max_f32_e32 v100, v89, v89
	v_mfma_f32_32x32x16_bf16 v[0:15], v[188:191], v[160:163], v[0:15]
	v_max_f32_e32 v99, v90, v90
	v_max_f32_e32 v98, v91, v91
	v_max_f32_e32 v97, v92, v92
	v_max_f32_e32 v96, v93, v93
	v_max_f32_e32 v93, v94, v94
	v_max_f32_e32 v92, v95, v95
	v_max_f32_e32 v91, v64, v64
	v_max_f32_e32 v90, v65, v65
	v_max_f32_e32 v89, v66, v66
	v_max_f32_e32 v88, v67, v67
	v_max_f32_e32 v87, v68, v68
	v_max_f32_e32 v86, v69, v69
	v_max_f32_e32 v85, v70, v70
	v_max_f32_e32 v84, v71, v71
	v_max_f32_e32 v83, v72, v72
	v_max_f32_e32 v82, v73, v73
	v_max_f32_e32 v81, v74, v74
	v_max_f32_e32 v80, v75, v75
	v_max_f32_e32 v76, v76, v76
	v_max_f32_e32 v75, v77, v77
	v_max_f32_e32 v74, v78, v78
	v_max_f32_e32 v73, v79, v79
	v_max_f32_e32 v72, v48, v48
	v_max_f32_e32 v71, v49, v49
	v_max_f32_e32 v70, v50, v50
	v_max_f32_e32 v69, v51, v51
	v_max_f32_e32 v68, v52, v52
	v_max_f32_e32 v67, v53, v53
	v_max_f32_e32 v66, v54, v54
	v_max_f32_e32 v65, v55, v55
	v_max_f32_e32 v64, v56, v56
	v_max_f32_e32 v57, v57, v57
	v_max_f32_e32 v56, v58, v58
	v_max_f32_e32 v55, v59, v59
	v_max_f32_e32 v54, v60, v60
	v_max_f32_e32 v53, v61, v61
	v_max_f32_e32 v52, v62, v62
	v_max_f32_e32 v51, v63, v63
	v_max_f32_e32 v50, v32, v32
	v_max_f32_e32 v49, v33, v33
	v_max_f32_e32 v48, v34, v34
	v_max_f32_e32 v34, v35, v35
	s_and_saveexec_b64 s[12:13], vcc
	s_cbranch_execz .LBB0_1000
	v_max_f32_e32 v32, 0, v143
	v_mul_f32_e32 v32, v32, v32
	v_bfe_u32 v33, v32, 16, 1
	v_add3_u32 v32, v32, v33, s52
	ds_write_b16_d16_hi v128, v32
	v_max_f32_e32 v32, 0, v142
	v_mul_f32_e32 v32, v32, v32
	v_bfe_u32 v33, v32, 16, 1
	v_add3_u32 v32, v32, v33, s52
	ds_write_b16_d16_hi v128, v32 offset:272
	v_max_f32_e32 v32, 0, v141
	v_mul_f32_e32 v32, v32, v32
	v_bfe_u32 v33, v32, 16, 1
	v_add3_u32 v32, v32, v33, s52
	ds_write_b16_d16_hi v128, v32 offset:544
	v_max_f32_e32 v32, 0, v140
	v_mul_f32_e32 v32, v32, v32
	v_bfe_u32 v33, v32, 16, 1
	v_add3_u32 v32, v32, v33, s52
	ds_write_b16_d16_hi v128, v32 offset:816
	v_max_f32_e32 v32, 0, v139
	v_mul_f32_e32 v32, v32, v32
	v_bfe_u32 v33, v32, 16, 1
	v_add3_u32 v32, v32, v33, s52
	ds_write_b16_d16_hi v128, v32 offset:2176
	v_max_f32_e32 v32, 0, v138
	v_mul_f32_e32 v32, v32, v32
	v_bfe_u32 v33, v32, 16, 1
	v_add3_u32 v32, v32, v33, s52
	ds_write_b16_d16_hi v128, v32 offset:2448
	v_max_f32_e32 v32, 0, v137
	v_mul_f32_e32 v32, v32, v32
	v_bfe_u32 v33, v32, 16, 1
	v_add3_u32 v32, v32, v33, s52
	ds_write_b16_d16_hi v128, v32 offset:2720
	v_max_f32_e32 v32, 0, v136
	v_mul_f32_e32 v32, v32, v32
	v_bfe_u32 v33, v32, 16, 1
	v_add3_u32 v32, v32, v33, s52
	ds_write_b16_d16_hi v128, v32 offset:2992
	v_max_f32_e32 v32, 0, v135
	v_mul_f32_e32 v32, v32, v32
	v_bfe_u32 v33, v32, 16, 1
	v_add3_u32 v32, v32, v33, s52
	ds_write_b16_d16_hi v128, v32 offset:4352
	v_max_f32_e32 v32, 0, v134
	v_mul_f32_e32 v32, v32, v32
	v_bfe_u32 v33, v32, 16, 1
	v_add3_u32 v32, v32, v33, s52
	ds_write_b16_d16_hi v128, v32 offset:4624
	v_max_f32_e32 v32, 0, v133
	v_mul_f32_e32 v32, v32, v32
	v_bfe_u32 v33, v32, 16, 1
	v_add3_u32 v32, v32, v33, s52
	ds_write_b16_d16_hi v128, v32 offset:4896
	v_max_f32_e32 v32, 0, v132
	v_mul_f32_e32 v32, v32, v32
	v_bfe_u32 v33, v32, 16, 1
	v_add3_u32 v32, v32, v33, s52
	ds_write_b16_d16_hi v128, v32 offset:5168
	v_max_f32_e32 v32, 0, v131
	v_mul_f32_e32 v32, v32, v32
	v_bfe_u32 v33, v32, 16, 1
	v_add3_u32 v32, v32, v33, s52
	ds_write_b16_d16_hi v128, v32 offset:6528
	v_max_f32_e32 v32, 0, v130
	v_mul_f32_e32 v32, v32, v32
	v_bfe_u32 v33, v32, 16, 1
	v_add3_u32 v32, v32, v33, s52
	ds_write_b16_d16_hi v128, v32 offset:6800
	v_max_f32_e32 v32, 0, v129
	v_mul_f32_e32 v32, v32, v32
	v_bfe_u32 v33, v32, 16, 1
	v_add3_u32 v32, v32, v33, s52
	ds_write_b16_d16_hi v128, v32 offset:7072
	v_max_f32_e32 v32, 0, v127
	v_mul_f32_e32 v32, v32, v32
	v_bfe_u32 v33, v32, 16, 1
	v_add3_u32 v32, v32, v33, s52
	ds_write_b16_d16_hi v128, v32 offset:7344
	v_max_f32_e32 v32, 0, v126
	v_mul_f32_e32 v32, v32, v32
	v_bfe_u32 v33, v32, 16, 1
	v_add3_u32 v32, v32, v33, s52
	ds_write_b16_d16_hi v128, v32 offset:64
	v_max_f32_e32 v32, 0, v125
	v_mul_f32_e32 v32, v32, v32
	v_bfe_u32 v33, v32, 16, 1
	v_add3_u32 v32, v32, v33, s52
	ds_write_b16_d16_hi v128, v32 offset:336
	v_max_f32_e32 v32, 0, v124
	v_mul_f32_e32 v32, v32, v32
	v_bfe_u32 v33, v32, 16, 1
	v_add3_u32 v32, v32, v33, s52
	ds_write_b16_d16_hi v128, v32 offset:608
	v_max_f32_e32 v32, 0, v123
	v_mul_f32_e32 v32, v32, v32
	v_bfe_u32 v33, v32, 16, 1
	v_add3_u32 v32, v32, v33, s52
	ds_write_b16_d16_hi v128, v32 offset:880
	v_max_f32_e32 v32, 0, v122
	v_mul_f32_e32 v32, v32, v32
	v_bfe_u32 v33, v32, 16, 1
	v_add3_u32 v32, v32, v33, s52
	ds_write_b16_d16_hi v128, v32 offset:2240
	v_max_f32_e32 v32, 0, v121
	v_mul_f32_e32 v32, v32, v32
	v_bfe_u32 v33, v32, 16, 1
	v_add3_u32 v32, v32, v33, s52
	ds_write_b16_d16_hi v128, v32 offset:2512
	v_max_f32_e32 v32, 0, v120
	v_mul_f32_e32 v32, v32, v32
	v_bfe_u32 v33, v32, 16, 1
	v_add3_u32 v32, v32, v33, s52
	ds_write_b16_d16_hi v128, v32 offset:2784
	v_max_f32_e32 v32, 0, v119
	v_mul_f32_e32 v32, v32, v32
	v_bfe_u32 v33, v32, 16, 1
	v_add3_u32 v32, v32, v33, s52
	ds_write_b16_d16_hi v128, v32 offset:3056
	v_max_f32_e32 v32, 0, v118
	v_mul_f32_e32 v32, v32, v32
	v_bfe_u32 v33, v32, 16, 1
	v_add3_u32 v32, v32, v33, s52
	ds_write_b16_d16_hi v128, v32 offset:4416
	v_max_f32_e32 v32, 0, v117
	v_mul_f32_e32 v32, v32, v32
	v_bfe_u32 v33, v32, 16, 1
	v_add3_u32 v32, v32, v33, s52
	ds_write_b16_d16_hi v128, v32 offset:4688
	v_max_f32_e32 v32, 0, v116
	v_mul_f32_e32 v32, v32, v32
	v_bfe_u32 v33, v32, 16, 1
	v_add3_u32 v32, v32, v33, s52
	ds_write_b16_d16_hi v128, v32 offset:4960
	v_max_f32_e32 v32, 0, v115
	v_mul_f32_e32 v32, v32, v32
	v_bfe_u32 v33, v32, 16, 1
	v_add3_u32 v32, v32, v33, s52
	ds_write_b16_d16_hi v128, v32 offset:5232
	v_max_f32_e32 v32, 0, v114
	v_mul_f32_e32 v32, v32, v32
	v_bfe_u32 v33, v32, 16, 1
	v_add3_u32 v32, v32, v33, s52
	ds_write_b16_d16_hi v128, v32 offset:6592
	v_max_f32_e32 v32, 0, v113
	v_mul_f32_e32 v32, v32, v32
	v_bfe_u32 v33, v32, 16, 1
	v_add3_u32 v32, v32, v33, s52
	ds_write_b16_d16_hi v128, v32 offset:6864
	v_max_f32_e32 v32, 0, v112
	v_mul_f32_e32 v32, v32, v32
	v_bfe_u32 v33, v32, 16, 1
	v_add3_u32 v32, v32, v33, s52
	ds_write_b16_d16_hi v128, v32 offset:7136
	v_max_f32_e32 v32, 0, v110
	v_mul_f32_e32 v32, v32, v32
	v_bfe_u32 v33, v32, 16, 1
	v_add3_u32 v32, v32, v33, s52
	ds_write_b16_d16_hi v128, v32 offset:7408
	v_max_f32_e32 v32, 0, v109
	v_mul_f32_e32 v32, v32, v32
	v_bfe_u32 v33, v32, 16, 1
	v_add3_u32 v32, v32, v33, s52
	ds_write_b16_d16_hi v128, v32 offset:8704
	v_max_f32_e32 v32, 0, v108
	v_mul_f32_e32 v32, v32, v32
	v_bfe_u32 v33, v32, 16, 1
	v_add3_u32 v32, v32, v33, s52
	ds_write_b16_d16_hi v128, v32 offset:8976
	v_max_f32_e32 v32, 0, v107
	v_mul_f32_e32 v32, v32, v32
	v_bfe_u32 v33, v32, 16, 1
	v_add3_u32 v32, v32, v33, s52
	ds_write_b16_d16_hi v128, v32 offset:9248
	v_max_f32_e32 v32, 0, v106
	v_mul_f32_e32 v32, v32, v32
	v_bfe_u32 v33, v32, 16, 1
	v_add3_u32 v32, v32, v33, s52
	ds_write_b16_d16_hi v128, v32 offset:9520
	v_max_f32_e32 v32, 0, v105
	v_mul_f32_e32 v32, v32, v32
	v_bfe_u32 v33, v32, 16, 1
	v_add3_u32 v32, v32, v33, s52
	ds_write_b16_d16_hi v128, v32 offset:10880
	v_max_f32_e32 v32, 0, v104
	v_mul_f32_e32 v32, v32, v32
	v_bfe_u32 v33, v32, 16, 1
	v_add3_u32 v32, v32, v33, s52
	ds_write_b16_d16_hi v128, v32 offset:11152
	v_max_f32_e32 v32, 0, v103
	v_mul_f32_e32 v32, v32, v32
	v_bfe_u32 v33, v32, 16, 1
	v_add3_u32 v32, v32, v33, s52
	ds_write_b16_d16_hi v128, v32 offset:11424
	v_max_f32_e32 v32, 0, v102
	v_mul_f32_e32 v32, v32, v32
	v_bfe_u32 v33, v32, 16, 1
	v_add3_u32 v32, v32, v33, s52
	ds_write_b16_d16_hi v128, v32 offset:11696
	v_max_f32_e32 v32, 0, v101
	v_mul_f32_e32 v32, v32, v32
	v_bfe_u32 v33, v32, 16, 1
	v_add3_u32 v32, v32, v33, s52
	ds_write_b16_d16_hi v128, v32 offset:13056
	v_max_f32_e32 v32, 0, v100
	v_mul_f32_e32 v32, v32, v32
	v_bfe_u32 v33, v32, 16, 1
	v_add3_u32 v32, v32, v33, s52
	ds_write_b16_d16_hi v128, v32 offset:13328
	v_max_f32_e32 v32, 0, v99
	v_mul_f32_e32 v32, v32, v32
	v_bfe_u32 v33, v32, 16, 1
	v_add3_u32 v32, v32, v33, s52
	ds_write_b16_d16_hi v128, v32 offset:13600
	v_max_f32_e32 v32, 0, v98
	v_mul_f32_e32 v32, v32, v32
	v_bfe_u32 v33, v32, 16, 1
	v_add3_u32 v32, v32, v33, s52
	ds_write_b16_d16_hi v128, v32 offset:13872
	v_max_f32_e32 v32, 0, v97
	v_mul_f32_e32 v32, v32, v32
	v_bfe_u32 v33, v32, 16, 1
	v_add3_u32 v32, v32, v33, s52
	ds_write_b16_d16_hi v128, v32 offset:15232
	v_max_f32_e32 v32, 0, v96
	v_mul_f32_e32 v32, v32, v32
	v_bfe_u32 v33, v32, 16, 1
	v_add3_u32 v32, v32, v33, s52
	ds_write_b16_d16_hi v128, v32 offset:15504
	v_max_f32_e32 v32, 0, v93
	v_mul_f32_e32 v32, v32, v32
	v_bfe_u32 v33, v32, 16, 1
	v_add3_u32 v32, v32, v33, s52
	ds_write_b16_d16_hi v128, v32 offset:15776
	v_max_f32_e32 v32, 0, v92
	v_mul_f32_e32 v32, v32, v32
	v_bfe_u32 v33, v32, 16, 1
	v_add3_u32 v32, v32, v33, s52
	ds_write_b16_d16_hi v128, v32 offset:16048
	v_max_f32_e32 v32, 0, v91
	v_mul_f32_e32 v32, v32, v32
	v_bfe_u32 v33, v32, 16, 1
	v_add3_u32 v32, v32, v33, s52
	ds_write_b16_d16_hi v128, v32 offset:8768
	v_max_f32_e32 v32, 0, v90
	v_mul_f32_e32 v32, v32, v32
	v_bfe_u32 v33, v32, 16, 1
	v_add3_u32 v32, v32, v33, s52
	ds_write_b16_d16_hi v128, v32 offset:9040
	v_max_f32_e32 v32, 0, v89
	v_mul_f32_e32 v32, v32, v32
	v_bfe_u32 v33, v32, 16, 1
	v_add3_u32 v32, v32, v33, s52
	ds_write_b16_d16_hi v128, v32 offset:9312
	v_max_f32_e32 v32, 0, v88
	v_mul_f32_e32 v32, v32, v32
	v_bfe_u32 v33, v32, 16, 1
	v_add3_u32 v32, v32, v33, s52
	ds_write_b16_d16_hi v128, v32 offset:9584
	v_max_f32_e32 v32, 0, v87
	v_mul_f32_e32 v32, v32, v32
	v_bfe_u32 v33, v32, 16, 1
	v_add3_u32 v32, v32, v33, s52
	ds_write_b16_d16_hi v128, v32 offset:10944
	v_max_f32_e32 v32, 0, v86
	v_mul_f32_e32 v32, v32, v32
	v_bfe_u32 v33, v32, 16, 1
	v_add3_u32 v32, v32, v33, s52
	ds_write_b16_d16_hi v128, v32 offset:11216
	v_max_f32_e32 v32, 0, v85
	v_mul_f32_e32 v32, v32, v32
	v_bfe_u32 v33, v32, 16, 1
	v_add3_u32 v32, v32, v33, s52
	ds_write_b16_d16_hi v128, v32 offset:11488
	v_max_f32_e32 v32, 0, v84
	v_mul_f32_e32 v32, v32, v32
	v_bfe_u32 v33, v32, 16, 1
	v_add3_u32 v32, v32, v33, s52
	ds_write_b16_d16_hi v128, v32 offset:11760
	v_max_f32_e32 v32, 0, v83
	v_mul_f32_e32 v32, v32, v32
	v_bfe_u32 v33, v32, 16, 1
	v_add3_u32 v32, v32, v33, s52
	ds_write_b16_d16_hi v128, v32 offset:13120
	v_max_f32_e32 v32, 0, v82
	v_mul_f32_e32 v32, v32, v32
	v_bfe_u32 v33, v32, 16, 1
	v_add3_u32 v32, v32, v33, s52
	ds_write_b16_d16_hi v128, v32 offset:13392
	v_max_f32_e32 v32, 0, v81
	v_mul_f32_e32 v32, v32, v32
	v_bfe_u32 v33, v32, 16, 1
	v_add3_u32 v32, v32, v33, s52
	ds_write_b16_d16_hi v128, v32 offset:13664
	v_max_f32_e32 v32, 0, v80
	v_mul_f32_e32 v32, v32, v32
	v_bfe_u32 v33, v32, 16, 1
	v_add3_u32 v32, v32, v33, s52
	ds_write_b16_d16_hi v128, v32 offset:13936
	v_max_f32_e32 v32, 0, v76
	v_mul_f32_e32 v32, v32, v32
	v_bfe_u32 v33, v32, 16, 1
	v_add3_u32 v32, v32, v33, s52
	ds_write_b16_d16_hi v128, v32 offset:15296
	v_max_f32_e32 v32, 0, v75
	v_mul_f32_e32 v32, v32, v32
	v_bfe_u32 v33, v32, 16, 1
	v_add3_u32 v32, v32, v33, s52
	ds_write_b16_d16_hi v128, v32 offset:15568
	v_max_f32_e32 v32, 0, v74
	v_mul_f32_e32 v32, v32, v32
	v_bfe_u32 v33, v32, 16, 1
	v_add3_u32 v32, v32, v33, s52
	ds_write_b16_d16_hi v128, v32 offset:15840
	v_max_f32_e32 v32, 0, v73
	v_mul_f32_e32 v32, v32, v32
	v_bfe_u32 v33, v32, 16, 1
	v_add3_u32 v32, v32, v33, s52
	ds_write_b16_d16_hi v128, v32 offset:16112
	v_max_f32_e32 v32, 0, v72
	v_mul_f32_e32 v32, v32, v32
	v_bfe_u32 v33, v32, 16, 1
	v_add3_u32 v32, v32, v33, s52
	ds_write_b16_d16_hi v128, v32 offset:17408
	v_max_f32_e32 v32, 0, v71
	v_mul_f32_e32 v32, v32, v32
	v_bfe_u32 v33, v32, 16, 1
	v_add3_u32 v32, v32, v33, s52
	ds_write_b16_d16_hi v128, v32 offset:17680
	v_max_f32_e32 v32, 0, v70
	v_mul_f32_e32 v32, v32, v32
	v_bfe_u32 v33, v32, 16, 1
	v_add3_u32 v32, v32, v33, s52
	ds_write_b16_d16_hi v128, v32 offset:17952
	v_max_f32_e32 v32, 0, v69
	v_mul_f32_e32 v32, v32, v32
	v_bfe_u32 v33, v32, 16, 1
	v_add3_u32 v32, v32, v33, s52
	ds_write_b16_d16_hi v128, v32 offset:18224
	v_max_f32_e32 v32, 0, v68
	v_mul_f32_e32 v32, v32, v32
	v_bfe_u32 v33, v32, 16, 1
	v_add3_u32 v32, v32, v33, s52
	ds_write_b16_d16_hi v128, v32 offset:19584
	v_max_f32_e32 v32, 0, v67
	v_mul_f32_e32 v32, v32, v32
	v_bfe_u32 v33, v32, 16, 1
	v_add3_u32 v32, v32, v33, s52
	ds_write_b16_d16_hi v128, v32 offset:19856
	v_max_f32_e32 v32, 0, v66
	v_mul_f32_e32 v32, v32, v32
	v_bfe_u32 v33, v32, 16, 1
	v_add3_u32 v32, v32, v33, s52
	ds_write_b16_d16_hi v128, v32 offset:20128
	v_max_f32_e32 v32, 0, v65
	v_mul_f32_e32 v32, v32, v32
	v_bfe_u32 v33, v32, 16, 1
	v_add3_u32 v32, v32, v33, s52
	ds_write_b16_d16_hi v128, v32 offset:20400
	v_max_f32_e32 v32, 0, v64
	v_mul_f32_e32 v32, v32, v32
	v_bfe_u32 v33, v32, 16, 1
	v_add3_u32 v32, v32, v33, s52
	ds_write_b16_d16_hi v128, v32 offset:21760
	v_max_f32_e32 v32, 0, v57
	v_mul_f32_e32 v32, v32, v32
	v_bfe_u32 v33, v32, 16, 1
	v_add3_u32 v32, v32, v33, s52
	ds_write_b16_d16_hi v128, v32 offset:22032
	v_max_f32_e32 v32, 0, v56
	v_mul_f32_e32 v32, v32, v32
	v_bfe_u32 v33, v32, 16, 1
	v_add3_u32 v32, v32, v33, s52
	ds_write_b16_d16_hi v128, v32 offset:22304
	v_max_f32_e32 v32, 0, v55
	v_mul_f32_e32 v32, v32, v32
	v_bfe_u32 v33, v32, 16, 1
	v_add3_u32 v32, v32, v33, s52
	ds_write_b16_d16_hi v128, v32 offset:22576
	v_max_f32_e32 v32, 0, v54
	v_mul_f32_e32 v32, v32, v32
	v_bfe_u32 v33, v32, 16, 1
	v_add3_u32 v32, v32, v33, s52
	ds_write_b16_d16_hi v128, v32 offset:23936
	v_max_f32_e32 v32, 0, v53
	v_mul_f32_e32 v32, v32, v32
	v_bfe_u32 v33, v32, 16, 1
	v_add3_u32 v32, v32, v33, s52
	ds_write_b16_d16_hi v128, v32 offset:24208
	v_max_f32_e32 v32, 0, v52
	v_mul_f32_e32 v32, v32, v32
	v_bfe_u32 v33, v32, 16, 1
	v_add3_u32 v32, v32, v33, s52
	ds_write_b16_d16_hi v128, v32 offset:24480
	v_max_f32_e32 v32, 0, v51
	v_mul_f32_e32 v32, v32, v32
	v_bfe_u32 v33, v32, 16, 1
	v_add3_u32 v32, v32, v33, s52
	ds_write_b16_d16_hi v128, v32 offset:24752
	v_max_f32_e32 v32, 0, v50
	v_mul_f32_e32 v32, v32, v32
	v_bfe_u32 v33, v32, 16, 1
	v_add3_u32 v32, v32, v33, s52
	ds_write_b16_d16_hi v128, v32 offset:17472
	v_max_f32_e32 v32, 0, v49
	v_mul_f32_e32 v32, v32, v32
	v_bfe_u32 v33, v32, 16, 1
	v_add3_u32 v32, v32, v33, s52
	ds_write_b16_d16_hi v128, v32 offset:17744
	v_max_f32_e32 v32, 0, v48
	v_mul_f32_e32 v32, v32, v32
	v_bfe_u32 v33, v32, 16, 1
	v_add3_u32 v32, v32, v33, s52
	ds_write_b16_d16_hi v128, v32 offset:18016
	v_max_f32_e32 v32, 0, v34
	v_mul_f32_e32 v32, v32, v32
	v_bfe_u32 v33, v32, 16, 1
	v_add3_u32 v32, v32, v33, s52
	ds_write_b16_d16_hi v128, v32 offset:18288
	v_max_f32_e32 v32, v36, v36
	v_max_f32_e32 v32, 0, v32
	v_mul_f32_e32 v32, v32, v32
	v_bfe_u32 v33, v32, 16, 1
	v_add3_u32 v32, v32, v33, s52
	ds_write_b16_d16_hi v128, v32 offset:19648
	v_max_f32_e32 v32, v37, v37
	v_max_f32_e32 v32, 0, v32
	v_mul_f32_e32 v32, v32, v32
	v_bfe_u32 v33, v32, 16, 1
	v_add3_u32 v32, v32, v33, s52
	ds_write_b16_d16_hi v128, v32 offset:19920
	v_max_f32_e32 v32, v38, v38
	v_max_f32_e32 v32, 0, v32
	v_mul_f32_e32 v32, v32, v32
	v_bfe_u32 v33, v32, 16, 1
	v_add3_u32 v32, v32, v33, s52
	ds_write_b16_d16_hi v128, v32 offset:20192
	v_max_f32_e32 v32, v39, v39
	v_max_f32_e32 v32, 0, v32
	v_mul_f32_e32 v32, v32, v32
	v_bfe_u32 v33, v32, 16, 1
	v_add3_u32 v32, v32, v33, s52
	ds_write_b16_d16_hi v128, v32 offset:20464
	v_max_f32_e32 v32, v40, v40
	v_max_f32_e32 v32, 0, v32
	v_mul_f32_e32 v32, v32, v32
	v_bfe_u32 v33, v32, 16, 1
	v_add3_u32 v32, v32, v33, s52
	ds_write_b16_d16_hi v128, v32 offset:21824
	v_max_f32_e32 v32, v41, v41
	v_max_f32_e32 v32, 0, v32
	v_mul_f32_e32 v32, v32, v32
	v_bfe_u32 v33, v32, 16, 1
	v_add3_u32 v32, v32, v33, s52
	ds_write_b16_d16_hi v128, v32 offset:22096
	v_max_f32_e32 v32, v42, v42
	v_max_f32_e32 v32, 0, v32
	v_mul_f32_e32 v32, v32, v32
	v_bfe_u32 v33, v32, 16, 1
	v_add3_u32 v32, v32, v33, s52
	ds_write_b16_d16_hi v128, v32 offset:22368
	v_max_f32_e32 v32, v43, v43
	v_max_f32_e32 v32, 0, v32
	v_mul_f32_e32 v32, v32, v32
	v_bfe_u32 v33, v32, 16, 1
	v_add3_u32 v32, v32, v33, s52
	ds_write_b16_d16_hi v128, v32 offset:22640
	v_max_f32_e32 v32, v44, v44
	v_max_f32_e32 v32, 0, v32
	v_mul_f32_e32 v32, v32, v32
	v_bfe_u32 v33, v32, 16, 1
	v_add3_u32 v32, v32, v33, s52
	ds_write_b16_d16_hi v128, v32 offset:24000
	v_max_f32_e32 v32, v45, v45
	v_max_f32_e32 v32, 0, v32
	v_mul_f32_e32 v32, v32, v32
	v_bfe_u32 v33, v32, 16, 1
	v_add3_u32 v32, v32, v33, s52
	ds_write_b16_d16_hi v128, v32 offset:24272
	v_max_f32_e32 v32, v46, v46
	v_max_f32_e32 v32, 0, v32
	v_mul_f32_e32 v32, v32, v32
	v_bfe_u32 v33, v32, 16, 1
	v_add3_u32 v32, v32, v33, s52
	ds_write_b16_d16_hi v128, v32 offset:24544
	v_max_f32_e32 v32, v47, v47
	v_max_f32_e32 v32, 0, v32
	v_mul_f32_e32 v32, v32, v32
	v_bfe_u32 v33, v32, 16, 1
	v_add3_u32 v32, v32, v33, s52
	ds_write_b16_d16_hi v128, v32 offset:24816
	v_max_f32_e32 v32, v16, v16
	v_max_f32_e32 v32, 0, v32
	v_mul_f32_e32 v32, v32, v32
	v_bfe_u32 v33, v32, 16, 1
	v_add3_u32 v32, v32, v33, s52
	ds_write_b16_d16_hi v128, v32 offset:26112
	v_max_f32_e32 v32, v17, v17
	v_max_f32_e32 v32, 0, v32
	v_mul_f32_e32 v32, v32, v32
	v_bfe_u32 v33, v32, 16, 1
	v_add3_u32 v32, v32, v33, s52
	ds_write_b16_d16_hi v128, v32 offset:26384
	v_max_f32_e32 v32, v18, v18
	v_max_f32_e32 v32, 0, v32
	v_mul_f32_e32 v32, v32, v32
	v_bfe_u32 v33, v32, 16, 1
	v_add3_u32 v32, v32, v33, s52
	ds_write_b16_d16_hi v128, v32 offset:26656
	v_max_f32_e32 v32, v19, v19
	v_max_f32_e32 v32, 0, v32
	v_mul_f32_e32 v32, v32, v32
	v_bfe_u32 v33, v32, 16, 1
	v_add3_u32 v32, v32, v33, s52
	ds_write_b16_d16_hi v128, v32 offset:26928
	v_max_f32_e32 v32, v20, v20
	v_max_f32_e32 v32, 0, v32
	v_mul_f32_e32 v32, v32, v32
	v_bfe_u32 v33, v32, 16, 1
	v_add3_u32 v32, v32, v33, s52
	ds_write_b16_d16_hi v128, v32 offset:28288
	v_max_f32_e32 v32, v21, v21
	v_max_f32_e32 v32, 0, v32
	v_mul_f32_e32 v32, v32, v32
	v_bfe_u32 v33, v32, 16, 1
	v_add3_u32 v32, v32, v33, s52
	ds_write_b16_d16_hi v128, v32 offset:28560
	v_max_f32_e32 v32, v22, v22
	v_max_f32_e32 v32, 0, v32
	v_mul_f32_e32 v32, v32, v32
	v_bfe_u32 v33, v32, 16, 1
	v_add3_u32 v32, v32, v33, s52
	ds_write_b16_d16_hi v128, v32 offset:28832
	v_max_f32_e32 v32, v23, v23
	v_max_f32_e32 v32, 0, v32
	v_mul_f32_e32 v32, v32, v32
	v_bfe_u32 v33, v32, 16, 1
	v_add3_u32 v32, v32, v33, s52
	ds_write_b16_d16_hi v128, v32 offset:29104
	v_max_f32_e32 v32, v24, v24
	v_max_f32_e32 v32, 0, v32
	v_mul_f32_e32 v32, v32, v32
	v_bfe_u32 v33, v32, 16, 1
	v_add3_u32 v32, v32, v33, s52
	ds_write_b16_d16_hi v128, v32 offset:30464
	v_max_f32_e32 v32, v25, v25
	v_max_f32_e32 v32, 0, v32
	v_mul_f32_e32 v32, v32, v32
	v_bfe_u32 v33, v32, 16, 1
	v_add3_u32 v32, v32, v33, s52
	ds_write_b16_d16_hi v128, v32 offset:30736
	v_max_f32_e32 v32, v26, v26
	v_max_f32_e32 v32, 0, v32
	v_mul_f32_e32 v32, v32, v32
	v_bfe_u32 v33, v32, 16, 1
	v_add3_u32 v32, v32, v33, s52
	ds_write_b16_d16_hi v128, v32 offset:31008
	v_max_f32_e32 v32, v27, v27
	v_max_f32_e32 v32, 0, v32
	v_mul_f32_e32 v32, v32, v32
	v_bfe_u32 v33, v32, 16, 1
	v_add3_u32 v32, v32, v33, s52
	ds_write_b16_d16_hi v128, v32 offset:31280
	v_max_f32_e32 v32, v28, v28
	v_max_f32_e32 v32, 0, v32
	v_mul_f32_e32 v32, v32, v32
	v_bfe_u32 v33, v32, 16, 1
	v_add3_u32 v32, v32, v33, s52
	ds_write_b16_d16_hi v128, v32 offset:32640
	v_max_f32_e32 v32, v29, v29
	v_max_f32_e32 v32, 0, v32
	v_mul_f32_e32 v32, v32, v32
	v_bfe_u32 v33, v32, 16, 1
	v_add3_u32 v32, v32, v33, s52
	ds_write_b16_d16_hi v128, v32 offset:32912
	v_max_f32_e32 v32, v30, v30
	v_max_f32_e32 v32, 0, v32
	v_mul_f32_e32 v32, v32, v32
	v_bfe_u32 v33, v32, 16, 1
	v_add3_u32 v32, v32, v33, s52
	ds_write_b16_d16_hi v128, v32 offset:33184
	v_max_f32_e32 v32, v31, v31
	v_max_f32_e32 v32, 0, v32
	v_mul_f32_e32 v32, v32, v32
	v_bfe_u32 v33, v32, 16, 1
	v_add3_u32 v32, v32, v33, s52
	ds_write_b16_d16_hi v128, v32 offset:33456
	v_max_f32_e32 v32, v0, v0
	v_max_f32_e32 v32, 0, v32
	v_mul_f32_e32 v32, v32, v32
	v_bfe_u32 v33, v32, 16, 1
	v_add3_u32 v32, v32, v33, s52
	ds_write_b16_d16_hi v128, v32 offset:26176
	v_max_f32_e32 v32, v1, v1
	v_max_f32_e32 v32, 0, v32
	v_mul_f32_e32 v32, v32, v32
	v_bfe_u32 v33, v32, 16, 1
	v_add3_u32 v32, v32, v33, s52
	ds_write_b16_d16_hi v128, v32 offset:26448
	v_max_f32_e32 v32, v2, v2
	v_max_f32_e32 v32, 0, v32
	v_mul_f32_e32 v32, v32, v32
	v_bfe_u32 v33, v32, 16, 1
	v_add3_u32 v32, v32, v33, s52
	ds_write_b16_d16_hi v128, v32 offset:26720
	v_max_f32_e32 v32, v3, v3
	v_max_f32_e32 v32, 0, v32
	v_mul_f32_e32 v32, v32, v32
	v_bfe_u32 v33, v32, 16, 1
	v_add3_u32 v32, v32, v33, s52
	ds_write_b16_d16_hi v128, v32 offset:26992
	v_max_f32_e32 v32, v4, v4
	v_max_f32_e32 v32, 0, v32
	v_mul_f32_e32 v32, v32, v32
	v_bfe_u32 v33, v32, 16, 1
	v_add3_u32 v32, v32, v33, s52
	ds_write_b16_d16_hi v128, v32 offset:28352
	v_max_f32_e32 v32, v5, v5
	v_max_f32_e32 v32, 0, v32
	v_mul_f32_e32 v32, v32, v32
	v_bfe_u32 v33, v32, 16, 1
	v_add3_u32 v32, v32, v33, s52
	ds_write_b16_d16_hi v128, v32 offset:28624
	v_max_f32_e32 v32, v6, v6
	v_max_f32_e32 v32, 0, v32
	v_mul_f32_e32 v32, v32, v32
	v_bfe_u32 v33, v32, 16, 1
	v_add3_u32 v32, v32, v33, s52
	ds_write_b16_d16_hi v128, v32 offset:28896
	v_max_f32_e32 v32, v7, v7
	v_max_f32_e32 v32, 0, v32
	v_mul_f32_e32 v32, v32, v32
	v_bfe_u32 v33, v32, 16, 1
	v_add3_u32 v32, v32, v33, s52
	ds_write_b16_d16_hi v128, v32 offset:29168
	v_max_f32_e32 v32, v8, v8
	v_max_f32_e32 v32, 0, v32
	v_mul_f32_e32 v32, v32, v32
	v_bfe_u32 v33, v32, 16, 1
	v_add3_u32 v32, v32, v33, s52
	ds_write_b16_d16_hi v128, v32 offset:30528
	v_max_f32_e32 v32, v9, v9
	v_max_f32_e32 v32, 0, v32
	v_mul_f32_e32 v32, v32, v32
	v_bfe_u32 v33, v32, 16, 1
	v_add3_u32 v32, v32, v33, s52
	ds_write_b16_d16_hi v128, v32 offset:30800
	v_max_f32_e32 v32, v10, v10
	v_max_f32_e32 v32, 0, v32
	v_mul_f32_e32 v32, v32, v32
	v_bfe_u32 v33, v32, 16, 1
	v_add3_u32 v32, v32, v33, s52
	ds_write_b16_d16_hi v128, v32 offset:31072
	v_max_f32_e32 v32, v11, v11
	v_max_f32_e32 v32, 0, v32
	v_mul_f32_e32 v32, v32, v32
	v_bfe_u32 v33, v32, 16, 1
	v_add3_u32 v32, v32, v33, s52
	ds_write_b16_d16_hi v128, v32 offset:31344
	v_max_f32_e32 v32, v12, v12
	v_max_f32_e32 v32, 0, v32
	v_mul_f32_e32 v32, v32, v32
	v_bfe_u32 v33, v32, 16, 1
	v_add3_u32 v32, v32, v33, s52
	ds_write_b16_d16_hi v128, v32 offset:32704
	v_max_f32_e32 v32, v13, v13
	v_max_f32_e32 v32, 0, v32
	v_mul_f32_e32 v32, v32, v32
	v_bfe_u32 v33, v32, 16, 1
	v_add3_u32 v32, v32, v33, s52
	ds_write_b16_d16_hi v128, v32 offset:32976
	v_max_f32_e32 v32, v14, v14
	v_max_f32_e32 v32, 0, v32
	v_mul_f32_e32 v32, v32, v32
	v_bfe_u32 v33, v32, 16, 1
	v_add3_u32 v32, v32, v33, s52
	ds_write_b16_d16_hi v128, v32 offset:33248
	v_max_f32_e32 v32, v15, v15
	v_max_f32_e32 v32, 0, v32
	v_mul_f32_e32 v32, v32, v32
	v_bfe_u32 v33, v32, 16, 1
	v_add3_u32 v32, v32, v33, s52
	ds_write_b16_d16_hi v128, v32 offset:33520

.LBB0_1284:
	ds_read_b128 v[216:219], v176 offset:36864
	ds_read_b128 v[200:203], v188
	ds_read_b128 v[220:223], v176 offset:41472
	ds_read_b128 v[204:207], v188 offset:4608
	ds_read_b128 v[208:211], v188 offset:9216
	ds_read_b128 v[212:215], v187
	s_waitcnt lgkmcnt(4)
	v_mfma_f32_32x32x16_bf16 v[112:127], v[200:203], v[216:219], v[112:127]
	ds_read_b128 v[240:243], v176 offset:36896
	global_load_dwordx4 v[140:143], v190, s[44:45]
	s_waitcnt lgkmcnt(4)
	v_mfma_f32_32x32x16_bf16 v[96:111], v[200:203], v[220:223], v[96:111]
	ds_read_b128 v[224:227], v188 offset:32
	global_load_dwordx4 v[164:167], v190, s[42:43]
	s_waitcnt lgkmcnt(4)
	v_mfma_f32_32x32x16_bf16 v[80:95], v[204:207], v[216:219], v[80:95]
	ds_read_b128 v[244:247], v176 offset:41504
	global_load_dwordx4 v[128:131], v191, s[42:43]
	s_waitcnt lgkmcnt(5)
	v_mfma_f32_32x32x16_bf16 v[64:79], v[204:207], v[220:223], v[64:79]
	ds_read_b128 v[228:231], v188 offset:4640
	global_load_dwordx4 v[132:135], v192, s[42:43]
	s_waitcnt lgkmcnt(5)
	v_mfma_f32_32x32x16_bf16 v[48:63], v[208:211], v[216:219], v[48:63]
	ds_read_b128 v[232:235], v188 offset:9248
	global_load_dwordx4 v[136:139], v193, s[42:43]
	s_waitcnt lgkmcnt(6)
	v_mfma_f32_32x32x16_bf16 v[32:47], v[208:211], v[220:223], v[32:47]
	ds_read_b128 v[236:239], v187 offset:32
	global_load_dwordx4 v[144:147], v194, s[42:43]
	s_waitcnt lgkmcnt(6)
	v_mfma_f32_32x32x16_bf16 v[16:31], v[212:215], v[216:219], v[16:31]
	global_load_dwordx4 v[148:151], v195, s[42:43]
	global_load_dwordx4 v[152:155], v196, s[42:43]
	s_waitcnt lgkmcnt(6)
	v_mfma_f32_32x32x16_bf16 v[0:15], v[212:215], v[220:223], v[0:15]
	global_load_dwordx4 v[156:159], v197, s[42:43]
	global_load_dwordx4 v[160:163], v191, s[44:45]
	s_waitcnt lgkmcnt(4)
	v_mfma_f32_32x32x16_bf16 v[112:127], v[224:227], v[240:243], v[112:127]
	ds_read_b128 v[200:203], v188 offset:64
	global_load_dwordx4 v[168:171], v192, s[44:45]
	s_waitcnt lgkmcnt(4)
	v_mfma_f32_32x32x16_bf16 v[96:111], v[224:227], v[244:247], v[96:111]
	ds_read_b128 v[204:207], v188 offset:4672
	global_load_dwordx4 v[172:175], v193, s[44:45]
	s_add_u32 s42, s42, 0x80
	s_addc_u32 s43, s43, 0
	s_add_u32 s44, s44, 0x80
	s_addc_u32 s45, s45, 0
	s_add_u32 s16, s16, 0x80
	s_waitcnt lgkmcnt(4)
	v_mfma_f32_32x32x16_bf16 v[80:95], v[228:231], v[240:243], v[80:95]
	ds_read_b128 v[208:211], v188 offset:9280
	s_waitcnt lgkmcnt(5)
	v_mfma_f32_32x32x16_bf16 v[64:79], v[228:231], v[244:247], v[64:79]
	ds_read_b128 v[212:215], v187 offset:64
	s_waitcnt lgkmcnt(5)
	v_mfma_f32_32x32x16_bf16 v[48:63], v[232:235], v[240:243], v[48:63]
	ds_read_b128 v[216:219], v176 offset:36928
	s_waitcnt lgkmcnt(6)
	v_mfma_f32_32x32x16_bf16 v[32:47], v[232:235], v[244:247], v[32:47]
	ds_read_b128 v[220:223], v176 offset:41536
	s_waitcnt lgkmcnt(6)
	v_mfma_f32_32x32x16_bf16 v[16:31], v[236:239], v[240:243], v[16:31]
	s_waitcnt lgkmcnt(6)
	v_mfma_f32_32x32x16_bf16 v[0:15], v[236:239], v[244:247], v[0:15]
	s_waitcnt lgkmcnt(1)
	v_mfma_f32_32x32x16_bf16 v[112:127], v[200:203], v[216:219], v[112:127]
	ds_read_b128 v[224:227], v188 offset:96
	s_waitcnt lgkmcnt(1)
	v_mfma_f32_32x32x16_bf16 v[96:111], v[200:203], v[220:223], v[96:111]
	ds_read_b128 v[228:231], v188 offset:4704
	s_waitcnt lgkmcnt(3)
	v_mfma_f32_32x32x16_bf16 v[80:95], v[204:207], v[216:219], v[80:95]
	ds_read_b128 v[232:235], v188 offset:9312
	s_waitcnt lgkmcnt(3)
	v_mfma_f32_32x32x16_bf16 v[64:79], v[204:207], v[220:223], v[64:79]
	ds_read_b128 v[236:239], v187 offset:96
	s_waitcnt lgkmcnt(5)
	v_mfma_f32_32x32x16_bf16 v[48:63], v[208:211], v[216:219], v[48:63]
	ds_read_b128 v[240:243], v176 offset:36960
	s_waitcnt lgkmcnt(5)
	v_mfma_f32_32x32x16_bf16 v[32:47], v[208:211], v[220:223], v[32:47]
	ds_read_b128 v[244:247], v176 offset:41568
	s_waitcnt lgkmcnt(7)
	v_mfma_f32_32x32x16_bf16 v[16:31], v[212:215], v[216:219], v[16:31]
	s_waitcnt lgkmcnt(6)
	v_mfma_f32_32x32x16_bf16 v[0:15], v[212:215], v[220:223], v[0:15]
	s_waitcnt lgkmcnt(0)
	s_barrier
	s_waitcnt vmcnt(0)
	s_waitcnt lgkmcnt(1)
	v_mfma_f32_32x32x16_bf16 v[112:127], v[224:227], v[240:243], v[112:127]
	ds_write_b128 v189, v[164:167]
	ds_write_b128 v189, v[128:131] offset:4608
	s_waitcnt lgkmcnt(2)
	v_mfma_f32_32x32x16_bf16 v[96:111], v[224:227], v[244:247], v[96:111]
	ds_write_b128 v189, v[132:135] offset:9216
	s_waitcnt lgkmcnt(4)
	v_mfma_f32_32x32x16_bf16 v[80:95], v[228:231], v[240:243], v[80:95]
	ds_write_b128 v189, v[136:139] offset:13824
	ds_write_b128 v189, v[144:147] offset:18432
	s_waitcnt lgkmcnt(5)
	v_mfma_f32_32x32x16_bf16 v[64:79], v[228:231], v[244:247], v[64:79]
	ds_write_b128 v189, v[148:151] offset:23040
	s_waitcnt lgkmcnt(7)
	v_mfma_f32_32x32x16_bf16 v[48:63], v[232:235], v[240:243], v[48:63]
	ds_write_b128 v189, v[152:155] offset:27648
	ds_write_b128 v189, v[156:159] offset:32256
	s_waitcnt lgkmcnt(8)
	v_mfma_f32_32x32x16_bf16 v[32:47], v[232:235], v[244:247], v[32:47]
	ds_write_b128 v189, v[140:143] offset:36864
	s_waitcnt lgkmcnt(10)
	v_mfma_f32_32x32x16_bf16 v[16:31], v[236:239], v[240:243], v[16:31]
	ds_write_b128 v189, v[160:163] offset:41472
	ds_write_b128 v189, v[168:171] offset:46080
	s_waitcnt lgkmcnt(11)
	v_mfma_f32_32x32x16_bf16 v[0:15], v[236:239], v[244:247], v[0:15]
	ds_write_b128 v189, v[172:175] offset:50688
	s_waitcnt lgkmcnt(0)
	s_barrier
	s_cmpk_lg_i32 s16, 0x780
	s_cbranch_scc1 .LBB0_1284
	ds_read_b128 v[128:131], v188 offset:4608
	ds_read_b128 v[132:135], v188 offset:9216
	ds_read_b128 v[136:139], v176 offset:41472
	ds_read_b128 v[140:143], v188
	ds_read_b128 v[144:147], v188 offset:32
	ds_read_b128 v[148:151], v176 offset:36864
	ds_read_b128 v[152:155], v176 offset:36896
	s_waitcnt lgkmcnt(1)
	v_mfma_f32_32x32x16_bf16 v[80:95], v[128:131], v[148:151], v[80:95]
	v_cmp_gt_u32_e32 vcc, s49, v182
	v_mfma_f32_32x32x16_bf16 v[64:79], v[128:131], v[136:139], v[64:79]
	v_mfma_f32_32x32x16_bf16 v[48:63], v[132:135], v[148:151], v[48:63]
	v_mfma_f32_32x32x16_bf16 v[32:47], v[132:135], v[136:139], v[32:47]
	ds_read_b128 v[128:131], v187
	ds_read_b128 v[132:135], v187 offset:32
	v_mfma_f32_32x32x16_bf16 v[112:127], v[140:143], v[148:151], v[112:127]
	v_mfma_f32_32x32x16_bf16 v[96:111], v[140:143], v[136:139], v[96:111]
	s_waitcnt lgkmcnt(1)
	v_mfma_f32_32x32x16_bf16 v[16:31], v[128:131], v[148:151], v[16:31]
	v_mfma_f32_32x32x16_bf16 v[0:15], v[128:131], v[136:139], v[0:15]
	ds_read_b128 v[128:131], v188 offset:4640
	ds_read_b128 v[136:139], v188 offset:9248
	ds_read_b128 v[140:143], v176 offset:41504
	v_mfma_f32_32x32x16_bf16 v[112:127], v[144:147], v[152:155], v[112:127]
	s_waitcnt lgkmcnt(0)
	v_mfma_f32_32x32x16_bf16 v[96:111], v[144:147], v[140:143], v[96:111]
	v_mfma_f32_32x32x16_bf16 v[80:95], v[128:131], v[152:155], v[80:95]
	v_mfma_f32_32x32x16_bf16 v[64:79], v[128:131], v[140:143], v[64:79]
	v_mfma_f32_32x32x16_bf16 v[48:63], v[136:139], v[152:155], v[48:63]
	v_mfma_f32_32x32x16_bf16 v[32:47], v[136:139], v[140:143], v[32:47]
	v_mfma_f32_32x32x16_bf16 v[16:31], v[132:135], v[152:155], v[16:31]
	v_mfma_f32_32x32x16_bf16 v[0:15], v[132:135], v[140:143], v[0:15]
	ds_read_b128 v[128:131], v188 offset:64
	ds_read_b128 v[132:135], v188 offset:4672
	ds_read_b128 v[136:139], v188 offset:9280
	ds_read_b128 v[140:143], v187 offset:64
	ds_read_b128 v[144:147], v176 offset:36928
	ds_read_b128 v[148:151], v176 offset:41536
	s_waitcnt lgkmcnt(1)
	v_mfma_f32_32x32x16_bf16 v[112:127], v[128:131], v[144:147], v[112:127]
	s_waitcnt lgkmcnt(0)
	v_mfma_f32_32x32x16_bf16 v[96:111], v[128:131], v[148:151], v[96:111]
	v_mfma_f32_32x32x16_bf16 v[80:95], v[132:135], v[144:147], v[80:95]
	v_mfma_f32_32x32x16_bf16 v[64:79], v[132:135], v[148:151], v[64:79]
	v_mfma_f32_32x32x16_bf16 v[48:63], v[136:139], v[144:147], v[48:63]
	v_mfma_f32_32x32x16_bf16 v[32:47], v[136:139], v[148:151], v[32:47]
	v_mfma_f32_32x32x16_bf16 v[16:31], v[140:143], v[144:147], v[16:31]
	v_mfma_f32_32x32x16_bf16 v[0:15], v[140:143], v[148:151], v[0:15]
	ds_read_b128 v[128:131], v188 offset:96
	ds_read_b128 v[132:135], v188 offset:4704
	ds_read_b128 v[136:139], v188 offset:9312
	ds_read_b128 v[140:143], v187 offset:96
	ds_read_b128 v[144:147], v176 offset:36960
	ds_read_b128 v[148:151], v176 offset:41568
	s_waitcnt lgkmcnt(0)
	s_barrier
	v_mfma_f32_32x32x16_bf16 v[112:127], v[128:131], v[144:147], v[112:127]
	v_mfma_f32_32x32x16_bf16 v[96:111], v[128:131], v[148:151], v[96:111]
	v_lshlrev_b32_e32 v128, 7, v185
	v_lshl_or_b32 v128, v184, 1, v128
	v_mad_u32_u24 v130, v186, s50, v128
	s_nop 7
	v_bfe_u32 v131, v117, 16, 1
	v_bfe_u32 v251, v118, 16, 1
	v_bfe_u32 v183, v121, 16, 1
	v_bfe_u32 v250, v122, 16, 1
	v_mfma_f32_32x32x16_bf16 v[80:95], v[132:135], v[144:147], v[80:95]
	v_bfe_u32 v249, v123, 16, 1
	v_bfe_u32 v246, v124, 16, 1
	v_bfe_u32 v244, v125, 16, 1
	v_bfe_u32 v247, v126, 16, 1
	v_bfe_u32 v248, v127, 16, 1
	v_bfe_u32 v245, v96, 16, 1
	v_bfe_u32 v243, v97, 16, 1
	v_mfma_f32_32x32x16_bf16 v[64:79], v[132:135], v[148:151], v[64:79]
	v_bfe_u32 v135, v115, 16, 1
	v_bfe_u32 v134, v116, 16, 1
	v_bfe_u32 v132, v119, 16, 1
	v_bfe_u32 v133, v120, 16, 1
	v_bfe_u32 v242, v98, 16, 1
	v_bfe_u32 v239, v99, 16, 1
	v_bfe_u32 v237, v100, 16, 1
	v_mfma_f32_32x32x16_bf16 v[48:63], v[136:139], v[144:147], v[48:63]
	v_bfe_u32 v240, v101, 16, 1
	v_bfe_u32 v241, v102, 16, 1
	v_bfe_u32 v238, v103, 16, 1
	v_bfe_u32 v236, v104, 16, 1
	v_bfe_u32 v235, v105, 16, 1
	v_bfe_u32 v232, v106, 16, 1
	v_bfe_u32 v230, v107, 16, 1
	v_mfma_f32_32x32x16_bf16 v[32:47], v[136:139], v[148:151], v[32:47]
	v_bfe_u32 v137, v112, 16, 1
	v_bfe_u32 v138, v113, 16, 1
	v_bfe_u32 v136, v114, 16, 1
	v_bfe_u32 v233, v108, 16, 1
	v_bfe_u32 v234, v109, 16, 1
	v_bfe_u32 v231, v110, 16, 1
	v_bfe_u32 v229, v111, 16, 1
	v_mfma_f32_32x32x16_bf16 v[16:31], v[140:143], v[144:147], v[16:31]
	v_bfe_u32 v228, v80, 16, 1
	v_bfe_u32 v252, v81, 16, 1
	v_bfe_u32 v253, v69, 16, 1
	v_bfe_u32 v225, v70, 16, 1
	v_bfe_u32 v223, v71, 16, 1
	v_bfe_u32 v226, v72, 16, 1
	v_bfe_u32 v227, v73, 16, 1
	v_mfma_f32_32x32x16_bf16 v[0:15], v[140:143], v[148:151], v[0:15]
	v_bfe_u32 v224, v74, 16, 1
	v_bfe_u32 v222, v75, 16, 1
	v_bfe_u32 v221, v76, 16, 1
	v_bfe_u32 v218, v77, 16, 1
	v_bfe_u32 v216, v78, 16, 1
	v_bfe_u32 v219, v79, 16, 1
	v_bfe_u32 v220, v48, 16, 1
	v_bfe_u32 v217, v49, 16, 1
	v_bfe_u32 v215, v50, 16, 1
	v_bfe_u32 v214, v51, 16, 1
	v_bfe_u32 v211, v52, 16, 1
	v_bfe_u32 v209, v53, 16, 1
	v_bfe_u32 v212, v54, 16, 1
	v_bfe_u32 v213, v55, 16, 1
	v_bfe_u32 v210, v56, 16, 1
	v_bfe_u32 v208, v57, 16, 1
	v_bfe_u32 v207, v58, 16, 1
	v_bfe_u32 v204, v59, 16, 1
	v_bfe_u32 v202, v60, 16, 1
	v_bfe_u32 v205, v61, 16, 1
	v_bfe_u32 v206, v62, 16, 1
	v_bfe_u32 v203, v63, 16, 1
	v_bfe_u32 v201, v32, 16, 1
	v_bfe_u32 v200, v33, 16, 1
	v_bfe_u32 v197, v34, 16, 1
	v_bfe_u32 v195, v35, 16, 1
	v_bfe_u32 v198, v36, 16, 1
	v_bfe_u32 v199, v37, 16, 1
	v_bfe_u32 v196, v38, 16, 1
	v_bfe_u32 v194, v39, 16, 1
	v_bfe_u32 v193, v40, 16, 1
	v_bfe_u32 v190, v41, 16, 1
	v_bfe_u32 v188, v42, 16, 1
	v_bfe_u32 v191, v43, 16, 1
	v_bfe_u32 v192, v44, 16, 1
	v_bfe_u32 v189, v45, 16, 1
	v_bfe_u32 v187, v46, 16, 1
	v_bfe_u32 v186, v47, 16, 1
	v_bfe_u32 v181, v16, 16, 1
	v_bfe_u32 v179, v17, 16, 1
	v_bfe_u32 v184, v18, 16, 1
	v_bfe_u32 v185, v19, 16, 1
	v_bfe_u32 v180, v20, 16, 1
	v_bfe_u32 v178, v21, 16, 1
	v_bfe_u32 v175, v22, 16, 1
	v_bfe_u32 v173, v23, 16, 1
	v_bfe_u32 v170, v24, 16, 1
	v_bfe_u32 v174, v25, 16, 1
	v_bfe_u32 v171, v26, 16, 1
	v_bfe_u32 v172, v27, 16, 1
	v_bfe_u32 v169, v28, 16, 1
	v_bfe_u32 v168, v29, 16, 1
	v_bfe_u32 v166, v30, 16, 1
	v_bfe_u32 v164, v31, 16, 1
	v_bfe_u32 v167, v0, 16, 1
	v_bfe_u32 v165, v1, 16, 1
	v_bfe_u32 v163, v2, 16, 1
	v_bfe_u32 v162, v3, 16, 1
	v_bfe_u32 v161, v4, 16, 1
	v_bfe_u32 v160, v5, 16, 1
	v_bfe_u32 v159, v6, 16, 1
	v_bfe_u32 v158, v7, 16, 1
	v_bfe_u32 v157, v8, 16, 1
	v_bfe_u32 v156, v9, 16, 1
	v_bfe_u32 v155, v10, 16, 1
	v_bfe_u32 v154, v11, 16, 1
	v_bfe_u32 v153, v12, 16, 1
	v_bfe_u32 v152, v13, 16, 1
	v_bfe_u32 v147, v14, 16, 1
	v_bfe_u32 v151, v15, 16, 1
	s_and_saveexec_b64 s[16:17], vcc
	s_cbranch_execz .LBB0_1287
	v_add3_u32 v128, v112, v137, s51
	ds_write_b16_d16_hi v130, v128
	v_add3_u32 v128, v113, v138, s51
	ds_write_b16_d16_hi v130, v128 offset:272
	v_add3_u32 v128, v114, v136, s51
	ds_write_b16_d16_hi v130, v128 offset:544
	v_add3_u32 v128, v115, v135, s51
	ds_write_b16_d16_hi v130, v128 offset:816
	v_add3_u32 v128, v116, v134, s51
	ds_write_b16_d16_hi v130, v128 offset:2176
	v_add3_u32 v128, v117, v131, s51
	ds_write_b16_d16_hi v130, v128 offset:2448
	v_add3_u32 v128, v118, v251, s51
	ds_write_b16_d16_hi v130, v128 offset:2720
	v_add3_u32 v128, v119, v132, s51
	ds_write_b16_d16_hi v130, v128 offset:2992
	v_add3_u32 v128, v120, v133, s51
	ds_write_b16_d16_hi v130, v128 offset:4352
	v_add3_u32 v128, v121, v183, s51
	ds_write_b16_d16_hi v130, v128 offset:4624
	v_add3_u32 v128, v122, v250, s51
	ds_write_b16_d16_hi v130, v128 offset:4896
	v_add3_u32 v128, v123, v249, s51
	ds_write_b16_d16_hi v130, v128 offset:5168
	v_add3_u32 v128, v124, v246, s51
	ds_write_b16_d16_hi v130, v128 offset:6528
	v_add3_u32 v128, v125, v244, s51
	ds_write_b16_d16_hi v130, v128 offset:6800
	v_add3_u32 v128, v126, v247, s51
	ds_write_b16_d16_hi v130, v128 offset:7072
	v_add3_u32 v128, v127, v248, s51
	ds_write_b16_d16_hi v130, v128 offset:7344
	v_add3_u32 v128, v96, v245, s51
	ds_write_b16_d16_hi v130, v128 offset:64
	v_add3_u32 v128, v97, v243, s51
	ds_write_b16_d16_hi v130, v128 offset:336
	v_add3_u32 v128, v98, v242, s51
	ds_write_b16_d16_hi v130, v128 offset:608
	v_add3_u32 v128, v99, v239, s51
	ds_write_b16_d16_hi v130, v128 offset:880
	v_add3_u32 v128, v100, v237, s51
	ds_write_b16_d16_hi v130, v128 offset:2240
	v_add3_u32 v128, v101, v240, s51
	ds_write_b16_d16_hi v130, v128 offset:2512
	v_add3_u32 v128, v102, v241, s51
	ds_write_b16_d16_hi v130, v128 offset:2784
	v_add3_u32 v128, v103, v238, s51
	ds_write_b16_d16_hi v130, v128 offset:3056
	v_add3_u32 v128, v104, v236, s51
	ds_write_b16_d16_hi v130, v128 offset:4416
	v_add3_u32 v128, v105, v235, s51
	ds_write_b16_d16_hi v130, v128 offset:4688
	v_add3_u32 v128, v106, v232, s51
	ds_write_b16_d16_hi v130, v128 offset:4960
	v_add3_u32 v128, v107, v230, s51
	ds_write_b16_d16_hi v130, v128 offset:5232
	v_add3_u32 v128, v108, v233, s51
	ds_write_b16_d16_hi v130, v128 offset:6592
	v_add3_u32 v128, v109, v234, s51
	ds_write_b16_d16_hi v130, v128 offset:6864
	v_add3_u32 v128, v110, v231, s51
	ds_write_b16_d16_hi v130, v128 offset:7136
	v_add3_u32 v128, v111, v229, s51
	ds_write_b16_d16_hi v130, v128 offset:7408
	v_add3_u32 v128, v80, v228, s51
	ds_write_b16_d16_hi v130, v128 offset:8704
	v_add3_u32 v128, v81, v252, s51
	ds_write_b16_d16_hi v130, v128 offset:8976
	v_bfe_u32 v128, v82, 16, 1
	v_add3_u32 v128, v82, v128, s51
	ds_write_b16_d16_hi v130, v128 offset:9248
	v_bfe_u32 v128, v83, 16, 1
	v_add3_u32 v128, v83, v128, s51
	ds_write_b16_d16_hi v130, v128 offset:9520
	v_bfe_u32 v128, v84, 16, 1
	v_add3_u32 v128, v84, v128, s51
	ds_write_b16_d16_hi v130, v128 offset:10880
	v_bfe_u32 v128, v85, 16, 1
	v_add3_u32 v128, v85, v128, s51
	ds_write_b16_d16_hi v130, v128 offset:11152
	v_bfe_u32 v128, v86, 16, 1
	v_add3_u32 v128, v86, v128, s51
	ds_write_b16_d16_hi v130, v128 offset:11424
	v_bfe_u32 v128, v87, 16, 1
	v_add3_u32 v128, v87, v128, s51
	ds_write_b16_d16_hi v130, v128 offset:11696
	v_bfe_u32 v128, v88, 16, 1
	v_add3_u32 v128, v88, v128, s51
	ds_write_b16_d16_hi v130, v128 offset:13056
	v_bfe_u32 v128, v89, 16, 1
	v_add3_u32 v128, v89, v128, s51
	ds_write_b16_d16_hi v130, v128 offset:13328
	v_bfe_u32 v128, v90, 16, 1
	v_add3_u32 v128, v90, v128, s51
	ds_write_b16_d16_hi v130, v128 offset:13600
	v_bfe_u32 v128, v91, 16, 1
	v_add3_u32 v128, v91, v128, s51
	ds_write_b16_d16_hi v130, v128 offset:13872
	v_bfe_u32 v128, v92, 16, 1
	v_add3_u32 v128, v92, v128, s51
	ds_write_b16_d16_hi v130, v128 offset:15232
	v_bfe_u32 v128, v93, 16, 1
	v_add3_u32 v128, v93, v128, s51
	ds_write_b16_d16_hi v130, v128 offset:15504
	v_bfe_u32 v128, v94, 16, 1
	v_add3_u32 v128, v94, v128, s51
	ds_write_b16_d16_hi v130, v128 offset:15776
	v_bfe_u32 v128, v95, 16, 1
	v_add3_u32 v128, v95, v128, s51
	ds_write_b16_d16_hi v130, v128 offset:16048
	v_bfe_u32 v128, v64, 16, 1
	v_add3_u32 v128, v64, v128, s51
	ds_write_b16_d16_hi v130, v128 offset:8768
	v_bfe_u32 v128, v65, 16, 1
	v_add3_u32 v128, v65, v128, s51
	ds_write_b16_d16_hi v130, v128 offset:9040
	v_bfe_u32 v128, v66, 16, 1
	v_add3_u32 v128, v66, v128, s51
	ds_write_b16_d16_hi v130, v128 offset:9312
	v_bfe_u32 v128, v67, 16, 1
	v_add3_u32 v128, v67, v128, s51
	ds_write_b16_d16_hi v130, v128 offset:9584
	v_bfe_u32 v128, v68, 16, 1
	v_add3_u32 v128, v68, v128, s51
	ds_write_b16_d16_hi v130, v128 offset:10944
	v_add3_u32 v128, v69, v253, s51
	ds_write_b16_d16_hi v130, v128 offset:11216
	v_add3_u32 v128, v70, v225, s51
	ds_write_b16_d16_hi v130, v128 offset:11488
	v_add3_u32 v128, v71, v223, s51
	ds_write_b16_d16_hi v130, v128 offset:11760
	v_add3_u32 v128, v72, v226, s51
	ds_write_b16_d16_hi v130, v128 offset:13120
	v_add3_u32 v128, v73, v227, s51
	ds_write_b16_d16_hi v130, v128 offset:13392
	v_add3_u32 v128, v74, v224, s51
	ds_write_b16_d16_hi v130, v128 offset:13664
	v_add3_u32 v128, v75, v222, s51
	ds_write_b16_d16_hi v130, v128 offset:13936
	v_add3_u32 v128, v76, v221, s51
	ds_write_b16_d16_hi v130, v128 offset:15296
	v_add3_u32 v128, v77, v218, s51
	ds_write_b16_d16_hi v130, v128 offset:15568
	v_add3_u32 v128, v78, v216, s51
	ds_write_b16_d16_hi v130, v128 offset:15840
	v_add3_u32 v128, v79, v219, s51
	ds_write_b16_d16_hi v130, v128 offset:16112
	v_add3_u32 v128, v48, v220, s51
	ds_write_b16_d16_hi v130, v128 offset:17408
	v_add3_u32 v128, v49, v217, s51
	ds_write_b16_d16_hi v130, v128 offset:17680
	v_add3_u32 v128, v50, v215, s51
	ds_write_b16_d16_hi v130, v128 offset:17952
	v_add3_u32 v128, v51, v214, s51
	ds_write_b16_d16_hi v130, v128 offset:18224
	v_add3_u32 v128, v52, v211, s51
	ds_write_b16_d16_hi v130, v128 offset:19584
	v_add3_u32 v128, v53, v209, s51
	ds_write_b16_d16_hi v130, v128 offset:19856
	v_add3_u32 v128, v54, v212, s51
	ds_write_b16_d16_hi v130, v128 offset:20128
	v_add3_u32 v128, v55, v213, s51
	ds_write_b16_d16_hi v130, v128 offset:20400
	v_add3_u32 v128, v56, v210, s51
	ds_write_b16_d16_hi v130, v128 offset:21760
	v_add3_u32 v128, v57, v208, s51
	ds_write_b16_d16_hi v130, v128 offset:22032
	v_add3_u32 v128, v58, v207, s51
	ds_write_b16_d16_hi v130, v128 offset:22304
	v_add3_u32 v128, v59, v204, s51
	ds_write_b16_d16_hi v130, v128 offset:22576
	v_add3_u32 v128, v60, v202, s51
	ds_write_b16_d16_hi v130, v128 offset:23936
	v_add3_u32 v128, v61, v205, s51
	ds_write_b16_d16_hi v130, v128 offset:24208
	v_add3_u32 v128, v62, v206, s51
	ds_write_b16_d16_hi v130, v128 offset:24480
	v_add3_u32 v128, v63, v203, s51
	ds_write_b16_d16_hi v130, v128 offset:24752
	v_add3_u32 v128, v32, v201, s51
	ds_write_b16_d16_hi v130, v128 offset:17472
	v_add3_u32 v128, v33, v200, s51
	ds_write_b16_d16_hi v130, v128 offset:17744
	v_add3_u32 v128, v34, v197, s51
	ds_write_b16_d16_hi v130, v128 offset:18016
	v_add3_u32 v128, v35, v195, s51
	ds_write_b16_d16_hi v130, v128 offset:18288
	v_add3_u32 v128, v36, v198, s51
	ds_write_b16_d16_hi v130, v128 offset:19648
	v_add3_u32 v128, v37, v199, s51
	ds_write_b16_d16_hi v130, v128 offset:19920
	v_add3_u32 v128, v38, v196, s51
	ds_write_b16_d16_hi v130, v128 offset:20192
	v_add3_u32 v128, v39, v194, s51
	ds_write_b16_d16_hi v130, v128 offset:20464
	v_add3_u32 v128, v40, v193, s51
	ds_write_b16_d16_hi v130, v128 offset:21824
	v_add3_u32 v128, v41, v190, s51
	ds_write_b16_d16_hi v130, v128 offset:22096
	v_add3_u32 v128, v42, v188, s51
	ds_write_b16_d16_hi v130, v128 offset:22368
	v_add3_u32 v128, v43, v191, s51
	ds_write_b16_d16_hi v130, v128 offset:22640
	v_add3_u32 v128, v44, v192, s51
	ds_write_b16_d16_hi v130, v128 offset:24000
	v_add3_u32 v128, v45, v189, s51
	ds_write_b16_d16_hi v130, v128 offset:24272
	v_add3_u32 v128, v46, v187, s51
	ds_write_b16_d16_hi v130, v128 offset:24544
	v_add3_u32 v128, v47, v186, s51
	ds_write_b16_d16_hi v130, v128 offset:24816
	v_add3_u32 v128, v16, v181, s51
	ds_write_b16_d16_hi v130, v128 offset:26112
	v_add3_u32 v128, v17, v179, s51
	ds_write_b16_d16_hi v130, v128 offset:26384
	v_add3_u32 v128, v18, v184, s51
	ds_write_b16_d16_hi v130, v128 offset:26656
	v_add3_u32 v128, v19, v185, s51
	ds_write_b16_d16_hi v130, v128 offset:26928
	v_add3_u32 v128, v20, v180, s51
	ds_write_b16_d16_hi v130, v128 offset:28288
	v_add3_u32 v128, v21, v178, s51
	ds_write_b16_d16_hi v130, v128 offset:28560
	v_add3_u32 v128, v22, v175, s51
	ds_write_b16_d16_hi v130, v128 offset:28832
	v_add3_u32 v128, v23, v173, s51
	ds_write_b16_d16_hi v130, v128 offset:29104
	v_add3_u32 v128, v24, v170, s51
	ds_write_b16_d16_hi v130, v128 offset:30464
	v_add3_u32 v128, v25, v174, s51
	ds_write_b16_d16_hi v130, v128 offset:30736
	v_add3_u32 v128, v26, v171, s51
	ds_write_b16_d16_hi v130, v128 offset:31008
	v_add3_u32 v128, v27, v172, s51
	ds_write_b16_d16_hi v130, v128 offset:31280
	v_add3_u32 v128, v28, v169, s51
	ds_write_b16_d16_hi v130, v128 offset:32640
	v_add3_u32 v128, v29, v168, s51
	ds_write_b16_d16_hi v130, v128 offset:32912
	v_add3_u32 v128, v30, v166, s51
	ds_write_b16_d16_hi v130, v128 offset:33184
	v_add3_u32 v128, v31, v164, s51
	ds_write_b16_d16_hi v130, v128 offset:33456
	v_add3_u32 v128, v0, v167, s51
	ds_write_b16_d16_hi v130, v128 offset:26176
	v_add3_u32 v128, v1, v165, s51
	ds_write_b16_d16_hi v130, v128 offset:26448
	v_add3_u32 v128, v2, v163, s51
	ds_write_b16_d16_hi v130, v128 offset:26720
	v_add3_u32 v128, v3, v162, s51
	ds_write_b16_d16_hi v130, v128 offset:26992
	v_add3_u32 v128, v4, v161, s51
	ds_write_b16_d16_hi v130, v128 offset:28352
	v_add3_u32 v128, v5, v160, s51
	ds_write_b16_d16_hi v130, v128 offset:28624
	v_add3_u32 v128, v6, v159, s51
	ds_write_b16_d16_hi v130, v128 offset:28896
	v_add3_u32 v128, v7, v158, s51
	ds_write_b16_d16_hi v130, v128 offset:29168
	v_add3_u32 v128, v8, v157, s51
	ds_write_b16_d16_hi v130, v128 offset:30528
	v_add3_u32 v128, v9, v156, s51
	ds_write_b16_d16_hi v130, v128 offset:30800
	v_add3_u32 v128, v10, v155, s51
	ds_write_b16_d16_hi v130, v128 offset:31072
	v_add3_u32 v128, v11, v154, s51
	ds_write_b16_d16_hi v130, v128 offset:31344
	v_add3_u32 v128, v12, v153, s51
	ds_write_b16_d16_hi v130, v128 offset:32704
	v_add3_u32 v128, v13, v152, s51
	ds_write_b16_d16_hi v130, v128 offset:32976
	v_add3_u32 v128, v14, v147, s51
	ds_write_b16_d16_hi v130, v128 offset:33248
	v_add3_u32 v128, v15, v151, s51
	ds_write_b16_d16_hi v130, v128 offset:33520

.LBB0_1684:
	s_waitcnt lgkmcnt(0)
	s_barrier
	s_waitcnt vmcnt(0)
	ds_write_b128 v161, v[88:91]
	ds_write_b128 v162, v[92:95]
	ds_write_b128 v163, v[96:99]
	ds_write_b128 v164, v[104:107] offset:13312
	ds_write_b128 v165, v[100:103] offset:13312
	s_waitcnt lgkmcnt(0)
	s_barrier
	ds_read_b128 v[32:35], v116
	ds_read_b128 v[88:91], v116 offset:32
	s_waitcnt lgkmcnt(1)
	v_mfma_f32_32x32x16_bf16 v[32:47], v[32:35], v[84:87], 0
	ds_read_b128 v[48:51], v116 offset:6656
	ds_read_b128 v[92:95], v116 offset:6688
	v_mov_b32_e32 v167, v109
	v_mov_b32_e32 v166, v108
	v_lshl_add_u64 v[100:101], s[8:9], 0, v[138:139]
	v_lshl_add_u64 v[144:145], s[8:9], 0, v[136:137]
	v_lshl_add_u64 v[102:103], s[8:9], 0, v[134:135]
	v_lshl_add_u64 v[106:107], s[8:9], 0, v[132:133]
	s_waitcnt lgkmcnt(1)
	v_mfma_f32_32x32x16_bf16 v[48:63], v[48:51], v[84:87], 0
	v_lshl_add_u64 v[104:105], s[8:9], 0, v[130:131]
	v_lshl_add_u64 v[140:141], s[8:9], 0, v[128:129]
	v_lshl_add_u64 v[142:143], s[8:9], 0, v[126:127]
	v_lshl_add_u64 v[146:147], s[8:9], 0, v[124:125]
	v_add_u32_e32 v172, v122, v159
	v_add_u32_e32 v173, v122, v160
	s_add_i32 s0, s0, -1
	v_mfma_f32_32x32x16_bf16 v[32:47], v[88:91], v[80:83], v[32:47]
	ds_read_b128 v[88:91], v116 offset:64
	v_lshl_add_u64 v[124:125], v[124:125], 0, s[44:45]
	v_lshl_add_u64 v[126:127], v[126:127], 0, s[44:45]
	v_lshl_add_u64 v[128:129], v[128:129], 0, s[46:47]
	v_lshl_add_u64 v[130:131], v[130:131], 0, s[48:49]
	v_lshl_add_u64 v[132:133], v[132:133], 0, s[46:47]
	v_lshl_add_u64 v[134:135], v[134:135], 0, s[48:49]
	s_waitcnt lgkmcnt(1)
	v_mfma_f32_32x32x16_bf16 v[48:63], v[92:95], v[80:83], v[48:63]
	ds_read_b128 v[168:171], v116 offset:96
	ds_read_b128 v[92:95], v116 offset:6720
	ds_read_b128 v[96:99], v116 offset:6752
	v_lshl_add_u64 v[136:137], v[136:137], 0, s[46:47]
	v_lshl_add_u64 v[138:139], v[138:139], 0, s[48:49]
	s_cmp_lg_u32 s0, 0
	s_waitcnt lgkmcnt(3)
	v_mfma_f32_32x32x16_bf16 v[32:47], v[88:91], v[76:79], v[32:47]
	s_waitcnt lgkmcnt(1)
	v_mfma_f32_32x32x16_bf16 v[48:63], v[92:95], v[76:79], v[48:63]
	ds_read_b128 v[92:95], v116 offset:128
	ds_read_b128 v[112:115], v116 offset:160
	ds_read_b128 v[88:91], v116 offset:6784
	ds_read_b128 v[108:111], v116 offset:6816
	v_mfma_f32_32x32x16_bf16 v[32:47], v[168:171], v[72:75], v[32:47]
	v_add_u32_e32 v168, v158, v159
	v_add_u32_e32 v169, v158, v160
	s_waitcnt lgkmcnt(4)
	v_mfma_f32_32x32x16_bf16 v[48:63], v[96:99], v[72:75], v[48:63]
	v_cndmask_b32_e32 v97, v145, v101, vcc
	v_cndmask_b32_e32 v96, v144, v100, vcc
	v_cndmask_b32_e64 v99, v107, v103, s[4:5]
	v_cndmask_b32_e64 v98, v106, v102, s[4:5]
	v_cndmask_b32_e64 v145, v141, v105, s[6:7]
	v_cndmask_b32_e64 v144, v140, v104, s[6:7]
	global_load_dwordx4 v[104:107], v[142:143], off
	global_load_dwordx4 v[100:103], v[146:147], off
	s_waitcnt lgkmcnt(0)
	v_mfma_f32_32x32x16_bf16 v[32:47], v[92:95], v[68:71], v[32:47]
	v_add_u32_e32 v143, 0x3000, v172
	v_add_u32_e32 v142, 0x3000, v173
	v_add_u32_e32 v141, 0x3000, v168
	v_add_u32_e32 v140, 0x3000, v169
	v_mfma_f32_32x32x16_bf16 v[48:63], v[88:91], v[68:71], v[48:63]
	global_load_dwordx4 v[88:91], v[96:97], off
	global_load_dwordx4 v[92:95], v[98:99], off
	s_nop 0
	global_load_dwordx4 v[96:99], v[144:145], off
	ds_read2_b64 v[144:147], v143 offset0:128 offset1:130
	v_mfma_f32_32x32x16_bf16 v[32:47], v[112:115], v[64:67], v[32:47]
	ds_read2_b64 v[112:115], v143 offset0:132 offset1:134
	ds_read2_b64 v[168:171], v142 offset0:128 offset1:130
	ds_read2_b64 v[172:175], v142 offset0:132 offset1:134
	ds_read2_b64 v[176:179], v143 offset0:136 offset1:138
	ds_read2_b64 v[180:183], v142 offset0:136 offset1:138
	ds_read2_b64 v[184:187], v141 offset0:140 offset1:142
	ds_read2_b64 v[188:191], v140 offset0:140 offset1:142
	v_mfma_f32_32x32x16_bf16 v[48:63], v[108:111], v[64:67], v[48:63]
	s_nop 3
	v_max_f32_e32 v108, v33, v33
	v_max_f32_e32 v109, v32, v32
	v_max_f32_e32 v108, v109, v108
	v_max3_f32 v108, v108, v34, v35
	v_max3_f32 v108, v108, v36, v37
	v_max3_f32 v108, v108, v38, v39
	v_max3_f32 v108, v108, v40, v41
	v_max3_f32 v108, v108, v42, v43
	v_max3_f32 v108, v108, v44, v45
	v_max3_f32 v108, v108, v46, v47
	v_max3_f32 v108, v108, v48, v49
	v_max3_f32 v108, v108, v50, v51
	v_max3_f32 v108, v108, v52, v53
	v_max3_f32 v108, v108, v54, v55
	v_max3_f32 v108, v108, v56, v57
	v_max3_f32 v108, v108, v58, v59
	v_max3_f32 v108, v108, v60, v61
	v_max3_f32 v108, v108, v62, v63
	ds_bpermute_b32 v109, v123, v108
	s_waitcnt lgkmcnt(0)
	v_max3_f32 v109, v167, v108, v109
	v_sub_f32_e32 v108, v167, v109
	v_sub_f32_e32 v32, v32, v109
	v_sub_f32_e32 v33, v33, v109
	v_sub_f32_e32 v34, v34, v109
	v_sub_f32_e32 v35, v35, v109
	v_sub_f32_e32 v36, v36, v109
	v_sub_f32_e32 v37, v37, v109
	v_sub_f32_e32 v38, v38, v109
	v_sub_f32_e32 v39, v39, v109
	v_sub_f32_e32 v110, v42, v109
	v_exp_f32_e32 v42, v108
	v_exp_f32_e32 v32, v32
	v_exp_f32_e32 v33, v33
	s_nop 0
	v_cvt_pk_bf16_f32 v223, v32, v33
	v_exp_f32_e32 v108, v34
	v_exp_f32_e32 v111, v35
	v_exp_f32_e32 v167, v36
	v_exp_f32_e32 v192, v37
	v_exp_f32_e32 v193, v38
	v_exp_f32_e32 v194, v39
	v_sub_f32_e32 v43, v43, v109
	v_sub_f32_e32 v40, v40, v109
	v_sub_f32_e32 v41, v41, v109
	v_exp_f32_e32 v43, v43
	v_exp_f32_e32 v195, v40
	v_exp_f32_e32 v196, v41
	v_add_f32_e32 v34, 0, v32
	v_bfe_u32 v39, v32, 16, 1
	v_add_f32_e32 v222, v33, v34
	v_add3_u32 v32, v32, v39, s61
	v_lshrrev_b32_e32 v32, 16, v32
	v_sub_f32_e32 v44, v44, v109
	v_sub_f32_e32 v45, v45, v109
	v_sub_f32_e32 v46, v46, v109
	v_pk_mul_f32 v[30:31], v[30:31], v[42:43] op_sel_hi:[1,0]
	v_pk_mul_f32 v[28:29], v[28:29], v[42:43] op_sel_hi:[1,0]
	v_pk_mul_f32 v[26:27], v[26:27], v[42:43] op_sel_hi:[1,0]
	v_pk_mul_f32 v[24:25], v[24:25], v[42:43] op_sel_hi:[1,0]
	v_pk_mul_f32 v[22:23], v[22:23], v[42:43] op_sel_hi:[1,0]
	v_pk_mul_f32 v[20:21], v[20:21], v[42:43] op_sel_hi:[1,0]
	v_pk_mul_f32 v[18:19], v[18:19], v[42:43] op_sel_hi:[1,0]
	v_pk_mul_f32 v[16:17], v[16:17], v[42:43] op_sel_hi:[1,0]
	v_pk_mul_f32 v[14:15], v[14:15], v[42:43] op_sel_hi:[1,0]
	v_pk_mul_f32 v[12:13], v[12:13], v[42:43] op_sel_hi:[1,0]
	v_pk_mul_f32 v[10:11], v[10:11], v[42:43] op_sel_hi:[1,0]
	v_pk_mul_f32 v[8:9], v[8:9], v[42:43] op_sel_hi:[1,0]
	v_pk_mul_f32 v[6:7], v[6:7], v[42:43] op_sel_hi:[1,0]
	v_pk_mul_f32 v[4:5], v[4:5], v[42:43] op_sel_hi:[1,0]
	v_pk_mul_f32 v[2:3], v[2:3], v[42:43] op_sel_hi:[1,0]
	v_pk_mul_f32 v[0:1], v[0:1], v[42:43] op_sel_hi:[1,0]
	v_cvt_pk_bf16_f32 v35, v193, v194
	v_cvt_pk_bf16_f32 v34, v167, v192
	v_cvt_pk_bf16_f32 v33, v108, v111
	v_mov_b32_e32 v32, v223
	v_sub_f32_e32 v47, v47, v109
	v_exp_f32_e32 v110, v110
	v_exp_f32_e32 v44, v44
	v_exp_f32_e32 v45, v45
	v_exp_f32_e32 v46, v46
	v_mfma_f32_32x32x16_bf16 v[16:31], v[144:147], v[32:35], v[16:31]
	v_exp_f32_e32 v47, v47
	v_bfe_u32 v199, v45, 16, 1
	v_bfe_u32 v202, v195, 16, 1
	v_bfe_u32 v203, v110, 16, 1
	v_bfe_u32 v204, v44, 16, 1
	v_mfma_f32_32x32x16_bf16 v[0:15], v[168:171], v[32:35], v[0:15]
	v_bfe_u32 v205, v46, 16, 1
	v_bfe_u32 v198, v47, 16, 1
	v_add3_u32 v197, v45, v199, s61
	v_add3_u32 v199, v46, v205, s61
	v_add3_u32 v200, v44, v204, s61
	v_add3_u32 v201, v110, v203, s61
	v_add3_u32 v202, v195, v202, s61
	v_add3_u32 v198, v47, v198, s61
	v_add_f32_e32 v37, v108, v222
	v_lshrrev_b32_e32 v144, 16, v199
	v_cvt_pk_bf16_f32 v35, v46, v47
	v_cvt_pk_bf16_f32 v34, v44, v45
	v_cvt_pk_bf16_f32 v33, v110, v43
	v_cvt_pk_bf16_f32 v32, v195, v196
	v_add_f32_e32 v108, v111, v37
	v_sub_f32_e32 v48, v48, v109
	v_mfma_f32_32x32x16_bf16 v[16:31], v[112:115], v[32:35], v[16:31]
	v_sub_f32_e32 v49, v49, v109
	v_sub_f32_e32 v50, v50, v109
	v_sub_f32_e32 v51, v51, v109
	v_sub_f32_e32 v52, v52, v109
	v_sub_f32_e32 v53, v53, v109
	v_sub_f32_e32 v54, v54, v109
	v_sub_f32_e32 v55, v55, v109
	v_mfma_f32_32x32x16_bf16 v[0:15], v[172:175], v[32:35], v[0:15]
	v_add_f32_e32 v32, v167, v108
	v_add_f32_e32 v32, v192, v32
	v_add_f32_e32 v32, v193, v32
	v_add_f32_e32 v32, v194, v32
	v_add_f32_e32 v32, v195, v32
	v_sub_f32_e32 v56, v56, v109
	v_exp_f32_e32 v48, v48
	v_exp_f32_e32 v49, v49
	v_exp_f32_e32 v50, v50
	v_exp_f32_e32 v51, v51
	v_exp_f32_e32 v52, v52
	v_exp_f32_e32 v53, v53
	v_exp_f32_e32 v54, v54
	v_add_f32_e32 v32, v196, v32
	v_exp_f32_e32 v55, v55
	v_exp_f32_e32 v56, v56
	v_add_f32_e32 v32, v110, v32
	v_add_f32_e32 v32, v43, v32
	v_add_f32_e32 v32, v44, v32
	v_bfe_u32 v207, v53, 16, 1
	v_bfe_u32 v208, v51, 16, 1
	v_bfe_u32 v209, v49, 16, 1
	v_bfe_u32 v210, v48, 16, 1
	v_bfe_u32 v211, v50, 16, 1
	v_bfe_u32 v212, v52, 16, 1
	v_bfe_u32 v213, v54, 16, 1
	v_add_f32_e32 v32, v45, v32
	v_bfe_u32 v206, v55, 16, 1
	v_bfe_u32 v218, v56, 16, 1
	v_add3_u32 v203, v49, v209, s61
	v_add3_u32 v204, v51, v208, s61
	v_add3_u32 v205, v53, v207, s61
	v_add3_u32 v207, v54, v213, s61
	v_add3_u32 v208, v52, v212, s61
	v_add3_u32 v209, v50, v211, s61
	v_add3_u32 v210, v48, v210, s61
	v_add_f32_e32 v32, v46, v32
	v_add3_u32 v206, v55, v206, s61
	v_lshrrev_b32_e32 v145, 16, v210
	v_lshrrev_b32_e32 v146, 16, v209
	v_lshrrev_b32_e32 v147, 16, v208
	v_lshrrev_b32_e32 v168, 16, v207
	v_add_f32_e32 v32, v47, v32
	v_sub_f32_e32 v57, v57, v109
	v_sub_f32_e32 v58, v58, v109
	v_sub_f32_e32 v59, v59, v109
	v_sub_f32_e32 v60, v60, v109
	v_sub_f32_e32 v61, v61, v109
	v_sub_f32_e32 v62, v62, v109
	v_cvt_pk_bf16_f32 v37, v54, v55
	v_cvt_pk_bf16_f32 v36, v52, v53
	v_cvt_pk_bf16_f32 v35, v50, v51
	v_cvt_pk_bf16_f32 v34, v48, v49
	v_add_f32_e32 v32, v48, v32
	v_sub_f32_e32 v63, v63, v109
	v_exp_f32_e32 v57, v57
	v_exp_f32_e32 v58, v58
	v_exp_f32_e32 v59, v59
	v_exp_f32_e32 v60, v60
	v_exp_f32_e32 v61, v61
	v_exp_f32_e32 v62, v62
	v_mfma_f32_32x32x16_bf16 v[16:31], v[176:179], v[34:37], v[16:31]
	v_add_f32_e32 v32, v49, v32
	v_exp_f32_e32 v63, v63
	v_add_f32_e32 v32, v50, v32
	v_add_f32_e32 v32, v51, v32
	v_add_f32_e32 v32, v52, v32
	v_bfe_u32 v215, v61, 16, 1
	v_bfe_u32 v216, v59, 16, 1
	v_mfma_f32_32x32x16_bf16 v[0:15], v[180:183], v[34:37], v[0:15]
	v_bfe_u32 v217, v57, 16, 1
	v_bfe_u32 v219, v58, 16, 1
	v_bfe_u32 v220, v60, 16, 1
	v_bfe_u32 v221, v62, 16, 1
	v_add_f32_e32 v32, v53, v32
	v_bfe_u32 v214, v63, 16, 1
	v_add3_u32 v211, v57, v217, s61
	v_add3_u32 v212, v59, v216, s61
	v_add3_u32 v213, v61, v215, s61
	v_add3_u32 v215, v62, v221, s61
	v_add3_u32 v216, v60, v220, s61
	v_add3_u32 v217, v58, v219, s61
	v_add_f32_e32 v32, v54, v32
	v_add3_u32 v214, v63, v214, s61
	v_add_f32_e32 v32, v55, v32
	v_cvt_pk_bf16_f32 v41, v62, v63
	v_cvt_pk_bf16_f32 v40, v60, v61
	v_cvt_pk_bf16_f32 v39, v58, v59
	v_cvt_pk_bf16_f32 v38, v56, v57
	v_add_f32_e32 v32, v56, v32
	v_add_f32_e32 v32, v57, v32
	v_mfma_f32_32x32x16_bf16 v[16:31], v[184:187], v[38:41], v[16:31]
	v_add_f32_e32 v32, v58, v32
	v_add_f32_e32 v32, v59, v32
	v_add_f32_e32 v32, v60, v32
	v_add_f32_e32 v32, v61, v32
	v_add_f32_e32 v32, v62, v32
	v_add_f32_e32 v108, v63, v32
	v_fmac_f32_e32 v108, v166, v42
	v_mfma_f32_32x32x16_bf16 v[0:15], v[188:191], v[38:41], v[0:15]
	s_cbranch_scc1 .LBB0_1684
	s_barrier
	s_waitcnt vmcnt(0)
	ds_write_b128 v161, v[88:91]
	ds_write_b128 v162, v[92:95]
	ds_write_b128 v163, v[96:99]
	ds_write_b128 v164, v[104:107] offset:13312
	ds_write_b128 v165, v[100:103] offset:13312
	s_waitcnt lgkmcnt(0)
	s_barrier
	ds_read_b128 v[32:35], v116
	ds_read_b128 v[36:39], v116 offset:32
	s_waitcnt lgkmcnt(1)
	v_mfma_f32_32x32x16_bf16 v[48:63], v[32:35], v[84:87], 0
	s_waitcnt lgkmcnt(0)
	v_mfma_f32_32x32x16_bf16 v[48:63], v[36:39], v[80:83], v[48:63]
	ds_read_b128 v[32:35], v116 offset:64
	ds_read_b128 v[36:39], v116 offset:96
	s_waitcnt lgkmcnt(1)
	v_mfma_f32_32x32x16_bf16 v[48:63], v[32:35], v[76:79], v[48:63]
	s_waitcnt lgkmcnt(0)
	v_mfma_f32_32x32x16_bf16 v[48:63], v[36:39], v[72:75], v[48:63]
	ds_read_b128 v[32:35], v116 offset:128
	ds_read_b128 v[36:39], v116 offset:160
	s_waitcnt lgkmcnt(1)
	v_mfma_f32_32x32x16_bf16 v[48:63], v[32:35], v[68:71], v[48:63]
	ds_read_b128 v[32:35], v116 offset:6656
	ds_read_b128 v[88:91], v116 offset:6688
	s_waitcnt lgkmcnt(2)
	v_mfma_f32_32x32x16_bf16 v[48:63], v[36:39], v[64:67], v[48:63]
	s_waitcnt lgkmcnt(1)
	v_mfma_f32_32x32x16_bf16 v[32:47], v[32:35], v[84:87], 0
	s_waitcnt lgkmcnt(0)
	v_mfma_f32_32x32x16_bf16 v[32:47], v[88:91], v[80:83], v[32:47]
	ds_read_b128 v[80:83], v116 offset:6720
	ds_read_b128 v[84:87], v116 offset:6752
	s_waitcnt lgkmcnt(1)
	v_mfma_f32_32x32x16_bf16 v[32:47], v[80:83], v[76:79], v[32:47]
	s_nop 3
	v_max_f32_e32 v80, v49, v49
	v_max_f32_e32 v81, v48, v48
	v_max_f32_e32 v80, v81, v80
	s_waitcnt lgkmcnt(0)
	v_mfma_f32_32x32x16_bf16 v[32:47], v[84:87], v[72:75], v[32:47]
	ds_read_b128 v[72:75], v116 offset:6784
	ds_read_b128 v[76:79], v116 offset:6816
	s_waitcnt lgkmcnt(1)
	v_mfma_f32_32x32x16_bf16 v[32:47], v[72:75], v[68:71], v[32:47]
	v_max3_f32 v68, v80, v50, v51
	v_max3_f32 v68, v68, v52, v53
	v_max3_f32 v68, v68, v54, v55
	v_max3_f32 v68, v68, v56, v57
	v_max3_f32 v68, v68, v58, v59
	v_max3_f32 v68, v68, v60, v61
	v_max3_f32 v68, v68, v62, v63
	s_waitcnt lgkmcnt(0)
	v_mfma_f32_32x32x16_bf16 v[32:47], v[76:79], v[64:67], v[32:47]
	s_nop 11
	v_max3_f32 v64, v68, v32, v33
	v_max3_f32 v64, v64, v34, v35
	v_max3_f32 v64, v64, v36, v37
	v_max3_f32 v64, v64, v38, v39
	v_max3_f32 v64, v64, v40, v41
	v_max3_f32 v64, v64, v42, v43
	v_max3_f32 v64, v64, v44, v45
	v_max3_f32 v64, v64, v46, v47
	ds_bpermute_b32 v65, v123, v64
	s_waitcnt lgkmcnt(0)
	v_max3_f32 v65, v109, v64, v65
	v_sub_f32_e32 v32, v32, v65
	v_exp_f32_e32 v66, v32
	v_sub_f32_e32 v32, v33, v65
	v_exp_f32_e32 v67, v32
	v_sub_f32_e32 v32, v34, v65
	v_exp_f32_e32 v68, v32
	v_sub_f32_e32 v32, v35, v65
	v_exp_f32_e32 v69, v32
	v_sub_f32_e32 v32, v36, v65
	v_exp_f32_e32 v70, v32
	v_sub_f32_e32 v32, v37, v65
	v_exp_f32_e32 v71, v32
	v_sub_f32_e32 v32, v38, v65
	v_exp_f32_e32 v72, v32
	v_sub_f32_e32 v32, v39, v65
	v_exp_f32_e32 v73, v32
	v_sub_f32_e32 v32, v40, v65
	v_exp_f32_e32 v74, v32
	v_sub_f32_e32 v32, v41, v65
	v_exp_f32_e32 v75, v32
	v_sub_f32_e32 v32, v42, v65
	v_sub_f32_e32 v48, v48, v65
	v_exp_f32_e32 v76, v32
	v_sub_f32_e32 v32, v43, v65
	v_exp_f32_e32 v48, v48
	v_sub_f32_e32 v49, v49, v65
	v_exp_f32_e32 v77, v32
	v_sub_f32_e32 v32, v44, v65
	v_exp_f32_e32 v49, v49
	v_sub_f32_e32 v50, v50, v65
	v_sub_f32_e32 v55, v55, v65
	v_exp_f32_e32 v78, v32
	v_sub_f32_e32 v32, v45, v65
	v_exp_f32_e32 v50, v50
	v_sub_f32_e32 v51, v51, v65
	v_sub_f32_e32 v53, v53, v65
	v_exp_f32_e32 v55, v55
	v_exp_f32_e32 v79, v32
	v_sub_f32_e32 v32, v46, v65
	v_exp_f32_e32 v51, v51
	v_sub_f32_e32 v52, v52, v65
	v_exp_f32_e32 v53, v53
	v_sub_f32_e32 v54, v54, v65
	v_exp_f32_e32 v80, v32
	v_sub_f32_e32 v32, v47, v65
	v_sub_f32_e32 v64, v109, v65
	v_exp_f32_e32 v52, v52
	v_exp_f32_e32 v54, v54
	v_sub_f32_e32 v56, v56, v65
	v_sub_f32_e32 v57, v57, v65
	v_sub_f32_e32 v58, v58, v65
	v_sub_f32_e32 v59, v59, v65
	v_sub_f32_e32 v60, v60, v65
	v_sub_f32_e32 v61, v61, v65
	v_sub_f32_e32 v62, v62, v65
	v_sub_f32_e32 v63, v63, v65
	v_exp_f32_e32 v65, v32
	v_add_f32_e32 v32, 0, v48
	v_add_f32_e32 v32, v49, v32
	v_add_f32_e32 v44, v50, v32
	ds_read2_b64 v[32:35], v143 offset0:128 offset1:130
	v_exp_f32_e32 v64, v64
	v_cvt_pk_bf16_f32 v39, v54, v55
	v_cvt_pk_bf16_f32 v38, v52, v53
	v_cvt_pk_bf16_f32 v37, v50, v51
	v_cvt_pk_bf16_f32 v36, v48, v49
	ds_read2_b64 v[40:43], v142 offset0:128 offset1:130
	v_pk_mul_f32 v[30:31], v[30:31], v[64:65] op_sel_hi:[1,0]
	v_pk_mul_f32 v[28:29], v[28:29], v[64:65] op_sel_hi:[1,0]
	v_pk_mul_f32 v[26:27], v[26:27], v[64:65] op_sel_hi:[1,0]
	v_pk_mul_f32 v[24:25], v[24:25], v[64:65] op_sel_hi:[1,0]
	v_pk_mul_f32 v[22:23], v[22:23], v[64:65] op_sel_hi:[1,0]
	v_pk_mul_f32 v[20:21], v[20:21], v[64:65] op_sel_hi:[1,0]
	v_pk_mul_f32 v[18:19], v[18:19], v[64:65] op_sel_hi:[1,0]
	v_pk_mul_f32 v[16:17], v[16:17], v[64:65] op_sel_hi:[1,0]
	v_exp_f32_e32 v57, v57
	v_exp_f32_e32 v59, v59
	s_waitcnt lgkmcnt(1)
	v_mfma_f32_32x32x16_bf16 v[16:31], v[32:35], v[36:39], v[16:31]
	v_add_f32_e32 v32, v51, v44
	v_exp_f32_e32 v56, v56
	v_exp_f32_e32 v58, v58
	v_exp_f32_e32 v60, v60
	v_exp_f32_e32 v62, v62
	v_add_f32_e32 v32, v52, v32
	v_exp_f32_e32 v61, v61
	v_exp_f32_e32 v63, v63
	v_add_f32_e32 v32, v53, v32
	v_pk_mul_f32 v[14:15], v[14:15], v[64:65] op_sel_hi:[1,0]
	v_pk_mul_f32 v[12:13], v[12:13], v[64:65] op_sel_hi:[1,0]
	v_pk_mul_f32 v[10:11], v[10:11], v[64:65] op_sel_hi:[1,0]
	v_pk_mul_f32 v[8:9], v[8:9], v[64:65] op_sel_hi:[1,0]
	v_pk_mul_f32 v[6:7], v[6:7], v[64:65] op_sel_hi:[1,0]
	v_pk_mul_f32 v[4:5], v[4:5], v[64:65] op_sel_hi:[1,0]
	v_pk_mul_f32 v[2:3], v[2:3], v[64:65] op_sel_hi:[1,0]
	v_pk_mul_f32 v[0:1], v[0:1], v[64:65] op_sel_hi:[1,0]
	v_add_f32_e32 v32, v54, v32
	v_add_f32_e32 v48, v55, v32
	s_waitcnt lgkmcnt(0)
	v_mfma_f32_32x32x16_bf16 v[0:15], v[40:43], v[36:39], v[0:15]
	ds_read2_b64 v[32:35], v143 offset0:132 offset1:134
	ds_read2_b64 v[44:47], v142 offset0:132 offset1:134
	v_add_f32_e32 v40, v56, v48
	v_bfe_u32 v38, v56, 16, 1
	v_bfe_u32 v39, v58, 16, 1
	v_bfe_u32 v48, v62, 16, 1
	v_add3_u32 v48, v62, v48, s61
	v_add3_u32 v39, v58, v39, s61
	v_add3_u32 v38, v56, v38, s61
	v_lshrrev_b32_e32 v49, 16, v38
	v_lshrrev_b32_e32 v50, 16, v39
	v_cvt_pk_bf16_f32 v39, v62, v63
	v_cvt_pk_bf16_f32 v38, v60, v61
	v_cvt_pk_bf16_f32 v37, v58, v59
	v_cvt_pk_bf16_f32 v36, v56, v57
	s_waitcnt lgkmcnt(1)
	s_nop 0
	v_mfma_f32_32x32x16_bf16 v[16:31], v[32:35], v[36:39], v[16:31]
	v_add_f32_e32 v32, v57, v40
	v_add_f32_e32 v32, v58, v32
	v_add_f32_e32 v32, v59, v32
	v_add_f32_e32 v32, v60, v32
	v_add_f32_e32 v32, v61, v32
	v_add_f32_e32 v32, v62, v32
	v_add_f32_e32 v32, v63, v32
	s_waitcnt lgkmcnt(0)
	v_mfma_f32_32x32x16_bf16 v[0:15], v[44:47], v[36:39], v[0:15]
	v_add_f32_e32 v44, v66, v32
	ds_read2_b64 v[32:35], v143 offset0:136 offset1:138
	v_cvt_pk_bf16_f32 v39, v72, v73
	v_cvt_pk_bf16_f32 v38, v70, v71
	v_cvt_pk_bf16_f32 v37, v68, v69
	v_cvt_pk_bf16_f32 v36, v66, v67
	ds_read2_b64 v[40:43], v142 offset0:136 offset1:138
	s_waitcnt lgkmcnt(1)
	v_mfma_f32_32x32x16_bf16 v[16:31], v[32:35], v[36:39], v[16:31]
	v_add_f32_e32 v32, v67, v44
	v_add_f32_e32 v32, v68, v32
	v_add_f32_e32 v32, v69, v32
	v_add_f32_e32 v32, v70, v32
	v_add_f32_e32 v32, v71, v32
	v_add_f32_e32 v32, v72, v32
	v_add_f32_e32 v32, v73, v32
	v_add_f32_e32 v32, v74, v32
	v_add_f32_e32 v32, v75, v32
	v_add_f32_e32 v32, v76, v32
	v_add_f32_e32 v32, v77, v32
	v_add_f32_e32 v32, v78, v32
	v_add_f32_e32 v32, v79, v32
	v_add_f32_e32 v32, v80, v32
	s_waitcnt lgkmcnt(0)
	v_mfma_f32_32x32x16_bf16 v[0:15], v[40:43], v[36:39], v[0:15]
	v_add_f32_e32 v40, v65, v32
	v_bfe_u32 v32, v74, 16, 1
	v_bfe_u32 v33, v76, 16, 1
	v_add3_u32 v33, v76, v33, s61
	v_add3_u32 v32, v74, v32, s61
	v_lshrrev_b32_e32 v43, 16, v32
	v_lshrrev_b32_e32 v44, 16, v33
	ds_read2_b64 v[32:35], v141 offset0:140 offset1:142
	v_fmac_f32_e32 v40, v108, v64
	v_cvt_pk_bf16_f32 v39, v80, v65
	ds_bpermute_b32 v41, v123, v40
	v_cvt_pk_bf16_f32 v38, v78, v79
	v_cvt_pk_bf16_f32 v37, v76, v77
	v_cvt_pk_bf16_f32 v36, v74, v75
	v_mov_b32_e32 v123, v117
	s_waitcnt lgkmcnt(0)
	v_add_f32_e32 v40, v40, v41
	v_mfma_f32_32x32x16_bf16 v[16:31], v[32:35], v[36:39], v[16:31]
	ds_read2_b64 v[32:35], v140 offset0:140 offset1:142
	v_div_scale_f32 v41, s[0:1], v40, v40, 1.0
	v_rcp_f32_e32 v42, v41
	s_waitcnt lgkmcnt(0)
	v_mfma_f32_32x32x16_bf16 v[0:15], v[32:35], v[36:39], v[0:15]
	v_fma_f32 v32, -v41, v42, 1.0
	v_fmac_f32_e32 v42, v32, v42
	v_div_scale_f32 v32, vcc, 1.0, v40, 1.0
	v_mul_f32_e32 v33, v32, v42
	v_fma_f32 v34, -v41, v33, v32
	v_fmac_f32_e32 v33, v34, v42
	v_fma_f32 v32, -v41, v33, v32
	v_div_fmas_f32 v32, v32, v42, v33
	v_div_fixup_f32 v32, v32, v40, 1.0
	v_mov_b32_e32 v38, v16
	v_mov_b32_e32 v39, v18
	v_mov_b32_e32 v18, v17
	v_lshlrev_b64 v[34:35], 11, v[118:119]
	v_pk_mul_f32 v[38:39], v[38:39], v[32:33] op_sel_hi:[1,0]
	v_pk_mul_f32 v[16:17], v[18:19], v[32:33] op_sel_hi:[1,0]
	v_lshl_add_u64 v[34:35], s[8:9], 0, v[34:35]
	v_and_b32_sdwa v19, v38, v155 dst_sel:DWORD dst_unused:UNUSED_PAD src0_sel:WORD_1 src1_sel:DWORD
	v_and_b32_sdwa v33, v17, v155 dst_sel:DWORD dst_unused:UNUSED_PAD src0_sel:WORD_1 src1_sel:DWORD
	v_lshl_add_u64 v[34:35], v[120:121], 1, v[34:35]
	v_and_b32_sdwa v18, v39, v155 dst_sel:DWORD dst_unused:UNUSED_PAD src0_sel:WORD_1 src1_sel:DWORD
	v_add3_u32 v19, v38, v19, s61
	v_and_b32_sdwa v38, v16, v155 dst_sel:DWORD dst_unused:UNUSED_PAD src0_sel:WORD_1 src1_sel:DWORD
	v_add3_u32 v17, v17, v33, s61
	v_lshl_add_u64 v[34:35], v[34:35], 0, v[122:123]
	v_add3_u32 v18, v39, v18, s61
	v_add3_u32 v16, v16, v38, s61
	v_and_b32_e32 v17, 0xffff0000, v17
	v_and_b32_e32 v16, 0xffff0000, v16
	v_or_b32_sdwa v17, v17, v18 dst_sel:DWORD dst_unused:UNUSED_PAD src0_sel:DWORD src1_sel:WORD_1
	v_add_co_u32_e32 v18, vcc, s63, v34
	v_or_b32_sdwa v16, v16, v19 dst_sel:DWORD dst_unused:UNUSED_PAD src0_sel:DWORD src1_sel:WORD_1
	s_nop 0
	v_addc_co_u32_e32 v19, vcc, 0, v35, vcc
	global_store_dwordx2 v[18:19], v[16:17], off offset:3840
	v_mov_b32_e32 v16, v20
	v_mov_b32_e32 v17, v22
	v_pk_mul_f32 v[16:17], v[16:17], v[32:33] op_sel_hi:[1,0]
	v_mov_b32_e32 v22, v21
	v_pk_mul_f32 v[18:19], v[22:23], v[32:33] op_sel_hi:[1,0]
	v_and_b32_sdwa v20, v17, v155 dst_sel:DWORD dst_unused:UNUSED_PAD src0_sel:WORD_1 src1_sel:DWORD
	v_and_b32_sdwa v21, v16, v155 dst_sel:DWORD dst_unused:UNUSED_PAD src0_sel:WORD_1 src1_sel:DWORD
	v_add3_u32 v16, v16, v21, s61
	v_add3_u32 v17, v17, v20, s61
	v_and_b32_sdwa v20, v19, v155 dst_sel:DWORD dst_unused:UNUSED_PAD src0_sel:WORD_1 src1_sel:DWORD
	v_and_b32_sdwa v21, v18, v155 dst_sel:DWORD dst_unused:UNUSED_PAD src0_sel:WORD_1 src1_sel:DWORD
	v_add3_u32 v19, v19, v20, s61
	v_add3_u32 v18, v18, v21, s61
	v_and_b32_e32 v19, 0xffff0000, v19
	v_and_b32_e32 v18, 0xffff0000, v18
	v_lshl_add_u64 v[36:37], v[34:35], 0, s[50:51]
	v_or_b32_sdwa v17, v19, v17 dst_sel:DWORD dst_unused:UNUSED_PAD src0_sel:DWORD src1_sel:WORD_1
	v_or_b32_sdwa v16, v18, v16 dst_sel:DWORD dst_unused:UNUSED_PAD src0_sel:DWORD src1_sel:WORD_1
	global_store_dwordx2 v[36:37], v[16:17], off offset:16
	v_mov_b32_e32 v16, v24
	v_mov_b32_e32 v17, v26
	v_pk_mul_f32 v[16:17], v[16:17], v[32:33] op_sel_hi:[1,0]
	v_mov_b32_e32 v26, v25
	v_pk_mul_f32 v[18:19], v[26:27], v[32:33] op_sel_hi:[1,0]
	v_and_b32_sdwa v20, v17, v155 dst_sel:DWORD dst_unused:UNUSED_PAD src0_sel:WORD_1 src1_sel:DWORD
	v_and_b32_sdwa v21, v16, v155 dst_sel:DWORD dst_unused:UNUSED_PAD src0_sel:WORD_1 src1_sel:DWORD
	v_add3_u32 v16, v16, v21, s61
	v_add3_u32 v17, v17, v20, s61
	v_and_b32_sdwa v20, v19, v155 dst_sel:DWORD dst_unused:UNUSED_PAD src0_sel:WORD_1 src1_sel:DWORD
	v_and_b32_sdwa v21, v18, v155 dst_sel:DWORD dst_unused:UNUSED_PAD src0_sel:WORD_1 src1_sel:DWORD
	v_add3_u32 v19, v19, v20, s61
	v_add3_u32 v18, v18, v21, s61
	v_and_b32_e32 v19, 0xffff0000, v19
	v_and_b32_e32 v18, 0xffff0000, v18
	v_or_b32_sdwa v17, v19, v17 dst_sel:DWORD dst_unused:UNUSED_PAD src0_sel:DWORD src1_sel:WORD_1
	v_or_b32_sdwa v16, v18, v16 dst_sel:DWORD dst_unused:UNUSED_PAD src0_sel:DWORD src1_sel:WORD_1
	global_store_dwordx2 v[36:37], v[16:17], off offset:32
	v_mov_b32_e32 v16, v28
	v_mov_b32_e32 v17, v30
	v_pk_mul_f32 v[16:17], v[16:17], v[32:33] op_sel_hi:[1,0]
	v_mov_b32_e32 v30, v29
	v_pk_mul_f32 v[18:19], v[30:31], v[32:33] op_sel_hi:[1,0]
	v_and_b32_sdwa v20, v17, v155 dst_sel:DWORD dst_unused:UNUSED_PAD src0_sel:WORD_1 src1_sel:DWORD
	v_and_b32_sdwa v21, v16, v155 dst_sel:DWORD dst_unused:UNUSED_PAD src0_sel:WORD_1 src1_sel:DWORD
	v_add3_u32 v16, v16, v21, s61
	v_add3_u32 v17, v17, v20, s61
	v_and_b32_sdwa v20, v19, v155 dst_sel:DWORD dst_unused:UNUSED_PAD src0_sel:WORD_1 src1_sel:DWORD
	v_and_b32_sdwa v21, v18, v155 dst_sel:DWORD dst_unused:UNUSED_PAD src0_sel:WORD_1 src1_sel:DWORD
	v_add3_u32 v19, v19, v20, s61
	v_add3_u32 v18, v18, v21, s61
	v_and_b32_e32 v19, 0xffff0000, v19
	v_and_b32_e32 v18, 0xffff0000, v18
	v_or_b32_sdwa v17, v19, v17 dst_sel:DWORD dst_unused:UNUSED_PAD src0_sel:DWORD src1_sel:WORD_1
	v_or_b32_sdwa v16, v18, v16 dst_sel:DWORD dst_unused:UNUSED_PAD src0_sel:DWORD src1_sel:WORD_1
	global_store_dwordx2 v[36:37], v[16:17], off offset:48
	v_mov_b32_e32 v16, v0
	v_mov_b32_e32 v17, v2
	v_pk_mul_f32 v[16:17], v[16:17], v[32:33] op_sel_hi:[1,0]
	v_mov_b32_e32 v2, v1
	v_pk_mul_f32 v[0:1], v[2:3], v[32:33] op_sel_hi:[1,0]
	v_and_b32_sdwa v2, v17, v155 dst_sel:DWORD dst_unused:UNUSED_PAD src0_sel:WORD_1 src1_sel:DWORD
	v_and_b32_sdwa v3, v16, v155 dst_sel:DWORD dst_unused:UNUSED_PAD src0_sel:WORD_1 src1_sel:DWORD
	v_add3_u32 v3, v16, v3, s61
	v_add3_u32 v2, v17, v2, s61
	v_and_b32_sdwa v16, v1, v155 dst_sel:DWORD dst_unused:UNUSED_PAD src0_sel:WORD_1 src1_sel:DWORD
	v_and_b32_sdwa v17, v0, v155 dst_sel:DWORD dst_unused:UNUSED_PAD src0_sel:WORD_1 src1_sel:DWORD
	v_add3_u32 v1, v1, v16, s61
	v_add3_u32 v0, v0, v17, s61
	v_and_b32_e32 v1, 0xffff0000, v1
	v_and_b32_e32 v0, 0xffff0000, v0
	v_or_b32_sdwa v1, v1, v2 dst_sel:DWORD dst_unused:UNUSED_PAD src0_sel:DWORD src1_sel:WORD_1
	v_or_b32_sdwa v0, v0, v3 dst_sel:DWORD dst_unused:UNUSED_PAD src0_sel:DWORD src1_sel:WORD_1
	global_store_dwordx2 v[36:37], v[0:1], off offset:64
	v_mov_b32_e32 v0, v4
	v_mov_b32_e32 v1, v6
	v_pk_mul_f32 v[0:1], v[0:1], v[32:33] op_sel_hi:[1,0]
	v_mov_b32_e32 v6, v5
	v_pk_mul_f32 v[2:3], v[6:7], v[32:33] op_sel_hi:[1,0]
	v_and_b32_sdwa v4, v1, v155 dst_sel:DWORD dst_unused:UNUSED_PAD src0_sel:WORD_1 src1_sel:DWORD
	v_and_b32_sdwa v5, v0, v155 dst_sel:DWORD dst_unused:UNUSED_PAD src0_sel:WORD_1 src1_sel:DWORD
	v_add3_u32 v0, v0, v5, s61
	v_add3_u32 v1, v1, v4, s61
	v_and_b32_sdwa v4, v3, v155 dst_sel:DWORD dst_unused:UNUSED_PAD src0_sel:WORD_1 src1_sel:DWORD
	v_and_b32_sdwa v5, v2, v155 dst_sel:DWORD dst_unused:UNUSED_PAD src0_sel:WORD_1 src1_sel:DWORD
	v_add3_u32 v3, v3, v4, s61
	v_add3_u32 v2, v2, v5, s61
	v_and_b32_e32 v3, 0xffff0000, v3
	v_and_b32_e32 v2, 0xffff0000, v2
	v_or_b32_sdwa v1, v3, v1 dst_sel:DWORD dst_unused:UNUSED_PAD src0_sel:DWORD src1_sel:WORD_1
	v_or_b32_sdwa v0, v2, v0 dst_sel:DWORD dst_unused:UNUSED_PAD src0_sel:DWORD src1_sel:WORD_1
	global_store_dwordx2 v[36:37], v[0:1], off offset:80
	v_mov_b32_e32 v0, v8
	v_mov_b32_e32 v1, v10
	v_pk_mul_f32 v[0:1], v[0:1], v[32:33] op_sel_hi:[1,0]
	v_mov_b32_e32 v10, v9
	v_pk_mul_f32 v[2:3], v[10:11], v[32:33] op_sel_hi:[1,0]
	v_and_b32_sdwa v4, v1, v155 dst_sel:DWORD dst_unused:UNUSED_PAD src0_sel:WORD_1 src1_sel:DWORD
	v_and_b32_sdwa v5, v0, v155 dst_sel:DWORD dst_unused:UNUSED_PAD src0_sel:WORD_1 src1_sel:DWORD
	v_add3_u32 v0, v0, v5, s61
	v_add3_u32 v1, v1, v4, s61
	v_and_b32_sdwa v4, v3, v155 dst_sel:DWORD dst_unused:UNUSED_PAD src0_sel:WORD_1 src1_sel:DWORD
	v_and_b32_sdwa v5, v2, v155 dst_sel:DWORD dst_unused:UNUSED_PAD src0_sel:WORD_1 src1_sel:DWORD
	v_add3_u32 v3, v3, v4, s61
	v_add3_u32 v2, v2, v5, s61
	v_and_b32_e32 v3, 0xffff0000, v3
	v_and_b32_e32 v2, 0xffff0000, v2
	v_or_b32_sdwa v1, v3, v1 dst_sel:DWORD dst_unused:UNUSED_PAD src0_sel:DWORD src1_sel:WORD_1
	v_or_b32_sdwa v0, v2, v0 dst_sel:DWORD dst_unused:UNUSED_PAD src0_sel:DWORD src1_sel:WORD_1
	global_store_dwordx2 v[36:37], v[0:1], off offset:96
	v_mov_b32_e32 v0, v12
	v_mov_b32_e32 v1, v14
	v_pk_mul_f32 v[0:1], v[0:1], v[32:33] op_sel_hi:[1,0]
	v_mov_b32_e32 v14, v13
	v_pk_mul_f32 v[2:3], v[14:15], v[32:33] op_sel_hi:[1,0]
	v_and_b32_sdwa v4, v1, v155 dst_sel:DWORD dst_unused:UNUSED_PAD src0_sel:WORD_1 src1_sel:DWORD
	v_and_b32_sdwa v5, v0, v155 dst_sel:DWORD dst_unused:UNUSED_PAD src0_sel:WORD_1 src1_sel:DWORD
	v_add3_u32 v0, v0, v5, s61
	v_add3_u32 v1, v1, v4, s61
	v_and_b32_sdwa v4, v3, v155 dst_sel:DWORD dst_unused:UNUSED_PAD src0_sel:WORD_1 src1_sel:DWORD
	v_and_b32_sdwa v5, v2, v155 dst_sel:DWORD dst_unused:UNUSED_PAD src0_sel:WORD_1 src1_sel:DWORD
	v_add3_u32 v3, v3, v4, s61
	v_add3_u32 v2, v2, v5, s61
	v_and_b32_e32 v3, 0xffff0000, v3
	v_and_b32_e32 v2, 0xffff0000, v2
	v_or_b32_sdwa v1, v3, v1 dst_sel:DWORD dst_unused:UNUSED_PAD src0_sel:DWORD src1_sel:WORD_1
	v_or_b32_sdwa v0, v2, v0 dst_sel:DWORD dst_unused:UNUSED_PAD src0_sel:DWORD src1_sel:WORD_1
	global_store_dwordx2 v[36:37], v[0:1], off offset:112
	s_branch .LBB0_1562
